# P0: adaLN GEMV with batched loads + two-pass S5 impulse table (T=C*abar^d formed once), on top of attention edits
# speedup vs baseline: 1.0142x; 1.0142x over previous
; __device__ __forceinline__ f32x2 cmul(f32x2 a, f32x2 b) { return (f32x2){a.x * b.x - a.y * b.y, a.x * b.y + a.y * b.x}; }
; __global__ void __launch_bounds__(NTHR, 2) hymba_fwd(Params P) {
;     ...
;             for (int idx = tid; idx < 4096; idx += NTHR) { const int d = idx >> 8, p = (idx >> 4) & 15, pp = idx & 15; float s = 0.f;
;                 for (int n = 0; n < 64; ++n) { const f32x2 t = cmul(CCl[p * 64 + n], PW[d * 64 + n]); const f32x2 b = BBl[n * 16 + pp]; s += t.x * b.x - t.y * b.y; }
;                 if (d == 0 && p == pp) s += P.d_skip[g * 16 + p];
;                 KT[idx] = s; }
.LBB0_18:
	s_or_b64 exec, exec, s[0:1]
	s_movk_i32 s0, 0x1000
	v_cmp_gt_i32_e32 vcc, s0, v8
	s_waitcnt lgkmcnt(0)
	s_barrier
	s_and_saveexec_b64 s[4:5], vcc
	s_cbranch_execz .LBB0_25
	s_lshl_b32 s14, s10, 4
	v_and_b32_e32 v2, 15, v8
	v_bfe_u32 v3, v8, 4, 4
	v_lshrrev_b32_e32 v4, 8, v8
	v_and_b32_e32 v5, 63, v8
	v_lshrrev_b32_e32 v6, 6, v8
	v_add_u32_e32 v7, s14, v3
	v_lshlrev_b32_e32 v7, 2, v7
	global_load_dword v9, v7, s[82:83]
	v_lshlrev_b32_e32 v10, 3, v5
	v_lshl_add_u32 v11, v6, 9, v10
	v_add_u32_e32 v11, 0x4200, v11
	v_mul_u32_u24_e32 v12, 528, v6
	v_add_u32_e32 v12, v12, v10
	v_add_u32_e32 v12, 0xb000, v12
	v_lshlrev_b32_e32 v13, 3, v2
	v_add_u32_e32 v13, 0x2200, v13
	v_lshl_add_u32 v14, v4, 4, v3
	v_mul_u32_u24_e32 v14, 528, v14
	v_add_u32_e32 v14, 0xb000, v14
	v_and_b32_e32 v15, 0xff, v8
	v_lshlrev_b32_e32 v15, 2, v15
	v_lshl_add_u32 v15, v4, 10, v15
	v_add_u32_e32 v15, 0x6200, v15
	v_cmp_eq_u32_e32 vcc, v2, v3
	v_cmp_eq_u32_e64 s[6:7], 0, v4
	s_nop 1
	s_and_b64 s[6:7], s[6:7], vcc
	ds_read_b64 v[20:21], v11
	ds_read_b64 v[22:23], v11 offset:4096
	ds_read_b64 v[24:25], v10 offset:0
	ds_read_b64 v[26:27], v10 offset:512
	ds_read_b64 v[28:29], v10 offset:1024
	ds_read_b64 v[30:31], v10 offset:1536
	ds_read_b64 v[32:33], v10 offset:2048
	ds_read_b64 v[34:35], v10 offset:2560
	ds_read_b64 v[36:37], v10 offset:3072
	ds_read_b64 v[38:39], v10 offset:3584
	s_waitcnt lgkmcnt(0)
	v_mul_f32_e32 v84, v21, v25
	v_mul_f32_e32 v85, v21, v24
	v_fma_f32 v84, v20, v24, -v84
	v_fma_f32 v85, v20, v25, v85
	ds_write_b64 v12, v[84:85] offset:0
	v_mul_f32_e32 v86, v23, v25
	v_mul_f32_e32 v87, v23, v24
	v_fma_f32 v86, v22, v24, -v86
	v_fma_f32 v87, v22, v25, v87
	ds_write_b64 v12, v[86:87] offset:4224
	v_mul_f32_e32 v88, v21, v27
	v_mul_f32_e32 v89, v21, v26
	v_fma_f32 v88, v20, v26, -v88
	v_fma_f32 v89, v20, v27, v89
	ds_write_b64 v12, v[88:89] offset:8448
	v_mul_f32_e32 v90, v23, v27
	v_mul_f32_e32 v91, v23, v26
	v_fma_f32 v90, v22, v26, -v90
	v_fma_f32 v91, v22, v27, v91
	ds_write_b64 v12, v[90:91] offset:12672
	v_mul_f32_e32 v84, v21, v29
	v_mul_f32_e32 v85, v21, v28
	v_fma_f32 v84, v20, v28, -v84
	v_fma_f32 v85, v20, v29, v85
	ds_write_b64 v12, v[84:85] offset:16896
	v_mul_f32_e32 v86, v23, v29
	v_mul_f32_e32 v87, v23, v28
	v_fma_f32 v86, v22, v28, -v86
	v_fma_f32 v87, v22, v29, v87
	ds_write_b64 v12, v[86:87] offset:21120
	v_mul_f32_e32 v88, v21, v31
	v_mul_f32_e32 v89, v21, v30
	v_fma_f32 v88, v20, v30, -v88
	v_fma_f32 v89, v20, v31, v89
	ds_write_b64 v12, v[88:89] offset:25344
	v_mul_f32_e32 v90, v23, v31
	v_mul_f32_e32 v91, v23, v30
	v_fma_f32 v90, v22, v30, -v90
	v_fma_f32 v91, v22, v31, v91
	ds_write_b64 v12, v[90:91] offset:29568
	v_mul_f32_e32 v84, v21, v33
	v_mul_f32_e32 v85, v21, v32
	v_fma_f32 v84, v20, v32, -v84
	v_fma_f32 v85, v20, v33, v85
	ds_write_b64 v12, v[84:85] offset:33792
	v_mul_f32_e32 v86, v23, v33
	v_mul_f32_e32 v87, v23, v32
	v_fma_f32 v86, v22, v32, -v86
	v_fma_f32 v87, v22, v33, v87
	ds_write_b64 v12, v[86:87] offset:38016
	v_mul_f32_e32 v88, v21, v35
	v_mul_f32_e32 v89, v21, v34
	v_fma_f32 v88, v20, v34, -v88
	v_fma_f32 v89, v20, v35, v89
	ds_write_b64 v12, v[88:89] offset:42240
	v_mul_f32_e32 v90, v23, v35
	v_mul_f32_e32 v91, v23, v34
	v_fma_f32 v90, v22, v34, -v90
	v_fma_f32 v91, v22, v35, v91
	ds_write_b64 v12, v[90:91] offset:46464
	v_mul_f32_e32 v84, v21, v37
	v_mul_f32_e32 v85, v21, v36
	v_fma_f32 v84, v20, v36, -v84
	v_fma_f32 v85, v20, v37, v85
	ds_write_b64 v12, v[84:85] offset:50688
	v_mul_f32_e32 v86, v23, v37
	v_mul_f32_e32 v87, v23, v36
	v_fma_f32 v86, v22, v36, -v86
	v_fma_f32 v87, v22, v37, v87
	ds_write_b64 v12, v[86:87] offset:54912
	v_mul_f32_e32 v88, v21, v39
	v_mul_f32_e32 v89, v21, v38
	v_fma_f32 v88, v20, v38, -v88
	v_fma_f32 v89, v20, v39, v89
	ds_write_b64 v12, v[88:89] offset:59136
	v_mul_f32_e32 v90, v23, v39
	v_mul_f32_e32 v91, v23, v38
	v_fma_f32 v90, v22, v38, -v90
	v_fma_f32 v91, v22, v39, v91
	ds_write_b64 v12, v[90:91] offset:63360
	s_waitcnt lgkmcnt(0)
	s_barrier
	v_mov_b32_e32 v16, 0
	v_mov_b32_e32 v17, 0
	v_mov_b32_e32 v18, 0
	v_mov_b32_e32 v19, 0
	ds_read_b64 v[100:101], v13 offset:0
	ds_read_b64 v[102:103], v13 offset:128
	ds_read_b128 v[104:107], v14 offset:0
	ds_read_b128 v[108:111], v14 offset:16896
	ds_read_b128 v[112:115], v14 offset:33792
	ds_read_b128 v[116:119], v14 offset:50688
	ds_read_b64 v[124:125], v13 offset:256
	ds_read_b64 v[126:127], v13 offset:384
	ds_read_b128 v[128:131], v14 offset:16
	ds_read_b128 v[132:135], v14 offset:16912
	ds_read_b128 v[136:139], v14 offset:33808
	ds_read_b128 v[140:143], v14 offset:50704
	s_waitcnt lgkmcnt(6)
	v_fmac_f32_e32 v16, v104, v100
	v_fma_f32 v16, -v105, v101, v16
	v_fmac_f32_e32 v17, v108, v100
	v_fma_f32 v17, -v109, v101, v17
	v_fmac_f32_e32 v18, v112, v100
	v_fma_f32 v18, -v113, v101, v18
	v_fmac_f32_e32 v19, v116, v100
	v_fma_f32 v19, -v117, v101, v19
	v_fmac_f32_e32 v16, v106, v102
	v_fma_f32 v16, -v107, v103, v16
	v_fmac_f32_e32 v17, v110, v102
	v_fma_f32 v17, -v111, v103, v17
	v_fmac_f32_e32 v18, v114, v102
	v_fma_f32 v18, -v115, v103, v18
	v_fmac_f32_e32 v19, v118, v102
	v_fma_f32 v19, -v119, v103, v19
	ds_read_b64 v[100:101], v13 offset:512
	ds_read_b64 v[102:103], v13 offset:640
	ds_read_b128 v[104:107], v14 offset:32
	ds_read_b128 v[108:111], v14 offset:16928
	ds_read_b128 v[112:115], v14 offset:33824
	ds_read_b128 v[116:119], v14 offset:50720
	s_waitcnt lgkmcnt(6)
; __device__ __forceinline__ f32x2 cmul(f32x2 a, f32x2 b) { return (f32x2){a.x * b.x - a.y * b.y, a.x * b.y + a.y * b.x}; }
; __global__ void __launch_bounds__(NTHR, 2) hymba_fwd(Params P) {
;     ...
;             for (int idx = tid; idx < 4096; idx += NTHR) { const int d = idx >> 8, p = (idx >> 4) & 15, pp = idx & 15; float s = 0.f;
;                 for (int n = 0; n < 64; ++n) { const f32x2 t = cmul(CCl[p * 64 + n], PW[d * 64 + n]); const f32x2 b = BBl[n * 16 + pp]; s += t.x * b.x - t.y * b.y; }
	v_fmac_f32_e32 v16, v128, v124
	v_fma_f32 v16, -v129, v125, v16
	v_fmac_f32_e32 v17, v132, v124
	v_fma_f32 v17, -v133, v125, v17
	v_fmac_f32_e32 v18, v136, v124
	v_fma_f32 v18, -v137, v125, v18
	v_fmac_f32_e32 v19, v140, v124
	v_fma_f32 v19, -v141, v125, v19
	v_fmac_f32_e32 v16, v130, v126
	v_fma_f32 v16, -v131, v127, v16
	v_fmac_f32_e32 v17, v134, v126
	v_fma_f32 v17, -v135, v127, v17
	v_fmac_f32_e32 v18, v138, v126
	v_fma_f32 v18, -v139, v127, v18
	v_fmac_f32_e32 v19, v142, v126
	v_fma_f32 v19, -v143, v127, v19
	ds_read_b64 v[124:125], v13 offset:768
	ds_read_b64 v[126:127], v13 offset:896
	ds_read_b128 v[128:131], v14 offset:48
	ds_read_b128 v[132:135], v14 offset:16944
	ds_read_b128 v[136:139], v14 offset:33840
	ds_read_b128 v[140:143], v14 offset:50736
	s_waitcnt lgkmcnt(6)
	v_fmac_f32_e32 v16, v104, v100
	v_fma_f32 v16, -v105, v101, v16
	v_fmac_f32_e32 v17, v108, v100
	v_fma_f32 v17, -v109, v101, v17
	v_fmac_f32_e32 v18, v112, v100
	v_fma_f32 v18, -v113, v101, v18
	v_fmac_f32_e32 v19, v116, v100
	v_fma_f32 v19, -v117, v101, v19
	v_fmac_f32_e32 v16, v106, v102
	v_fma_f32 v16, -v107, v103, v16
	v_fmac_f32_e32 v17, v110, v102
	v_fma_f32 v17, -v111, v103, v17
	v_fmac_f32_e32 v18, v114, v102
	v_fma_f32 v18, -v115, v103, v18
	v_fmac_f32_e32 v19, v118, v102
	v_fma_f32 v19, -v119, v103, v19
	ds_read_b64 v[100:101], v13 offset:1024
	ds_read_b64 v[102:103], v13 offset:1152
	ds_read_b128 v[104:107], v14 offset:64
	ds_read_b128 v[108:111], v14 offset:16960
	ds_read_b128 v[112:115], v14 offset:33856
	ds_read_b128 v[116:119], v14 offset:50752
	s_waitcnt lgkmcnt(6)
	v_fmac_f32_e32 v16, v128, v124
	v_fma_f32 v16, -v129, v125, v16
	v_fmac_f32_e32 v17, v132, v124
	v_fma_f32 v17, -v133, v125, v17
	v_fmac_f32_e32 v18, v136, v124
	v_fma_f32 v18, -v137, v125, v18
	v_fmac_f32_e32 v19, v140, v124
	v_fma_f32 v19, -v141, v125, v19
	v_fmac_f32_e32 v16, v130, v126
	v_fma_f32 v16, -v131, v127, v16
	v_fmac_f32_e32 v17, v134, v126
	v_fma_f32 v17, -v135, v127, v17
	v_fmac_f32_e32 v18, v138, v126
	v_fma_f32 v18, -v139, v127, v18
	v_fmac_f32_e32 v19, v142, v126
	v_fma_f32 v19, -v143, v127, v19
	ds_read_b64 v[124:125], v13 offset:1280
	ds_read_b64 v[126:127], v13 offset:1408
	ds_read_b128 v[128:131], v14 offset:80
	ds_read_b128 v[132:135], v14 offset:16976
	ds_read_b128 v[136:139], v14 offset:33872
	ds_read_b128 v[140:143], v14 offset:50768
	s_waitcnt lgkmcnt(6)
	v_fmac_f32_e32 v16, v104, v100
	v_fma_f32 v16, -v105, v101, v16
	v_fmac_f32_e32 v17, v108, v100
	v_fma_f32 v17, -v109, v101, v17
	v_fmac_f32_e32 v18, v112, v100
	v_fma_f32 v18, -v113, v101, v18
	v_fmac_f32_e32 v19, v116, v100
	v_fma_f32 v19, -v117, v101, v19
	v_fmac_f32_e32 v16, v106, v102
	v_fma_f32 v16, -v107, v103, v16
	v_fmac_f32_e32 v17, v110, v102
	v_fma_f32 v17, -v111, v103, v17
	v_fmac_f32_e32 v18, v114, v102
	v_fma_f32 v18, -v115, v103, v18
	v_fmac_f32_e32 v19, v118, v102
	v_fma_f32 v19, -v119, v103, v19
	ds_read_b64 v[100:101], v13 offset:1536
	ds_read_b64 v[102:103], v13 offset:1664
	ds_read_b128 v[104:107], v14 offset:96
	ds_read_b128 v[108:111], v14 offset:16992
	ds_read_b128 v[112:115], v14 offset:33888
	ds_read_b128 v[116:119], v14 offset:50784
	s_waitcnt lgkmcnt(6)
	v_fmac_f32_e32 v16, v128, v124
	v_fma_f32 v16, -v129, v125, v16
	v_fmac_f32_e32 v17, v132, v124
	v_fma_f32 v17, -v133, v125, v17
	v_fmac_f32_e32 v18, v136, v124
	v_fma_f32 v18, -v137, v125, v18
	v_fmac_f32_e32 v19, v140, v124
	v_fma_f32 v19, -v141, v125, v19
	v_fmac_f32_e32 v16, v130, v126
	v_fma_f32 v16, -v131, v127, v16
	v_fmac_f32_e32 v17, v134, v126
	v_fma_f32 v17, -v135, v127, v17
	v_fmac_f32_e32 v18, v138, v126
	v_fma_f32 v18, -v139, v127, v18
	v_fmac_f32_e32 v19, v142, v126
	v_fma_f32 v19, -v143, v127, v19
	ds_read_b64 v[124:125], v13 offset:1792
	ds_read_b64 v[126:127], v13 offset:1920
	ds_read_b128 v[128:131], v14 offset:112
	ds_read_b128 v[132:135], v14 offset:17008
	ds_read_b128 v[136:139], v14 offset:33904
	ds_read_b128 v[140:143], v14 offset:50800
	s_waitcnt lgkmcnt(6)
	v_fmac_f32_e32 v16, v104, v100
	v_fma_f32 v16, -v105, v101, v16
	v_fmac_f32_e32 v17, v108, v100
	v_fma_f32 v17, -v109, v101, v17
	v_fmac_f32_e32 v18, v112, v100
	v_fma_f32 v18, -v113, v101, v18
	v_fmac_f32_e32 v19, v116, v100
	v_fma_f32 v19, -v117, v101, v19
	v_fmac_f32_e32 v16, v106, v102
	v_fma_f32 v16, -v107, v103, v16
	v_fmac_f32_e32 v17, v110, v102
	v_fma_f32 v17, -v111, v103, v17
	v_fmac_f32_e32 v18, v114, v102
	v_fma_f32 v18, -v115, v103, v18
	v_fmac_f32_e32 v19, v118, v102
	v_fma_f32 v19, -v119, v103, v19
	ds_read_b64 v[100:101], v13 offset:2048
	ds_read_b64 v[102:103], v13 offset:2176
	ds_read_b128 v[104:107], v14 offset:128
	ds_read_b128 v[108:111], v14 offset:17024
	ds_read_b128 v[112:115], v14 offset:33920
	ds_read_b128 v[116:119], v14 offset:50816
	s_waitcnt lgkmcnt(6)
	v_fmac_f32_e32 v16, v128, v124
	v_fma_f32 v16, -v129, v125, v16
	v_fmac_f32_e32 v17, v132, v124
	v_fma_f32 v17, -v133, v125, v17
	v_fmac_f32_e32 v18, v136, v124
	v_fma_f32 v18, -v137, v125, v18
	v_fmac_f32_e32 v19, v140, v124
	v_fma_f32 v19, -v141, v125, v19
	v_fmac_f32_e32 v16, v130, v126
	v_fma_f32 v16, -v131, v127, v16
	v_fmac_f32_e32 v17, v134, v126
	v_fma_f32 v17, -v135, v127, v17
	v_fmac_f32_e32 v18, v138, v126
	v_fma_f32 v18, -v139, v127, v18
	v_fmac_f32_e32 v19, v142, v126
	v_fma_f32 v19, -v143, v127, v19
	ds_read_b64 v[124:125], v13 offset:2304
	ds_read_b64 v[126:127], v13 offset:2432
	ds_read_b128 v[128:131], v14 offset:144
	ds_read_b128 v[132:135], v14 offset:17040
	ds_read_b128 v[136:139], v14 offset:33936
	ds_read_b128 v[140:143], v14 offset:50832
	s_waitcnt lgkmcnt(6)
; __device__ __forceinline__ f32x2 cmul(f32x2 a, f32x2 b) { return (f32x2){a.x * b.x - a.y * b.y, a.x * b.y + a.y * b.x}; }
; __global__ void __launch_bounds__(NTHR, 2) hymba_fwd(Params P) {
;     ...
;             for (int idx = tid; idx < 4096; idx += NTHR) { const int d = idx >> 8, p = (idx >> 4) & 15, pp = idx & 15; float s = 0.f;
;                 for (int n = 0; n < 64; ++n) { const f32x2 t = cmul(CCl[p * 64 + n], PW[d * 64 + n]); const f32x2 b = BBl[n * 16 + pp]; s += t.x * b.x - t.y * b.y; }
	v_fmac_f32_e32 v16, v104, v100
	v_fma_f32 v16, -v105, v101, v16
	v_fmac_f32_e32 v17, v108, v100
	v_fma_f32 v17, -v109, v101, v17
	v_fmac_f32_e32 v18, v112, v100
	v_fma_f32 v18, -v113, v101, v18
	v_fmac_f32_e32 v19, v116, v100
	v_fma_f32 v19, -v117, v101, v19
	v_fmac_f32_e32 v16, v106, v102
	v_fma_f32 v16, -v107, v103, v16
	v_fmac_f32_e32 v17, v110, v102
	v_fma_f32 v17, -v111, v103, v17
	v_fmac_f32_e32 v18, v114, v102
	v_fma_f32 v18, -v115, v103, v18
	v_fmac_f32_e32 v19, v118, v102
	v_fma_f32 v19, -v119, v103, v19
	ds_read_b64 v[100:101], v13 offset:2560
	ds_read_b64 v[102:103], v13 offset:2688
	ds_read_b128 v[104:107], v14 offset:160
	ds_read_b128 v[108:111], v14 offset:17056
	ds_read_b128 v[112:115], v14 offset:33952
	ds_read_b128 v[116:119], v14 offset:50848
	s_waitcnt lgkmcnt(6)
	v_fmac_f32_e32 v16, v128, v124
	v_fma_f32 v16, -v129, v125, v16
	v_fmac_f32_e32 v17, v132, v124
	v_fma_f32 v17, -v133, v125, v17
	v_fmac_f32_e32 v18, v136, v124
	v_fma_f32 v18, -v137, v125, v18
	v_fmac_f32_e32 v19, v140, v124
	v_fma_f32 v19, -v141, v125, v19
	v_fmac_f32_e32 v16, v130, v126
	v_fma_f32 v16, -v131, v127, v16
	v_fmac_f32_e32 v17, v134, v126
	v_fma_f32 v17, -v135, v127, v17
	v_fmac_f32_e32 v18, v138, v126
	v_fma_f32 v18, -v139, v127, v18
	v_fmac_f32_e32 v19, v142, v126
	v_fma_f32 v19, -v143, v127, v19
	ds_read_b64 v[124:125], v13 offset:2816
	ds_read_b64 v[126:127], v13 offset:2944
	ds_read_b128 v[128:131], v14 offset:176
	ds_read_b128 v[132:135], v14 offset:17072
	ds_read_b128 v[136:139], v14 offset:33968
	ds_read_b128 v[140:143], v14 offset:50864
	s_waitcnt lgkmcnt(6)
	v_fmac_f32_e32 v16, v104, v100
	v_fma_f32 v16, -v105, v101, v16
	v_fmac_f32_e32 v17, v108, v100
	v_fma_f32 v17, -v109, v101, v17
	v_fmac_f32_e32 v18, v112, v100
	v_fma_f32 v18, -v113, v101, v18
	v_fmac_f32_e32 v19, v116, v100
	v_fma_f32 v19, -v117, v101, v19
	v_fmac_f32_e32 v16, v106, v102
	v_fma_f32 v16, -v107, v103, v16
	v_fmac_f32_e32 v17, v110, v102
	v_fma_f32 v17, -v111, v103, v17
	v_fmac_f32_e32 v18, v114, v102
	v_fma_f32 v18, -v115, v103, v18
	v_fmac_f32_e32 v19, v118, v102
	v_fma_f32 v19, -v119, v103, v19
	ds_read_b64 v[100:101], v13 offset:3072
	ds_read_b64 v[102:103], v13 offset:3200
	ds_read_b128 v[104:107], v14 offset:192
	ds_read_b128 v[108:111], v14 offset:17088
	ds_read_b128 v[112:115], v14 offset:33984
	ds_read_b128 v[116:119], v14 offset:50880
	s_waitcnt lgkmcnt(6)
	v_fmac_f32_e32 v16, v128, v124
	v_fma_f32 v16, -v129, v125, v16
	v_fmac_f32_e32 v17, v132, v124
	v_fma_f32 v17, -v133, v125, v17
	v_fmac_f32_e32 v18, v136, v124
	v_fma_f32 v18, -v137, v125, v18
	v_fmac_f32_e32 v19, v140, v124
	v_fma_f32 v19, -v141, v125, v19
	v_fmac_f32_e32 v16, v130, v126
	v_fma_f32 v16, -v131, v127, v16
	v_fmac_f32_e32 v17, v134, v126
	v_fma_f32 v17, -v135, v127, v17
	v_fmac_f32_e32 v18, v138, v126
	v_fma_f32 v18, -v139, v127, v18
	v_fmac_f32_e32 v19, v142, v126
	v_fma_f32 v19, -v143, v127, v19
	ds_read_b64 v[124:125], v13 offset:3328
	ds_read_b64 v[126:127], v13 offset:3456
	ds_read_b128 v[128:131], v14 offset:208
	ds_read_b128 v[132:135], v14 offset:17104
	ds_read_b128 v[136:139], v14 offset:34000
	ds_read_b128 v[140:143], v14 offset:50896
	s_waitcnt lgkmcnt(6)
	v_fmac_f32_e32 v16, v104, v100
	v_fma_f32 v16, -v105, v101, v16
	v_fmac_f32_e32 v17, v108, v100
	v_fma_f32 v17, -v109, v101, v17
	v_fmac_f32_e32 v18, v112, v100
	v_fma_f32 v18, -v113, v101, v18
	v_fmac_f32_e32 v19, v116, v100
	v_fma_f32 v19, -v117, v101, v19
	v_fmac_f32_e32 v16, v106, v102
	v_fma_f32 v16, -v107, v103, v16
	v_fmac_f32_e32 v17, v110, v102
	v_fma_f32 v17, -v111, v103, v17
	v_fmac_f32_e32 v18, v114, v102
	v_fma_f32 v18, -v115, v103, v18
	v_fmac_f32_e32 v19, v118, v102
	v_fma_f32 v19, -v119, v103, v19
	ds_read_b64 v[100:101], v13 offset:3584
	ds_read_b64 v[102:103], v13 offset:3712
	ds_read_b128 v[104:107], v14 offset:224
	ds_read_b128 v[108:111], v14 offset:17120
	ds_read_b128 v[112:115], v14 offset:34016
	ds_read_b128 v[116:119], v14 offset:50912
	s_waitcnt lgkmcnt(6)
	v_fmac_f32_e32 v16, v128, v124
	v_fma_f32 v16, -v129, v125, v16
	v_fmac_f32_e32 v17, v132, v124
	v_fma_f32 v17, -v133, v125, v17
	v_fmac_f32_e32 v18, v136, v124
	v_fma_f32 v18, -v137, v125, v18
	v_fmac_f32_e32 v19, v140, v124
	v_fma_f32 v19, -v141, v125, v19
	v_fmac_f32_e32 v16, v130, v126
	v_fma_f32 v16, -v131, v127, v16
	v_fmac_f32_e32 v17, v134, v126
	v_fma_f32 v17, -v135, v127, v17
	v_fmac_f32_e32 v18, v138, v126
	v_fma_f32 v18, -v139, v127, v18
	v_fmac_f32_e32 v19, v142, v126
	v_fma_f32 v19, -v143, v127, v19
	ds_read_b64 v[124:125], v13 offset:3840
	ds_read_b64 v[126:127], v13 offset:3968
	ds_read_b128 v[128:131], v14 offset:240
	ds_read_b128 v[132:135], v14 offset:17136
	ds_read_b128 v[136:139], v14 offset:34032
	ds_read_b128 v[140:143], v14 offset:50928
	s_waitcnt lgkmcnt(6)
	v_fmac_f32_e32 v16, v104, v100
	v_fma_f32 v16, -v105, v101, v16
	v_fmac_f32_e32 v17, v108, v100
	v_fma_f32 v17, -v109, v101, v17
	v_fmac_f32_e32 v18, v112, v100
	v_fma_f32 v18, -v113, v101, v18
	v_fmac_f32_e32 v19, v116, v100
	v_fma_f32 v19, -v117, v101, v19
	v_fmac_f32_e32 v16, v106, v102
	v_fma_f32 v16, -v107, v103, v16
	v_fmac_f32_e32 v17, v110, v102
	v_fma_f32 v17, -v111, v103, v17
	v_fmac_f32_e32 v18, v114, v102
	v_fma_f32 v18, -v115, v103, v18
	v_fmac_f32_e32 v19, v118, v102
	v_fma_f32 v19, -v119, v103, v19
	ds_read_b64 v[100:101], v13 offset:4096
	ds_read_b64 v[102:103], v13 offset:4224
	ds_read_b128 v[104:107], v14 offset:256
	ds_read_b128 v[108:111], v14 offset:17152
	ds_read_b128 v[112:115], v14 offset:34048
	ds_read_b128 v[116:119], v14 offset:50944
	s_waitcnt lgkmcnt(6)
; __device__ __forceinline__ f32x2 cmul(f32x2 a, f32x2 b) { return (f32x2){a.x * b.x - a.y * b.y, a.x * b.y + a.y * b.x}; }
; __global__ void __launch_bounds__(NTHR, 2) hymba_fwd(Params P) {
;     ...
;             for (int idx = tid; idx < 4096; idx += NTHR) { const int d = idx >> 8, p = (idx >> 4) & 15, pp = idx & 15; float s = 0.f;
;                 for (int n = 0; n < 64; ++n) { const f32x2 t = cmul(CCl[p * 64 + n], PW[d * 64 + n]); const f32x2 b = BBl[n * 16 + pp]; s += t.x * b.x - t.y * b.y; }
	v_fmac_f32_e32 v16, v128, v124
	v_fma_f32 v16, -v129, v125, v16
	v_fmac_f32_e32 v17, v132, v124
	v_fma_f32 v17, -v133, v125, v17
	v_fmac_f32_e32 v18, v136, v124
	v_fma_f32 v18, -v137, v125, v18
	v_fmac_f32_e32 v19, v140, v124
	v_fma_f32 v19, -v141, v125, v19
	v_fmac_f32_e32 v16, v130, v126
	v_fma_f32 v16, -v131, v127, v16
	v_fmac_f32_e32 v17, v134, v126
	v_fma_f32 v17, -v135, v127, v17
	v_fmac_f32_e32 v18, v138, v126
	v_fma_f32 v18, -v139, v127, v18
	v_fmac_f32_e32 v19, v142, v126
	v_fma_f32 v19, -v143, v127, v19
	ds_read_b64 v[124:125], v13 offset:4352
	ds_read_b64 v[126:127], v13 offset:4480
	ds_read_b128 v[128:131], v14 offset:272
	ds_read_b128 v[132:135], v14 offset:17168
	ds_read_b128 v[136:139], v14 offset:34064
	ds_read_b128 v[140:143], v14 offset:50960
	s_waitcnt lgkmcnt(6)
	v_fmac_f32_e32 v16, v104, v100
	v_fma_f32 v16, -v105, v101, v16
	v_fmac_f32_e32 v17, v108, v100
	v_fma_f32 v17, -v109, v101, v17
	v_fmac_f32_e32 v18, v112, v100
	v_fma_f32 v18, -v113, v101, v18
	v_fmac_f32_e32 v19, v116, v100
	v_fma_f32 v19, -v117, v101, v19
	v_fmac_f32_e32 v16, v106, v102
	v_fma_f32 v16, -v107, v103, v16
	v_fmac_f32_e32 v17, v110, v102
	v_fma_f32 v17, -v111, v103, v17
	v_fmac_f32_e32 v18, v114, v102
	v_fma_f32 v18, -v115, v103, v18
	v_fmac_f32_e32 v19, v118, v102
	v_fma_f32 v19, -v119, v103, v19
	ds_read_b64 v[100:101], v13 offset:4608
	ds_read_b64 v[102:103], v13 offset:4736
	ds_read_b128 v[104:107], v14 offset:288
	ds_read_b128 v[108:111], v14 offset:17184
	ds_read_b128 v[112:115], v14 offset:34080
	ds_read_b128 v[116:119], v14 offset:50976
	s_waitcnt lgkmcnt(6)
	v_fmac_f32_e32 v16, v128, v124
	v_fma_f32 v16, -v129, v125, v16
	v_fmac_f32_e32 v17, v132, v124
	v_fma_f32 v17, -v133, v125, v17
	v_fmac_f32_e32 v18, v136, v124
	v_fma_f32 v18, -v137, v125, v18
	v_fmac_f32_e32 v19, v140, v124
	v_fma_f32 v19, -v141, v125, v19
	v_fmac_f32_e32 v16, v130, v126
	v_fma_f32 v16, -v131, v127, v16
	v_fmac_f32_e32 v17, v134, v126
	v_fma_f32 v17, -v135, v127, v17
	v_fmac_f32_e32 v18, v138, v126
	v_fma_f32 v18, -v139, v127, v18
	v_fmac_f32_e32 v19, v142, v126
	v_fma_f32 v19, -v143, v127, v19
	ds_read_b64 v[124:125], v13 offset:4864
	ds_read_b64 v[126:127], v13 offset:4992
	ds_read_b128 v[128:131], v14 offset:304
	ds_read_b128 v[132:135], v14 offset:17200
	ds_read_b128 v[136:139], v14 offset:34096
	ds_read_b128 v[140:143], v14 offset:50992
	s_waitcnt lgkmcnt(6)
	v_fmac_f32_e32 v16, v104, v100
	v_fma_f32 v16, -v105, v101, v16
	v_fmac_f32_e32 v17, v108, v100
	v_fma_f32 v17, -v109, v101, v17
	v_fmac_f32_e32 v18, v112, v100
	v_fma_f32 v18, -v113, v101, v18
	v_fmac_f32_e32 v19, v116, v100
	v_fma_f32 v19, -v117, v101, v19
	v_fmac_f32_e32 v16, v106, v102
	v_fma_f32 v16, -v107, v103, v16
	v_fmac_f32_e32 v17, v110, v102
	v_fma_f32 v17, -v111, v103, v17
	v_fmac_f32_e32 v18, v114, v102
	v_fma_f32 v18, -v115, v103, v18
	v_fmac_f32_e32 v19, v118, v102
	v_fma_f32 v19, -v119, v103, v19
	ds_read_b64 v[100:101], v13 offset:5120
	ds_read_b64 v[102:103], v13 offset:5248
	ds_read_b128 v[104:107], v14 offset:320
	ds_read_b128 v[108:111], v14 offset:17216
	ds_read_b128 v[112:115], v14 offset:34112
	ds_read_b128 v[116:119], v14 offset:51008
	s_waitcnt lgkmcnt(6)
	v_fmac_f32_e32 v16, v128, v124
	v_fma_f32 v16, -v129, v125, v16
	v_fmac_f32_e32 v17, v132, v124
	v_fma_f32 v17, -v133, v125, v17
	v_fmac_f32_e32 v18, v136, v124
	v_fma_f32 v18, -v137, v125, v18
	v_fmac_f32_e32 v19, v140, v124
	v_fma_f32 v19, -v141, v125, v19
	v_fmac_f32_e32 v16, v130, v126
	v_fma_f32 v16, -v131, v127, v16
	v_fmac_f32_e32 v17, v134, v126
	v_fma_f32 v17, -v135, v127, v17
	v_fmac_f32_e32 v18, v138, v126
	v_fma_f32 v18, -v139, v127, v18
	v_fmac_f32_e32 v19, v142, v126
	v_fma_f32 v19, -v143, v127, v19
	ds_read_b64 v[124:125], v13 offset:5376
	ds_read_b64 v[126:127], v13 offset:5504
	ds_read_b128 v[128:131], v14 offset:336
	ds_read_b128 v[132:135], v14 offset:17232
	ds_read_b128 v[136:139], v14 offset:34128
	ds_read_b128 v[140:143], v14 offset:51024
	s_waitcnt lgkmcnt(6)
	v_fmac_f32_e32 v16, v104, v100
	v_fma_f32 v16, -v105, v101, v16
	v_fmac_f32_e32 v17, v108, v100
	v_fma_f32 v17, -v109, v101, v17
	v_fmac_f32_e32 v18, v112, v100
	v_fma_f32 v18, -v113, v101, v18
	v_fmac_f32_e32 v19, v116, v100
	v_fma_f32 v19, -v117, v101, v19
	v_fmac_f32_e32 v16, v106, v102
	v_fma_f32 v16, -v107, v103, v16
	v_fmac_f32_e32 v17, v110, v102
	v_fma_f32 v17, -v111, v103, v17
	v_fmac_f32_e32 v18, v114, v102
	v_fma_f32 v18, -v115, v103, v18
	v_fmac_f32_e32 v19, v118, v102
	v_fma_f32 v19, -v119, v103, v19
	ds_read_b64 v[100:101], v13 offset:5632
	ds_read_b64 v[102:103], v13 offset:5760
	ds_read_b128 v[104:107], v14 offset:352
	ds_read_b128 v[108:111], v14 offset:17248
	ds_read_b128 v[112:115], v14 offset:34144
	ds_read_b128 v[116:119], v14 offset:51040
	s_waitcnt lgkmcnt(6)
	v_fmac_f32_e32 v16, v128, v124
	v_fma_f32 v16, -v129, v125, v16
	v_fmac_f32_e32 v17, v132, v124
	v_fma_f32 v17, -v133, v125, v17
	v_fmac_f32_e32 v18, v136, v124
	v_fma_f32 v18, -v137, v125, v18
	v_fmac_f32_e32 v19, v140, v124
	v_fma_f32 v19, -v141, v125, v19
	v_fmac_f32_e32 v16, v130, v126
	v_fma_f32 v16, -v131, v127, v16
	v_fmac_f32_e32 v17, v134, v126
	v_fma_f32 v17, -v135, v127, v17
	v_fmac_f32_e32 v18, v138, v126
	v_fma_f32 v18, -v139, v127, v18
	v_fmac_f32_e32 v19, v142, v126
	v_fma_f32 v19, -v143, v127, v19
	ds_read_b64 v[124:125], v13 offset:5888
	ds_read_b64 v[126:127], v13 offset:6016
	ds_read_b128 v[128:131], v14 offset:368
	ds_read_b128 v[132:135], v14 offset:17264
	ds_read_b128 v[136:139], v14 offset:34160
	ds_read_b128 v[140:143], v14 offset:51056
	s_waitcnt lgkmcnt(6)
; __device__ __forceinline__ f32x2 cmul(f32x2 a, f32x2 b) { return (f32x2){a.x * b.x - a.y * b.y, a.x * b.y + a.y * b.x}; }
; __global__ void __launch_bounds__(NTHR, 2) hymba_fwd(Params P) {
;     ...
;             for (int idx = tid; idx < 4096; idx += NTHR) { const int d = idx >> 8, p = (idx >> 4) & 15, pp = idx & 15; float s = 0.f;
;                 for (int n = 0; n < 64; ++n) { const f32x2 t = cmul(CCl[p * 64 + n], PW[d * 64 + n]); const f32x2 b = BBl[n * 16 + pp]; s += t.x * b.x - t.y * b.y; }
	v_fmac_f32_e32 v16, v104, v100
	v_fma_f32 v16, -v105, v101, v16
	v_fmac_f32_e32 v17, v108, v100
	v_fma_f32 v17, -v109, v101, v17
	v_fmac_f32_e32 v18, v112, v100
	v_fma_f32 v18, -v113, v101, v18
	v_fmac_f32_e32 v19, v116, v100
	v_fma_f32 v19, -v117, v101, v19
	v_fmac_f32_e32 v16, v106, v102
	v_fma_f32 v16, -v107, v103, v16
	v_fmac_f32_e32 v17, v110, v102
	v_fma_f32 v17, -v111, v103, v17
	v_fmac_f32_e32 v18, v114, v102
	v_fma_f32 v18, -v115, v103, v18
	v_fmac_f32_e32 v19, v118, v102
	v_fma_f32 v19, -v119, v103, v19
	ds_read_b64 v[100:101], v13 offset:6144
	ds_read_b64 v[102:103], v13 offset:6272
	ds_read_b128 v[104:107], v14 offset:384
	ds_read_b128 v[108:111], v14 offset:17280
	ds_read_b128 v[112:115], v14 offset:34176
	ds_read_b128 v[116:119], v14 offset:51072
	s_waitcnt lgkmcnt(6)
	v_fmac_f32_e32 v16, v128, v124
	v_fma_f32 v16, -v129, v125, v16
	v_fmac_f32_e32 v17, v132, v124
	v_fma_f32 v17, -v133, v125, v17
	v_fmac_f32_e32 v18, v136, v124
	v_fma_f32 v18, -v137, v125, v18
	v_fmac_f32_e32 v19, v140, v124
	v_fma_f32 v19, -v141, v125, v19
	v_fmac_f32_e32 v16, v130, v126
	v_fma_f32 v16, -v131, v127, v16
	v_fmac_f32_e32 v17, v134, v126
	v_fma_f32 v17, -v135, v127, v17
	v_fmac_f32_e32 v18, v138, v126
	v_fma_f32 v18, -v139, v127, v18
	v_fmac_f32_e32 v19, v142, v126
	v_fma_f32 v19, -v143, v127, v19
	ds_read_b64 v[124:125], v13 offset:6400
	ds_read_b64 v[126:127], v13 offset:6528
	ds_read_b128 v[128:131], v14 offset:400
	ds_read_b128 v[132:135], v14 offset:17296
	ds_read_b128 v[136:139], v14 offset:34192
	ds_read_b128 v[140:143], v14 offset:51088
	s_waitcnt lgkmcnt(6)
	v_fmac_f32_e32 v16, v104, v100
	v_fma_f32 v16, -v105, v101, v16
	v_fmac_f32_e32 v17, v108, v100
	v_fma_f32 v17, -v109, v101, v17
	v_fmac_f32_e32 v18, v112, v100
	v_fma_f32 v18, -v113, v101, v18
	v_fmac_f32_e32 v19, v116, v100
	v_fma_f32 v19, -v117, v101, v19
	v_fmac_f32_e32 v16, v106, v102
	v_fma_f32 v16, -v107, v103, v16
	v_fmac_f32_e32 v17, v110, v102
	v_fma_f32 v17, -v111, v103, v17
	v_fmac_f32_e32 v18, v114, v102
	v_fma_f32 v18, -v115, v103, v18
	v_fmac_f32_e32 v19, v118, v102
	v_fma_f32 v19, -v119, v103, v19
	ds_read_b64 v[100:101], v13 offset:6656
	ds_read_b64 v[102:103], v13 offset:6784
	ds_read_b128 v[104:107], v14 offset:416
	ds_read_b128 v[108:111], v14 offset:17312
	ds_read_b128 v[112:115], v14 offset:34208
	ds_read_b128 v[116:119], v14 offset:51104
	s_waitcnt lgkmcnt(6)
	v_fmac_f32_e32 v16, v128, v124
	v_fma_f32 v16, -v129, v125, v16
	v_fmac_f32_e32 v17, v132, v124
	v_fma_f32 v17, -v133, v125, v17
	v_fmac_f32_e32 v18, v136, v124
	v_fma_f32 v18, -v137, v125, v18
	v_fmac_f32_e32 v19, v140, v124
	v_fma_f32 v19, -v141, v125, v19
	v_fmac_f32_e32 v16, v130, v126
	v_fma_f32 v16, -v131, v127, v16
	v_fmac_f32_e32 v17, v134, v126
	v_fma_f32 v17, -v135, v127, v17
	v_fmac_f32_e32 v18, v138, v126
	v_fma_f32 v18, -v139, v127, v18
	v_fmac_f32_e32 v19, v142, v126
	v_fma_f32 v19, -v143, v127, v19
	ds_read_b64 v[124:125], v13 offset:6912
	ds_read_b64 v[126:127], v13 offset:7040
	ds_read_b128 v[128:131], v14 offset:432
	ds_read_b128 v[132:135], v14 offset:17328
	ds_read_b128 v[136:139], v14 offset:34224
	ds_read_b128 v[140:143], v14 offset:51120
	s_waitcnt lgkmcnt(6)
	v_fmac_f32_e32 v16, v104, v100
	v_fma_f32 v16, -v105, v101, v16
	v_fmac_f32_e32 v17, v108, v100
	v_fma_f32 v17, -v109, v101, v17
	v_fmac_f32_e32 v18, v112, v100
	v_fma_f32 v18, -v113, v101, v18
	v_fmac_f32_e32 v19, v116, v100
	v_fma_f32 v19, -v117, v101, v19
	v_fmac_f32_e32 v16, v106, v102
	v_fma_f32 v16, -v107, v103, v16
	v_fmac_f32_e32 v17, v110, v102
	v_fma_f32 v17, -v111, v103, v17
	v_fmac_f32_e32 v18, v114, v102
	v_fma_f32 v18, -v115, v103, v18
	v_fmac_f32_e32 v19, v118, v102
	v_fma_f32 v19, -v119, v103, v19
	ds_read_b64 v[100:101], v13 offset:7168
	ds_read_b64 v[102:103], v13 offset:7296
	ds_read_b128 v[104:107], v14 offset:448
	ds_read_b128 v[108:111], v14 offset:17344
	ds_read_b128 v[112:115], v14 offset:34240
	ds_read_b128 v[116:119], v14 offset:51136
	s_waitcnt lgkmcnt(6)
	v_fmac_f32_e32 v16, v128, v124
	v_fma_f32 v16, -v129, v125, v16
	v_fmac_f32_e32 v17, v132, v124
	v_fma_f32 v17, -v133, v125, v17
	v_fmac_f32_e32 v18, v136, v124
	v_fma_f32 v18, -v137, v125, v18
	v_fmac_f32_e32 v19, v140, v124
	v_fma_f32 v19, -v141, v125, v19
	v_fmac_f32_e32 v16, v130, v126
	v_fma_f32 v16, -v131, v127, v16
	v_fmac_f32_e32 v17, v134, v126
	v_fma_f32 v17, -v135, v127, v17
	v_fmac_f32_e32 v18, v138, v126
	v_fma_f32 v18, -v139, v127, v18
	v_fmac_f32_e32 v19, v142, v126
	v_fma_f32 v19, -v143, v127, v19
	ds_read_b64 v[124:125], v13 offset:7424
	ds_read_b64 v[126:127], v13 offset:7552
	ds_read_b128 v[128:131], v14 offset:464
	ds_read_b128 v[132:135], v14 offset:17360
	ds_read_b128 v[136:139], v14 offset:34256
	ds_read_b128 v[140:143], v14 offset:51152
	s_waitcnt lgkmcnt(6)
	v_fmac_f32_e32 v16, v104, v100
	v_fma_f32 v16, -v105, v101, v16
	v_fmac_f32_e32 v17, v108, v100
	v_fma_f32 v17, -v109, v101, v17
	v_fmac_f32_e32 v18, v112, v100
	v_fma_f32 v18, -v113, v101, v18
	v_fmac_f32_e32 v19, v116, v100
	v_fma_f32 v19, -v117, v101, v19
	v_fmac_f32_e32 v16, v106, v102
	v_fma_f32 v16, -v107, v103, v16
	v_fmac_f32_e32 v17, v110, v102
	v_fma_f32 v17, -v111, v103, v17
	v_fmac_f32_e32 v18, v114, v102
	v_fma_f32 v18, -v115, v103, v18
	v_fmac_f32_e32 v19, v118, v102
	v_fma_f32 v19, -v119, v103, v19
	ds_read_b64 v[100:101], v13 offset:7680
	ds_read_b64 v[102:103], v13 offset:7808
	ds_read_b128 v[104:107], v14 offset:480
	ds_read_b128 v[108:111], v14 offset:17376
	ds_read_b128 v[112:115], v14 offset:34272
	ds_read_b128 v[116:119], v14 offset:51168
	s_waitcnt lgkmcnt(6)
; __device__ __forceinline__ f32x2 cmul(f32x2 a, f32x2 b) { return (f32x2){a.x * b.x - a.y * b.y, a.x * b.y + a.y * b.x}; }
; __global__ void __launch_bounds__(NTHR, 2) hymba_fwd(Params P) {
;     ...
;             for (int idx = tid; idx < 4096; idx += NTHR) { const int d = idx >> 8, p = (idx >> 4) & 15, pp = idx & 15; float s = 0.f;
;                 for (int n = 0; n < 64; ++n) { const f32x2 t = cmul(CCl[p * 64 + n], PW[d * 64 + n]); const f32x2 b = BBl[n * 16 + pp]; s += t.x * b.x - t.y * b.y; }
;                 if (d == 0 && p == pp) s += P.d_skip[g * 16 + p];
;                 KT[idx] = s; }
	v_fmac_f32_e32 v16, v128, v124
	v_fma_f32 v16, -v129, v125, v16
	v_fmac_f32_e32 v17, v132, v124
	v_fma_f32 v17, -v133, v125, v17
	v_fmac_f32_e32 v18, v136, v124
	v_fma_f32 v18, -v137, v125, v18
	v_fmac_f32_e32 v19, v140, v124
	v_fma_f32 v19, -v141, v125, v19
	v_fmac_f32_e32 v16, v130, v126
	v_fma_f32 v16, -v131, v127, v16
	v_fmac_f32_e32 v17, v134, v126
	v_fma_f32 v17, -v135, v127, v17
	v_fmac_f32_e32 v18, v138, v126
	v_fma_f32 v18, -v139, v127, v18
	v_fmac_f32_e32 v19, v142, v126
	v_fma_f32 v19, -v143, v127, v19
	ds_read_b64 v[124:125], v13 offset:7936
	ds_read_b64 v[126:127], v13 offset:8064
	ds_read_b128 v[128:131], v14 offset:496
	ds_read_b128 v[132:135], v14 offset:17392
	ds_read_b128 v[136:139], v14 offset:34288
	ds_read_b128 v[140:143], v14 offset:51184
	s_waitcnt lgkmcnt(6)
	v_fmac_f32_e32 v16, v104, v100
	v_fma_f32 v16, -v105, v101, v16
	v_fmac_f32_e32 v17, v108, v100
	v_fma_f32 v17, -v109, v101, v17
	v_fmac_f32_e32 v18, v112, v100
	v_fma_f32 v18, -v113, v101, v18
	v_fmac_f32_e32 v19, v116, v100
	v_fma_f32 v19, -v117, v101, v19
	v_fmac_f32_e32 v16, v106, v102
	v_fma_f32 v16, -v107, v103, v16
	v_fmac_f32_e32 v17, v110, v102
	v_fma_f32 v17, -v111, v103, v17
	v_fmac_f32_e32 v18, v114, v102
	v_fma_f32 v18, -v115, v103, v18
	v_fmac_f32_e32 v19, v118, v102
	v_fma_f32 v19, -v119, v103, v19
	s_waitcnt lgkmcnt(0)
	v_fmac_f32_e32 v16, v128, v124
	v_fma_f32 v16, -v129, v125, v16
	v_fmac_f32_e32 v17, v132, v124
	v_fma_f32 v17, -v133, v125, v17
	v_fmac_f32_e32 v18, v136, v124
	v_fma_f32 v18, -v137, v125, v18
	v_fmac_f32_e32 v19, v140, v124
	v_fma_f32 v19, -v141, v125, v19
	v_fmac_f32_e32 v16, v130, v126
	v_fma_f32 v16, -v131, v127, v16
	v_fmac_f32_e32 v17, v134, v126
	v_fma_f32 v17, -v135, v127, v17
	v_fmac_f32_e32 v18, v138, v126
	v_fma_f32 v18, -v139, v127, v18
	v_fmac_f32_e32 v19, v142, v126
	v_fma_f32 v19, -v143, v127, v19
	s_waitcnt vmcnt(0)
	v_add_f32_e32 v9, v16, v9
	v_cndmask_b32_e64 v16, v16, v9, s[6:7]
	ds_write_b32 v15, v16 offset:0
	ds_write_b32 v15, v17 offset:2048
	ds_write_b32 v15, v18 offset:4096
	ds_write_b32 v15, v19 offset:6144
	s_waitcnt lgkmcnt(0)
	s_barrier
	ds_read_b64 v[20:21], v11
	ds_read_b64 v[22:23], v11 offset:4096
	ds_read_b64 v[24:25], v10 offset:4096
	ds_read_b64 v[26:27], v10 offset:4608
	ds_read_b64 v[28:29], v10 offset:5120
	ds_read_b64 v[30:31], v10 offset:5632
	ds_read_b64 v[32:33], v10 offset:6144
	ds_read_b64 v[34:35], v10 offset:6656
	ds_read_b64 v[36:37], v10 offset:7168
	ds_read_b64 v[38:39], v10 offset:7680
	s_waitcnt lgkmcnt(0)
	v_mul_f32_e32 v84, v21, v25
	v_mul_f32_e32 v85, v21, v24
	v_fma_f32 v84, v20, v24, -v84
	v_fma_f32 v85, v20, v25, v85
	ds_write_b64 v12, v[84:85] offset:0
	v_mul_f32_e32 v86, v23, v25
	v_mul_f32_e32 v87, v23, v24
	v_fma_f32 v86, v22, v24, -v86
	v_fma_f32 v87, v22, v25, v87
	ds_write_b64 v12, v[86:87] offset:4224
	v_mul_f32_e32 v88, v21, v27
	v_mul_f32_e32 v89, v21, v26
	v_fma_f32 v88, v20, v26, -v88
	v_fma_f32 v89, v20, v27, v89
	ds_write_b64 v12, v[88:89] offset:8448
	v_mul_f32_e32 v90, v23, v27
	v_mul_f32_e32 v91, v23, v26
	v_fma_f32 v90, v22, v26, -v90
	v_fma_f32 v91, v22, v27, v91
	ds_write_b64 v12, v[90:91] offset:12672
	v_mul_f32_e32 v84, v21, v29
	v_mul_f32_e32 v85, v21, v28
	v_fma_f32 v84, v20, v28, -v84
	v_fma_f32 v85, v20, v29, v85
	ds_write_b64 v12, v[84:85] offset:16896
	v_mul_f32_e32 v86, v23, v29
	v_mul_f32_e32 v87, v23, v28
	v_fma_f32 v86, v22, v28, -v86
	v_fma_f32 v87, v22, v29, v87
	ds_write_b64 v12, v[86:87] offset:21120
	v_mul_f32_e32 v88, v21, v31
	v_mul_f32_e32 v89, v21, v30
	v_fma_f32 v88, v20, v30, -v88
	v_fma_f32 v89, v20, v31, v89
	ds_write_b64 v12, v[88:89] offset:25344
	v_mul_f32_e32 v90, v23, v31
	v_mul_f32_e32 v91, v23, v30
	v_fma_f32 v90, v22, v30, -v90
	v_fma_f32 v91, v22, v31, v91
	ds_write_b64 v12, v[90:91] offset:29568
	v_mul_f32_e32 v84, v21, v33
	v_mul_f32_e32 v85, v21, v32
	v_fma_f32 v84, v20, v32, -v84
	v_fma_f32 v85, v20, v33, v85
	ds_write_b64 v12, v[84:85] offset:33792
	v_mul_f32_e32 v86, v23, v33
	v_mul_f32_e32 v87, v23, v32
	v_fma_f32 v86, v22, v32, -v86
	v_fma_f32 v87, v22, v33, v87
	ds_write_b64 v12, v[86:87] offset:38016
	v_mul_f32_e32 v88, v21, v35
	v_mul_f32_e32 v89, v21, v34
	v_fma_f32 v88, v20, v34, -v88
	v_fma_f32 v89, v20, v35, v89
	ds_write_b64 v12, v[88:89] offset:42240
	v_mul_f32_e32 v90, v23, v35
	v_mul_f32_e32 v91, v23, v34
	v_fma_f32 v90, v22, v34, -v90
	v_fma_f32 v91, v22, v35, v91
	ds_write_b64 v12, v[90:91] offset:46464
	v_mul_f32_e32 v84, v21, v37
	v_mul_f32_e32 v85, v21, v36
	v_fma_f32 v84, v20, v36, -v84
	v_fma_f32 v85, v20, v37, v85
	ds_write_b64 v12, v[84:85] offset:50688
	v_mul_f32_e32 v86, v23, v37
	v_mul_f32_e32 v87, v23, v36
	v_fma_f32 v86, v22, v36, -v86
	v_fma_f32 v87, v22, v37, v87
	ds_write_b64 v12, v[86:87] offset:54912
	v_mul_f32_e32 v88, v21, v39
	v_mul_f32_e32 v89, v21, v38
	v_fma_f32 v88, v20, v38, -v88
	v_fma_f32 v89, v20, v39, v89
	ds_write_b64 v12, v[88:89] offset:59136
	v_mul_f32_e32 v90, v23, v39
	v_mul_f32_e32 v91, v23, v38
	v_fma_f32 v90, v22, v38, -v90
	v_fma_f32 v91, v22, v39, v91
	ds_write_b64 v12, v[90:91] offset:63360
	s_waitcnt lgkmcnt(0)
	s_barrier
; __device__ __forceinline__ f32x2 cmul(f32x2 a, f32x2 b) { return (f32x2){a.x * b.x - a.y * b.y, a.x * b.y + a.y * b.x}; }
; __global__ void __launch_bounds__(NTHR, 2) hymba_fwd(Params P) {
;     ...
;             for (int idx = tid; idx < 4096; idx += NTHR) { const int d = idx >> 8, p = (idx >> 4) & 15, pp = idx & 15; float s = 0.f;
;                 for (int n = 0; n < 64; ++n) { const f32x2 t = cmul(CCl[p * 64 + n], PW[d * 64 + n]); const f32x2 b = BBl[n * 16 + pp]; s += t.x * b.x - t.y * b.y; }
	v_mov_b32_e32 v16, 0
	v_mov_b32_e32 v17, 0
	v_mov_b32_e32 v18, 0
	v_mov_b32_e32 v19, 0
	ds_read_b64 v[100:101], v13 offset:0
	ds_read_b64 v[102:103], v13 offset:128
	ds_read_b128 v[104:107], v14 offset:0
	ds_read_b128 v[108:111], v14 offset:16896
	ds_read_b128 v[112:115], v14 offset:33792
	ds_read_b128 v[116:119], v14 offset:50688
	ds_read_b64 v[124:125], v13 offset:256
	ds_read_b64 v[126:127], v13 offset:384
	ds_read_b128 v[128:131], v14 offset:16
	ds_read_b128 v[132:135], v14 offset:16912
	ds_read_b128 v[136:139], v14 offset:33808
	ds_read_b128 v[140:143], v14 offset:50704
	s_waitcnt lgkmcnt(6)
	v_fmac_f32_e32 v16, v104, v100
	v_fma_f32 v16, -v105, v101, v16
	v_fmac_f32_e32 v17, v108, v100
	v_fma_f32 v17, -v109, v101, v17
	v_fmac_f32_e32 v18, v112, v100
	v_fma_f32 v18, -v113, v101, v18
	v_fmac_f32_e32 v19, v116, v100
	v_fma_f32 v19, -v117, v101, v19
	v_fmac_f32_e32 v16, v106, v102
	v_fma_f32 v16, -v107, v103, v16
	v_fmac_f32_e32 v17, v110, v102
	v_fma_f32 v17, -v111, v103, v17
	v_fmac_f32_e32 v18, v114, v102
	v_fma_f32 v18, -v115, v103, v18
	v_fmac_f32_e32 v19, v118, v102
	v_fma_f32 v19, -v119, v103, v19
	ds_read_b64 v[100:101], v13 offset:512
	ds_read_b64 v[102:103], v13 offset:640
	ds_read_b128 v[104:107], v14 offset:32
	ds_read_b128 v[108:111], v14 offset:16928
	ds_read_b128 v[112:115], v14 offset:33824
	ds_read_b128 v[116:119], v14 offset:50720
	s_waitcnt lgkmcnt(6)
	v_fmac_f32_e32 v16, v128, v124
	v_fma_f32 v16, -v129, v125, v16
	v_fmac_f32_e32 v17, v132, v124
	v_fma_f32 v17, -v133, v125, v17
	v_fmac_f32_e32 v18, v136, v124
	v_fma_f32 v18, -v137, v125, v18
	v_fmac_f32_e32 v19, v140, v124
	v_fma_f32 v19, -v141, v125, v19
	v_fmac_f32_e32 v16, v130, v126
	v_fma_f32 v16, -v131, v127, v16
	v_fmac_f32_e32 v17, v134, v126
	v_fma_f32 v17, -v135, v127, v17
	v_fmac_f32_e32 v18, v138, v126
	v_fma_f32 v18, -v139, v127, v18
	v_fmac_f32_e32 v19, v142, v126
	v_fma_f32 v19, -v143, v127, v19
	ds_read_b64 v[124:125], v13 offset:768
	ds_read_b64 v[126:127], v13 offset:896
	ds_read_b128 v[128:131], v14 offset:48
	ds_read_b128 v[132:135], v14 offset:16944
	ds_read_b128 v[136:139], v14 offset:33840
	ds_read_b128 v[140:143], v14 offset:50736
	s_waitcnt lgkmcnt(6)
	v_fmac_f32_e32 v16, v104, v100
	v_fma_f32 v16, -v105, v101, v16
	v_fmac_f32_e32 v17, v108, v100
	v_fma_f32 v17, -v109, v101, v17
	v_fmac_f32_e32 v18, v112, v100
	v_fma_f32 v18, -v113, v101, v18
	v_fmac_f32_e32 v19, v116, v100
	v_fma_f32 v19, -v117, v101, v19
	v_fmac_f32_e32 v16, v106, v102
	v_fma_f32 v16, -v107, v103, v16
	v_fmac_f32_e32 v17, v110, v102
	v_fma_f32 v17, -v111, v103, v17
	v_fmac_f32_e32 v18, v114, v102
	v_fma_f32 v18, -v115, v103, v18
	v_fmac_f32_e32 v19, v118, v102
	v_fma_f32 v19, -v119, v103, v19
	ds_read_b64 v[100:101], v13 offset:1024
	ds_read_b64 v[102:103], v13 offset:1152
	ds_read_b128 v[104:107], v14 offset:64
	ds_read_b128 v[108:111], v14 offset:16960
	ds_read_b128 v[112:115], v14 offset:33856
	ds_read_b128 v[116:119], v14 offset:50752
	s_waitcnt lgkmcnt(6)
	v_fmac_f32_e32 v16, v128, v124
	v_fma_f32 v16, -v129, v125, v16
	v_fmac_f32_e32 v17, v132, v124
	v_fma_f32 v17, -v133, v125, v17
	v_fmac_f32_e32 v18, v136, v124
	v_fma_f32 v18, -v137, v125, v18
	v_fmac_f32_e32 v19, v140, v124
	v_fma_f32 v19, -v141, v125, v19
	v_fmac_f32_e32 v16, v130, v126
	v_fma_f32 v16, -v131, v127, v16
	v_fmac_f32_e32 v17, v134, v126
	v_fma_f32 v17, -v135, v127, v17
	v_fmac_f32_e32 v18, v138, v126
	v_fma_f32 v18, -v139, v127, v18
	v_fmac_f32_e32 v19, v142, v126
	v_fma_f32 v19, -v143, v127, v19
	ds_read_b64 v[124:125], v13 offset:1280
	ds_read_b64 v[126:127], v13 offset:1408
	ds_read_b128 v[128:131], v14 offset:80
	ds_read_b128 v[132:135], v14 offset:16976
	ds_read_b128 v[136:139], v14 offset:33872
	ds_read_b128 v[140:143], v14 offset:50768
	s_waitcnt lgkmcnt(6)
	v_fmac_f32_e32 v16, v104, v100
	v_fma_f32 v16, -v105, v101, v16
	v_fmac_f32_e32 v17, v108, v100
	v_fma_f32 v17, -v109, v101, v17
	v_fmac_f32_e32 v18, v112, v100
	v_fma_f32 v18, -v113, v101, v18
	v_fmac_f32_e32 v19, v116, v100
	v_fma_f32 v19, -v117, v101, v19
	v_fmac_f32_e32 v16, v106, v102
	v_fma_f32 v16, -v107, v103, v16
	v_fmac_f32_e32 v17, v110, v102
	v_fma_f32 v17, -v111, v103, v17
	v_fmac_f32_e32 v18, v114, v102
	v_fma_f32 v18, -v115, v103, v18
	v_fmac_f32_e32 v19, v118, v102
	v_fma_f32 v19, -v119, v103, v19
	ds_read_b64 v[100:101], v13 offset:1536
	ds_read_b64 v[102:103], v13 offset:1664
	ds_read_b128 v[104:107], v14 offset:96
	ds_read_b128 v[108:111], v14 offset:16992
	ds_read_b128 v[112:115], v14 offset:33888
	ds_read_b128 v[116:119], v14 offset:50784
	s_waitcnt lgkmcnt(6)
	v_fmac_f32_e32 v16, v128, v124
	v_fma_f32 v16, -v129, v125, v16
	v_fmac_f32_e32 v17, v132, v124
	v_fma_f32 v17, -v133, v125, v17
	v_fmac_f32_e32 v18, v136, v124
	v_fma_f32 v18, -v137, v125, v18
	v_fmac_f32_e32 v19, v140, v124
	v_fma_f32 v19, -v141, v125, v19
	v_fmac_f32_e32 v16, v130, v126
	v_fma_f32 v16, -v131, v127, v16
	v_fmac_f32_e32 v17, v134, v126
	v_fma_f32 v17, -v135, v127, v17
	v_fmac_f32_e32 v18, v138, v126
	v_fma_f32 v18, -v139, v127, v18
	v_fmac_f32_e32 v19, v142, v126
	v_fma_f32 v19, -v143, v127, v19
	ds_read_b64 v[124:125], v13 offset:1792
	ds_read_b64 v[126:127], v13 offset:1920
	ds_read_b128 v[128:131], v14 offset:112
	ds_read_b128 v[132:135], v14 offset:17008
	ds_read_b128 v[136:139], v14 offset:33904
	ds_read_b128 v[140:143], v14 offset:50800
	s_waitcnt lgkmcnt(6)
; __device__ __forceinline__ f32x2 cmul(f32x2 a, f32x2 b) { return (f32x2){a.x * b.x - a.y * b.y, a.x * b.y + a.y * b.x}; }
; __global__ void __launch_bounds__(NTHR, 2) hymba_fwd(Params P) {
;     ...
;             for (int idx = tid; idx < 4096; idx += NTHR) { const int d = idx >> 8, p = (idx >> 4) & 15, pp = idx & 15; float s = 0.f;
;                 for (int n = 0; n < 64; ++n) { const f32x2 t = cmul(CCl[p * 64 + n], PW[d * 64 + n]); const f32x2 b = BBl[n * 16 + pp]; s += t.x * b.x - t.y * b.y; }
	v_fmac_f32_e32 v16, v104, v100
	v_fma_f32 v16, -v105, v101, v16
	v_fmac_f32_e32 v17, v108, v100
	v_fma_f32 v17, -v109, v101, v17
	v_fmac_f32_e32 v18, v112, v100
	v_fma_f32 v18, -v113, v101, v18
	v_fmac_f32_e32 v19, v116, v100
	v_fma_f32 v19, -v117, v101, v19
	v_fmac_f32_e32 v16, v106, v102
	v_fma_f32 v16, -v107, v103, v16
	v_fmac_f32_e32 v17, v110, v102
	v_fma_f32 v17, -v111, v103, v17
	v_fmac_f32_e32 v18, v114, v102
	v_fma_f32 v18, -v115, v103, v18
	v_fmac_f32_e32 v19, v118, v102
	v_fma_f32 v19, -v119, v103, v19
	ds_read_b64 v[100:101], v13 offset:2048
	ds_read_b64 v[102:103], v13 offset:2176
	ds_read_b128 v[104:107], v14 offset:128
	ds_read_b128 v[108:111], v14 offset:17024
	ds_read_b128 v[112:115], v14 offset:33920
	ds_read_b128 v[116:119], v14 offset:50816
	s_waitcnt lgkmcnt(6)
	v_fmac_f32_e32 v16, v128, v124
	v_fma_f32 v16, -v129, v125, v16
	v_fmac_f32_e32 v17, v132, v124
	v_fma_f32 v17, -v133, v125, v17
	v_fmac_f32_e32 v18, v136, v124
	v_fma_f32 v18, -v137, v125, v18
	v_fmac_f32_e32 v19, v140, v124
	v_fma_f32 v19, -v141, v125, v19
	v_fmac_f32_e32 v16, v130, v126
	v_fma_f32 v16, -v131, v127, v16
	v_fmac_f32_e32 v17, v134, v126
	v_fma_f32 v17, -v135, v127, v17
	v_fmac_f32_e32 v18, v138, v126
	v_fma_f32 v18, -v139, v127, v18
	v_fmac_f32_e32 v19, v142, v126
	v_fma_f32 v19, -v143, v127, v19
	ds_read_b64 v[124:125], v13 offset:2304
	ds_read_b64 v[126:127], v13 offset:2432
	ds_read_b128 v[128:131], v14 offset:144
	ds_read_b128 v[132:135], v14 offset:17040
	ds_read_b128 v[136:139], v14 offset:33936
	ds_read_b128 v[140:143], v14 offset:50832
	s_waitcnt lgkmcnt(6)
	v_fmac_f32_e32 v16, v104, v100
	v_fma_f32 v16, -v105, v101, v16
	v_fmac_f32_e32 v17, v108, v100
	v_fma_f32 v17, -v109, v101, v17
	v_fmac_f32_e32 v18, v112, v100
	v_fma_f32 v18, -v113, v101, v18
	v_fmac_f32_e32 v19, v116, v100
	v_fma_f32 v19, -v117, v101, v19
	v_fmac_f32_e32 v16, v106, v102
	v_fma_f32 v16, -v107, v103, v16
	v_fmac_f32_e32 v17, v110, v102
	v_fma_f32 v17, -v111, v103, v17
	v_fmac_f32_e32 v18, v114, v102
	v_fma_f32 v18, -v115, v103, v18
	v_fmac_f32_e32 v19, v118, v102
	v_fma_f32 v19, -v119, v103, v19
	ds_read_b64 v[100:101], v13 offset:2560
	ds_read_b64 v[102:103], v13 offset:2688
	ds_read_b128 v[104:107], v14 offset:160
	ds_read_b128 v[108:111], v14 offset:17056
	ds_read_b128 v[112:115], v14 offset:33952
	ds_read_b128 v[116:119], v14 offset:50848
	s_waitcnt lgkmcnt(6)
	v_fmac_f32_e32 v16, v128, v124
	v_fma_f32 v16, -v129, v125, v16
	v_fmac_f32_e32 v17, v132, v124
	v_fma_f32 v17, -v133, v125, v17
	v_fmac_f32_e32 v18, v136, v124
	v_fma_f32 v18, -v137, v125, v18
	v_fmac_f32_e32 v19, v140, v124
	v_fma_f32 v19, -v141, v125, v19
	v_fmac_f32_e32 v16, v130, v126
	v_fma_f32 v16, -v131, v127, v16
	v_fmac_f32_e32 v17, v134, v126
	v_fma_f32 v17, -v135, v127, v17
	v_fmac_f32_e32 v18, v138, v126
	v_fma_f32 v18, -v139, v127, v18
	v_fmac_f32_e32 v19, v142, v126
	v_fma_f32 v19, -v143, v127, v19
	ds_read_b64 v[124:125], v13 offset:2816
	ds_read_b64 v[126:127], v13 offset:2944
	ds_read_b128 v[128:131], v14 offset:176
	ds_read_b128 v[132:135], v14 offset:17072
	ds_read_b128 v[136:139], v14 offset:33968
	ds_read_b128 v[140:143], v14 offset:50864
	s_waitcnt lgkmcnt(6)
	v_fmac_f32_e32 v16, v104, v100
	v_fma_f32 v16, -v105, v101, v16
	v_fmac_f32_e32 v17, v108, v100
	v_fma_f32 v17, -v109, v101, v17
	v_fmac_f32_e32 v18, v112, v100
	v_fma_f32 v18, -v113, v101, v18
	v_fmac_f32_e32 v19, v116, v100
	v_fma_f32 v19, -v117, v101, v19
	v_fmac_f32_e32 v16, v106, v102
	v_fma_f32 v16, -v107, v103, v16
	v_fmac_f32_e32 v17, v110, v102
	v_fma_f32 v17, -v111, v103, v17
	v_fmac_f32_e32 v18, v114, v102
	v_fma_f32 v18, -v115, v103, v18
	v_fmac_f32_e32 v19, v118, v102
	v_fma_f32 v19, -v119, v103, v19
	ds_read_b64 v[100:101], v13 offset:3072
	ds_read_b64 v[102:103], v13 offset:3200
	ds_read_b128 v[104:107], v14 offset:192
	ds_read_b128 v[108:111], v14 offset:17088
	ds_read_b128 v[112:115], v14 offset:33984
	ds_read_b128 v[116:119], v14 offset:50880
	s_waitcnt lgkmcnt(6)
	v_fmac_f32_e32 v16, v128, v124
	v_fma_f32 v16, -v129, v125, v16
	v_fmac_f32_e32 v17, v132, v124
	v_fma_f32 v17, -v133, v125, v17
	v_fmac_f32_e32 v18, v136, v124
	v_fma_f32 v18, -v137, v125, v18
	v_fmac_f32_e32 v19, v140, v124
	v_fma_f32 v19, -v141, v125, v19
	v_fmac_f32_e32 v16, v130, v126
	v_fma_f32 v16, -v131, v127, v16
	v_fmac_f32_e32 v17, v134, v126
	v_fma_f32 v17, -v135, v127, v17
	v_fmac_f32_e32 v18, v138, v126
	v_fma_f32 v18, -v139, v127, v18
	v_fmac_f32_e32 v19, v142, v126
	v_fma_f32 v19, -v143, v127, v19
	ds_read_b64 v[124:125], v13 offset:3328
	ds_read_b64 v[126:127], v13 offset:3456
	ds_read_b128 v[128:131], v14 offset:208
	ds_read_b128 v[132:135], v14 offset:17104
	ds_read_b128 v[136:139], v14 offset:34000
	ds_read_b128 v[140:143], v14 offset:50896
	s_waitcnt lgkmcnt(6)
	v_fmac_f32_e32 v16, v104, v100
	v_fma_f32 v16, -v105, v101, v16
	v_fmac_f32_e32 v17, v108, v100
	v_fma_f32 v17, -v109, v101, v17
	v_fmac_f32_e32 v18, v112, v100
	v_fma_f32 v18, -v113, v101, v18
	v_fmac_f32_e32 v19, v116, v100
	v_fma_f32 v19, -v117, v101, v19
	v_fmac_f32_e32 v16, v106, v102
	v_fma_f32 v16, -v107, v103, v16
	v_fmac_f32_e32 v17, v110, v102
	v_fma_f32 v17, -v111, v103, v17
	v_fmac_f32_e32 v18, v114, v102
	v_fma_f32 v18, -v115, v103, v18
	v_fmac_f32_e32 v19, v118, v102
	v_fma_f32 v19, -v119, v103, v19
	ds_read_b64 v[100:101], v13 offset:3584
	ds_read_b64 v[102:103], v13 offset:3712
	ds_read_b128 v[104:107], v14 offset:224
	ds_read_b128 v[108:111], v14 offset:17120
	ds_read_b128 v[112:115], v14 offset:34016
	ds_read_b128 v[116:119], v14 offset:50912
	s_waitcnt lgkmcnt(6)
; __device__ __forceinline__ f32x2 cmul(f32x2 a, f32x2 b) { return (f32x2){a.x * b.x - a.y * b.y, a.x * b.y + a.y * b.x}; }
; __global__ void __launch_bounds__(NTHR, 2) hymba_fwd(Params P) {
;     ...
;             for (int idx = tid; idx < 4096; idx += NTHR) { const int d = idx >> 8, p = (idx >> 4) & 15, pp = idx & 15; float s = 0.f;
;                 for (int n = 0; n < 64; ++n) { const f32x2 t = cmul(CCl[p * 64 + n], PW[d * 64 + n]); const f32x2 b = BBl[n * 16 + pp]; s += t.x * b.x - t.y * b.y; }
	v_fmac_f32_e32 v16, v128, v124
	v_fma_f32 v16, -v129, v125, v16
	v_fmac_f32_e32 v17, v132, v124
	v_fma_f32 v17, -v133, v125, v17
	v_fmac_f32_e32 v18, v136, v124
	v_fma_f32 v18, -v137, v125, v18
	v_fmac_f32_e32 v19, v140, v124
	v_fma_f32 v19, -v141, v125, v19
	v_fmac_f32_e32 v16, v130, v126
	v_fma_f32 v16, -v131, v127, v16
	v_fmac_f32_e32 v17, v134, v126
	v_fma_f32 v17, -v135, v127, v17
	v_fmac_f32_e32 v18, v138, v126
	v_fma_f32 v18, -v139, v127, v18
	v_fmac_f32_e32 v19, v142, v126
	v_fma_f32 v19, -v143, v127, v19
	ds_read_b64 v[124:125], v13 offset:3840
	ds_read_b64 v[126:127], v13 offset:3968
	ds_read_b128 v[128:131], v14 offset:240
	ds_read_b128 v[132:135], v14 offset:17136
	ds_read_b128 v[136:139], v14 offset:34032
	ds_read_b128 v[140:143], v14 offset:50928
	s_waitcnt lgkmcnt(6)
	v_fmac_f32_e32 v16, v104, v100
	v_fma_f32 v16, -v105, v101, v16
	v_fmac_f32_e32 v17, v108, v100
	v_fma_f32 v17, -v109, v101, v17
	v_fmac_f32_e32 v18, v112, v100
	v_fma_f32 v18, -v113, v101, v18
	v_fmac_f32_e32 v19, v116, v100
	v_fma_f32 v19, -v117, v101, v19
	v_fmac_f32_e32 v16, v106, v102
	v_fma_f32 v16, -v107, v103, v16
	v_fmac_f32_e32 v17, v110, v102
	v_fma_f32 v17, -v111, v103, v17
	v_fmac_f32_e32 v18, v114, v102
	v_fma_f32 v18, -v115, v103, v18
	v_fmac_f32_e32 v19, v118, v102
	v_fma_f32 v19, -v119, v103, v19
	ds_read_b64 v[100:101], v13 offset:4096
	ds_read_b64 v[102:103], v13 offset:4224
	ds_read_b128 v[104:107], v14 offset:256
	ds_read_b128 v[108:111], v14 offset:17152
	ds_read_b128 v[112:115], v14 offset:34048
	ds_read_b128 v[116:119], v14 offset:50944
	s_waitcnt lgkmcnt(6)
	v_fmac_f32_e32 v16, v128, v124
	v_fma_f32 v16, -v129, v125, v16
	v_fmac_f32_e32 v17, v132, v124
	v_fma_f32 v17, -v133, v125, v17
	v_fmac_f32_e32 v18, v136, v124
	v_fma_f32 v18, -v137, v125, v18
	v_fmac_f32_e32 v19, v140, v124
	v_fma_f32 v19, -v141, v125, v19
	v_fmac_f32_e32 v16, v130, v126
	v_fma_f32 v16, -v131, v127, v16
	v_fmac_f32_e32 v17, v134, v126
	v_fma_f32 v17, -v135, v127, v17
	v_fmac_f32_e32 v18, v138, v126
	v_fma_f32 v18, -v139, v127, v18
	v_fmac_f32_e32 v19, v142, v126
	v_fma_f32 v19, -v143, v127, v19
	ds_read_b64 v[124:125], v13 offset:4352
	ds_read_b64 v[126:127], v13 offset:4480
	ds_read_b128 v[128:131], v14 offset:272
	ds_read_b128 v[132:135], v14 offset:17168
	ds_read_b128 v[136:139], v14 offset:34064
	ds_read_b128 v[140:143], v14 offset:50960
	s_waitcnt lgkmcnt(6)
	v_fmac_f32_e32 v16, v104, v100
	v_fma_f32 v16, -v105, v101, v16
	v_fmac_f32_e32 v17, v108, v100
	v_fma_f32 v17, -v109, v101, v17
	v_fmac_f32_e32 v18, v112, v100
	v_fma_f32 v18, -v113, v101, v18
	v_fmac_f32_e32 v19, v116, v100
	v_fma_f32 v19, -v117, v101, v19
	v_fmac_f32_e32 v16, v106, v102
	v_fma_f32 v16, -v107, v103, v16
	v_fmac_f32_e32 v17, v110, v102
	v_fma_f32 v17, -v111, v103, v17
	v_fmac_f32_e32 v18, v114, v102
	v_fma_f32 v18, -v115, v103, v18
	v_fmac_f32_e32 v19, v118, v102
	v_fma_f32 v19, -v119, v103, v19
	ds_read_b64 v[100:101], v13 offset:4608
	ds_read_b64 v[102:103], v13 offset:4736
	ds_read_b128 v[104:107], v14 offset:288
	ds_read_b128 v[108:111], v14 offset:17184
	ds_read_b128 v[112:115], v14 offset:34080
	ds_read_b128 v[116:119], v14 offset:50976
	s_waitcnt lgkmcnt(6)
	v_fmac_f32_e32 v16, v128, v124
	v_fma_f32 v16, -v129, v125, v16
	v_fmac_f32_e32 v17, v132, v124
	v_fma_f32 v17, -v133, v125, v17
	v_fmac_f32_e32 v18, v136, v124
	v_fma_f32 v18, -v137, v125, v18
	v_fmac_f32_e32 v19, v140, v124
	v_fma_f32 v19, -v141, v125, v19
	v_fmac_f32_e32 v16, v130, v126
	v_fma_f32 v16, -v131, v127, v16
	v_fmac_f32_e32 v17, v134, v126
	v_fma_f32 v17, -v135, v127, v17
	v_fmac_f32_e32 v18, v138, v126
	v_fma_f32 v18, -v139, v127, v18
	v_fmac_f32_e32 v19, v142, v126
	v_fma_f32 v19, -v143, v127, v19
	ds_read_b64 v[124:125], v13 offset:4864
	ds_read_b64 v[126:127], v13 offset:4992
	ds_read_b128 v[128:131], v14 offset:304
	ds_read_b128 v[132:135], v14 offset:17200
	ds_read_b128 v[136:139], v14 offset:34096
	ds_read_b128 v[140:143], v14 offset:50992
	s_waitcnt lgkmcnt(6)
	v_fmac_f32_e32 v16, v104, v100
	v_fma_f32 v16, -v105, v101, v16
	v_fmac_f32_e32 v17, v108, v100
	v_fma_f32 v17, -v109, v101, v17
	v_fmac_f32_e32 v18, v112, v100
	v_fma_f32 v18, -v113, v101, v18
	v_fmac_f32_e32 v19, v116, v100
	v_fma_f32 v19, -v117, v101, v19
	v_fmac_f32_e32 v16, v106, v102
	v_fma_f32 v16, -v107, v103, v16
	v_fmac_f32_e32 v17, v110, v102
	v_fma_f32 v17, -v111, v103, v17
	v_fmac_f32_e32 v18, v114, v102
	v_fma_f32 v18, -v115, v103, v18
	v_fmac_f32_e32 v19, v118, v102
	v_fma_f32 v19, -v119, v103, v19
	ds_read_b64 v[100:101], v13 offset:5120
	ds_read_b64 v[102:103], v13 offset:5248
	ds_read_b128 v[104:107], v14 offset:320
	ds_read_b128 v[108:111], v14 offset:17216
	ds_read_b128 v[112:115], v14 offset:34112
	ds_read_b128 v[116:119], v14 offset:51008
	s_waitcnt lgkmcnt(6)
	v_fmac_f32_e32 v16, v128, v124
	v_fma_f32 v16, -v129, v125, v16
	v_fmac_f32_e32 v17, v132, v124
	v_fma_f32 v17, -v133, v125, v17
	v_fmac_f32_e32 v18, v136, v124
	v_fma_f32 v18, -v137, v125, v18
	v_fmac_f32_e32 v19, v140, v124
	v_fma_f32 v19, -v141, v125, v19
	v_fmac_f32_e32 v16, v130, v126
	v_fma_f32 v16, -v131, v127, v16
	v_fmac_f32_e32 v17, v134, v126
	v_fma_f32 v17, -v135, v127, v17
	v_fmac_f32_e32 v18, v138, v126
	v_fma_f32 v18, -v139, v127, v18
	v_fmac_f32_e32 v19, v142, v126
	v_fma_f32 v19, -v143, v127, v19
	ds_read_b64 v[124:125], v13 offset:5376
	ds_read_b64 v[126:127], v13 offset:5504
	ds_read_b128 v[128:131], v14 offset:336
	ds_read_b128 v[132:135], v14 offset:17232
	ds_read_b128 v[136:139], v14 offset:34128
	ds_read_b128 v[140:143], v14 offset:51024
	s_waitcnt lgkmcnt(6)
; __device__ __forceinline__ f32x2 cmul(f32x2 a, f32x2 b) { return (f32x2){a.x * b.x - a.y * b.y, a.x * b.y + a.y * b.x}; }
; __global__ void __launch_bounds__(NTHR, 2) hymba_fwd(Params P) {
;     ...
;             for (int idx = tid; idx < 4096; idx += NTHR) { const int d = idx >> 8, p = (idx >> 4) & 15, pp = idx & 15; float s = 0.f;
;                 for (int n = 0; n < 64; ++n) { const f32x2 t = cmul(CCl[p * 64 + n], PW[d * 64 + n]); const f32x2 b = BBl[n * 16 + pp]; s += t.x * b.x - t.y * b.y; }
	v_fmac_f32_e32 v16, v104, v100
	v_fma_f32 v16, -v105, v101, v16
	v_fmac_f32_e32 v17, v108, v100
	v_fma_f32 v17, -v109, v101, v17
	v_fmac_f32_e32 v18, v112, v100
	v_fma_f32 v18, -v113, v101, v18
	v_fmac_f32_e32 v19, v116, v100
	v_fma_f32 v19, -v117, v101, v19
	v_fmac_f32_e32 v16, v106, v102
	v_fma_f32 v16, -v107, v103, v16
	v_fmac_f32_e32 v17, v110, v102
	v_fma_f32 v17, -v111, v103, v17
	v_fmac_f32_e32 v18, v114, v102
	v_fma_f32 v18, -v115, v103, v18
	v_fmac_f32_e32 v19, v118, v102
	v_fma_f32 v19, -v119, v103, v19
	ds_read_b64 v[100:101], v13 offset:5632
	ds_read_b64 v[102:103], v13 offset:5760
	ds_read_b128 v[104:107], v14 offset:352
	ds_read_b128 v[108:111], v14 offset:17248
	ds_read_b128 v[112:115], v14 offset:34144
	ds_read_b128 v[116:119], v14 offset:51040
	s_waitcnt lgkmcnt(6)
	v_fmac_f32_e32 v16, v128, v124
	v_fma_f32 v16, -v129, v125, v16
	v_fmac_f32_e32 v17, v132, v124
	v_fma_f32 v17, -v133, v125, v17
	v_fmac_f32_e32 v18, v136, v124
	v_fma_f32 v18, -v137, v125, v18
	v_fmac_f32_e32 v19, v140, v124
	v_fma_f32 v19, -v141, v125, v19
	v_fmac_f32_e32 v16, v130, v126
	v_fma_f32 v16, -v131, v127, v16
	v_fmac_f32_e32 v17, v134, v126
	v_fma_f32 v17, -v135, v127, v17
	v_fmac_f32_e32 v18, v138, v126
	v_fma_f32 v18, -v139, v127, v18
	v_fmac_f32_e32 v19, v142, v126
	v_fma_f32 v19, -v143, v127, v19
	ds_read_b64 v[124:125], v13 offset:5888
	ds_read_b64 v[126:127], v13 offset:6016
	ds_read_b128 v[128:131], v14 offset:368
	ds_read_b128 v[132:135], v14 offset:17264
	ds_read_b128 v[136:139], v14 offset:34160
	ds_read_b128 v[140:143], v14 offset:51056
	s_waitcnt lgkmcnt(6)
	v_fmac_f32_e32 v16, v104, v100
	v_fma_f32 v16, -v105, v101, v16
	v_fmac_f32_e32 v17, v108, v100
	v_fma_f32 v17, -v109, v101, v17
	v_fmac_f32_e32 v18, v112, v100
	v_fma_f32 v18, -v113, v101, v18
	v_fmac_f32_e32 v19, v116, v100
	v_fma_f32 v19, -v117, v101, v19
	v_fmac_f32_e32 v16, v106, v102
	v_fma_f32 v16, -v107, v103, v16
	v_fmac_f32_e32 v17, v110, v102
	v_fma_f32 v17, -v111, v103, v17
	v_fmac_f32_e32 v18, v114, v102
	v_fma_f32 v18, -v115, v103, v18
	v_fmac_f32_e32 v19, v118, v102
	v_fma_f32 v19, -v119, v103, v19
	ds_read_b64 v[100:101], v13 offset:6144
	ds_read_b64 v[102:103], v13 offset:6272
	ds_read_b128 v[104:107], v14 offset:384
	ds_read_b128 v[108:111], v14 offset:17280
	ds_read_b128 v[112:115], v14 offset:34176
	ds_read_b128 v[116:119], v14 offset:51072
	s_waitcnt lgkmcnt(6)
	v_fmac_f32_e32 v16, v128, v124
	v_fma_f32 v16, -v129, v125, v16
	v_fmac_f32_e32 v17, v132, v124
	v_fma_f32 v17, -v133, v125, v17
	v_fmac_f32_e32 v18, v136, v124
	v_fma_f32 v18, -v137, v125, v18
	v_fmac_f32_e32 v19, v140, v124
	v_fma_f32 v19, -v141, v125, v19
	v_fmac_f32_e32 v16, v130, v126
	v_fma_f32 v16, -v131, v127, v16
	v_fmac_f32_e32 v17, v134, v126
	v_fma_f32 v17, -v135, v127, v17
	v_fmac_f32_e32 v18, v138, v126
	v_fma_f32 v18, -v139, v127, v18
	v_fmac_f32_e32 v19, v142, v126
	v_fma_f32 v19, -v143, v127, v19
	ds_read_b64 v[124:125], v13 offset:6400
	ds_read_b64 v[126:127], v13 offset:6528
	ds_read_b128 v[128:131], v14 offset:400
	ds_read_b128 v[132:135], v14 offset:17296
	ds_read_b128 v[136:139], v14 offset:34192
	ds_read_b128 v[140:143], v14 offset:51088
	s_waitcnt lgkmcnt(6)
	v_fmac_f32_e32 v16, v104, v100
	v_fma_f32 v16, -v105, v101, v16
	v_fmac_f32_e32 v17, v108, v100
	v_fma_f32 v17, -v109, v101, v17
	v_fmac_f32_e32 v18, v112, v100
	v_fma_f32 v18, -v113, v101, v18
	v_fmac_f32_e32 v19, v116, v100
	v_fma_f32 v19, -v117, v101, v19
	v_fmac_f32_e32 v16, v106, v102
	v_fma_f32 v16, -v107, v103, v16
	v_fmac_f32_e32 v17, v110, v102
	v_fma_f32 v17, -v111, v103, v17
	v_fmac_f32_e32 v18, v114, v102
	v_fma_f32 v18, -v115, v103, v18
	v_fmac_f32_e32 v19, v118, v102
	v_fma_f32 v19, -v119, v103, v19
	ds_read_b64 v[100:101], v13 offset:6656
	ds_read_b64 v[102:103], v13 offset:6784
	ds_read_b128 v[104:107], v14 offset:416
	ds_read_b128 v[108:111], v14 offset:17312
	ds_read_b128 v[112:115], v14 offset:34208
	ds_read_b128 v[116:119], v14 offset:51104
	s_waitcnt lgkmcnt(6)
	v_fmac_f32_e32 v16, v128, v124
	v_fma_f32 v16, -v129, v125, v16
	v_fmac_f32_e32 v17, v132, v124
	v_fma_f32 v17, -v133, v125, v17
	v_fmac_f32_e32 v18, v136, v124
	v_fma_f32 v18, -v137, v125, v18
	v_fmac_f32_e32 v19, v140, v124
	v_fma_f32 v19, -v141, v125, v19
	v_fmac_f32_e32 v16, v130, v126
	v_fma_f32 v16, -v131, v127, v16
	v_fmac_f32_e32 v17, v134, v126
	v_fma_f32 v17, -v135, v127, v17
	v_fmac_f32_e32 v18, v138, v126
	v_fma_f32 v18, -v139, v127, v18
	v_fmac_f32_e32 v19, v142, v126
	v_fma_f32 v19, -v143, v127, v19
	ds_read_b64 v[124:125], v13 offset:6912
	ds_read_b64 v[126:127], v13 offset:7040
	ds_read_b128 v[128:131], v14 offset:432
	ds_read_b128 v[132:135], v14 offset:17328
	ds_read_b128 v[136:139], v14 offset:34224
	ds_read_b128 v[140:143], v14 offset:51120
	s_waitcnt lgkmcnt(6)
; __device__ __forceinline__ f32x2 cmul(f32x2 a, f32x2 b) { return (f32x2){a.x * b.x - a.y * b.y, a.x * b.y + a.y * b.x}; }
; __global__ void __launch_bounds__(NTHR, 2) hymba_fwd(Params P) {
;     ...
;             for (int idx = tid; idx < 4096; idx += NTHR) { const int d = idx >> 8, p = (idx >> 4) & 15, pp = idx & 15; float s = 0.f;
;                 for (int n = 0; n < 64; ++n) { const f32x2 t = cmul(CCl[p * 64 + n], PW[d * 64 + n]); const f32x2 b = BBl[n * 16 + pp]; s += t.x * b.x - t.y * b.y; }
;                 if (d == 0 && p == pp) s += P.d_skip[g * 16 + p];
;                 KT[idx] = s; }
	v_fmac_f32_e32 v16, v104, v100
	v_fma_f32 v16, -v105, v101, v16
	v_fmac_f32_e32 v17, v108, v100
	v_fma_f32 v17, -v109, v101, v17
	v_fmac_f32_e32 v18, v112, v100
	v_fma_f32 v18, -v113, v101, v18
	v_fmac_f32_e32 v19, v116, v100
	v_fma_f32 v19, -v117, v101, v19
	v_fmac_f32_e32 v16, v106, v102
	v_fma_f32 v16, -v107, v103, v16
	v_fmac_f32_e32 v17, v110, v102
	v_fma_f32 v17, -v111, v103, v17
	v_fmac_f32_e32 v18, v114, v102
	v_fma_f32 v18, -v115, v103, v18
	v_fmac_f32_e32 v19, v118, v102
	v_fma_f32 v19, -v119, v103, v19
	ds_read_b64 v[100:101], v13 offset:7168
	ds_read_b64 v[102:103], v13 offset:7296
	ds_read_b128 v[104:107], v14 offset:448
	ds_read_b128 v[108:111], v14 offset:17344
	ds_read_b128 v[112:115], v14 offset:34240
	ds_read_b128 v[116:119], v14 offset:51136
	s_waitcnt lgkmcnt(6)
	v_fmac_f32_e32 v16, v128, v124
	v_fma_f32 v16, -v129, v125, v16
	v_fmac_f32_e32 v17, v132, v124
	v_fma_f32 v17, -v133, v125, v17
	v_fmac_f32_e32 v18, v136, v124
	v_fma_f32 v18, -v137, v125, v18
	v_fmac_f32_e32 v19, v140, v124
	v_fma_f32 v19, -v141, v125, v19
	v_fmac_f32_e32 v16, v130, v126
	v_fma_f32 v16, -v131, v127, v16
	v_fmac_f32_e32 v17, v134, v126
	v_fma_f32 v17, -v135, v127, v17
	v_fmac_f32_e32 v18, v138, v126
	v_fma_f32 v18, -v139, v127, v18
	v_fmac_f32_e32 v19, v142, v126
	v_fma_f32 v19, -v143, v127, v19
	ds_read_b64 v[124:125], v13 offset:7424
	ds_read_b64 v[126:127], v13 offset:7552
	ds_read_b128 v[128:131], v14 offset:464
	ds_read_b128 v[132:135], v14 offset:17360
	ds_read_b128 v[136:139], v14 offset:34256
	ds_read_b128 v[140:143], v14 offset:51152
	s_waitcnt lgkmcnt(6)
	v_fmac_f32_e32 v16, v104, v100
	v_fma_f32 v16, -v105, v101, v16
	v_fmac_f32_e32 v17, v108, v100
	v_fma_f32 v17, -v109, v101, v17
	v_fmac_f32_e32 v18, v112, v100
	v_fma_f32 v18, -v113, v101, v18
	v_fmac_f32_e32 v19, v116, v100
	v_fma_f32 v19, -v117, v101, v19
	v_fmac_f32_e32 v16, v106, v102
	v_fma_f32 v16, -v107, v103, v16
	v_fmac_f32_e32 v17, v110, v102
	v_fma_f32 v17, -v111, v103, v17
	v_fmac_f32_e32 v18, v114, v102
	v_fma_f32 v18, -v115, v103, v18
	v_fmac_f32_e32 v19, v118, v102
	v_fma_f32 v19, -v119, v103, v19
	ds_read_b64 v[100:101], v13 offset:7680
	ds_read_b64 v[102:103], v13 offset:7808
	ds_read_b128 v[104:107], v14 offset:480
	ds_read_b128 v[108:111], v14 offset:17376
	ds_read_b128 v[112:115], v14 offset:34272
	ds_read_b128 v[116:119], v14 offset:51168
	s_waitcnt lgkmcnt(6)
	v_fmac_f32_e32 v16, v128, v124
	v_fma_f32 v16, -v129, v125, v16
	v_fmac_f32_e32 v17, v132, v124
	v_fma_f32 v17, -v133, v125, v17
	v_fmac_f32_e32 v18, v136, v124
	v_fma_f32 v18, -v137, v125, v18
	v_fmac_f32_e32 v19, v140, v124
	v_fma_f32 v19, -v141, v125, v19
	v_fmac_f32_e32 v16, v130, v126
	v_fma_f32 v16, -v131, v127, v16
	v_fmac_f32_e32 v17, v134, v126
	v_fma_f32 v17, -v135, v127, v17
	v_fmac_f32_e32 v18, v138, v126
	v_fma_f32 v18, -v139, v127, v18
	v_fmac_f32_e32 v19, v142, v126
	v_fma_f32 v19, -v143, v127, v19
	ds_read_b64 v[124:125], v13 offset:7936
	ds_read_b64 v[126:127], v13 offset:8064
	ds_read_b128 v[128:131], v14 offset:496
	ds_read_b128 v[132:135], v14 offset:17392
	ds_read_b128 v[136:139], v14 offset:34288
	ds_read_b128 v[140:143], v14 offset:51184
	s_waitcnt lgkmcnt(6)
	v_fmac_f32_e32 v16, v104, v100
	v_fma_f32 v16, -v105, v101, v16
	v_fmac_f32_e32 v17, v108, v100
	v_fma_f32 v17, -v109, v101, v17
	v_fmac_f32_e32 v18, v112, v100
	v_fma_f32 v18, -v113, v101, v18
	v_fmac_f32_e32 v19, v116, v100
	v_fma_f32 v19, -v117, v101, v19
	v_fmac_f32_e32 v16, v106, v102
	v_fma_f32 v16, -v107, v103, v16
	v_fmac_f32_e32 v17, v110, v102
	v_fma_f32 v17, -v111, v103, v17
	v_fmac_f32_e32 v18, v114, v102
	v_fma_f32 v18, -v115, v103, v18
	v_fmac_f32_e32 v19, v118, v102
	v_fma_f32 v19, -v119, v103, v19
	s_waitcnt lgkmcnt(0)
	v_fmac_f32_e32 v16, v128, v124
	v_fma_f32 v16, -v129, v125, v16
	v_fmac_f32_e32 v17, v132, v124
	v_fma_f32 v17, -v133, v125, v17
	v_fmac_f32_e32 v18, v136, v124
	v_fma_f32 v18, -v137, v125, v18
	v_fmac_f32_e32 v19, v140, v124
	v_fma_f32 v19, -v141, v125, v19
	v_fmac_f32_e32 v16, v130, v126
	v_fma_f32 v16, -v131, v127, v16
	v_fmac_f32_e32 v17, v134, v126
	v_fma_f32 v17, -v135, v127, v17
	v_fmac_f32_e32 v18, v138, v126
	v_fma_f32 v18, -v139, v127, v18
	v_fmac_f32_e32 v19, v142, v126
	v_fma_f32 v19, -v143, v127, v19
	ds_write_b32 v15, v16 offset:8192
	ds_write_b32 v15, v17 offset:10240
	ds_write_b32 v15, v18 offset:12288
	ds_write_b32 v15, v19 offset:14336

; __device__ __forceinline__ float siluf_(float x) { return x * __builtin_amdgcn_rcpf(1.f + __expf(-x)); }
; __global__ void __launch_bounds__(NTHR, 2) hymba_fwd(Params P) {
;     ...
;             for (int idx = lane; idx < 2048; idx += 64) { const int kk = idx >> 4, b = idx & 15, k = wave * 128 + kk;
;                 const float c = (b < 8) ? P.c_prompt[b * DM + k] : P.c_sample[(b - 8) * DM + k]; sil[idx] = siluf_(c); }
;             asm volatile("s_waitcnt lgkmcnt(0)" ::: "memory");
;             const int col = it * 64 + lane;
;             float acc[16];
; #pragma unroll
;             for (int b = 0; b < 16; ++b) acc[b] = 0.f;
; #pragma unroll 32
;             for (int kk = 0; kk < 128; ++kk) { const float wv = P.w_ada[(size_t)(wave * 128 + kk) * 3072 + col];
.LBB0_50:
	v_ashrrev_i32_e32 v5, 31, v4
	v_lshl_add_u64 v[8:9], v[4:5], 2, v[2:3]
	global_load_dword v82, v[8:9], off
	global_load_dword v83, v[8:9], off offset:16
	global_load_dword v84, v[8:9], off offset:32
	global_load_dword v85, v[8:9], off offset:48
	global_load_dword v86, v[8:9], off offset:64
	global_load_dword v87, v[8:9], off offset:80
	global_load_dword v88, v[8:9], off offset:96
	global_load_dword v89, v[8:9], off offset:112
	global_load_dword v90, v[8:9], off offset:128
	global_load_dword v91, v[8:9], off offset:144
	global_load_dword v92, v[8:9], off offset:160
	global_load_dword v93, v[8:9], off offset:176
	global_load_dword v94, v[8:9], off offset:192
	global_load_dword v95, v[8:9], off offset:208
	global_load_dword v96, v[8:9], off offset:224
	global_load_dword v97, v[8:9], off offset:240
	global_load_dword v98, v[8:9], off offset:256
	global_load_dword v99, v[8:9], off offset:272
	global_load_dword v100, v[8:9], off offset:288
	global_load_dword v101, v[8:9], off offset:304
	global_load_dword v102, v[8:9], off offset:320
	global_load_dword v103, v[8:9], off offset:336
	global_load_dword v104, v[8:9], off offset:352
	global_load_dword v105, v[8:9], off offset:368
	global_load_dword v106, v[8:9], off offset:384
	global_load_dword v107, v[8:9], off offset:400
	global_load_dword v108, v[8:9], off offset:416
	global_load_dword v109, v[8:9], off offset:432
	global_load_dword v110, v[8:9], off offset:448
	global_load_dword v111, v[8:9], off offset:464
	global_load_dword v112, v[8:9], off offset:480
	global_load_dword v113, v[8:9], off offset:496
	s_mul_hi_i32 s1, s6, 0x3000
	s_mulk_i32 s6, 0x3000
	v_add_u32_e32 v242, s19, v45
	s_add_u32 s0, s54, s6
	s_addc_u32 s1, s55, s1
	v_lshlrev_b32_e32 v242, 2, v242
	global_load_dword v114, v242, s[0:1]
	s_add_u32 s0, s0, 0x3000
	s_addc_u32 s1, s1, 0
	global_load_dword v115, v242, s[0:1]
	s_add_u32 s0, s0, 0x3000
	s_addc_u32 s1, s1, 0
	global_load_dword v116, v242, s[0:1]
	s_add_u32 s0, s0, 0x3000
	s_addc_u32 s1, s1, 0
	global_load_dword v117, v242, s[0:1]
	s_add_u32 s0, s0, 0x3000
	s_addc_u32 s1, s1, 0
	global_load_dword v118, v242, s[0:1]
	s_add_u32 s0, s0, 0x3000
	s_addc_u32 s1, s1, 0
	global_load_dword v119, v242, s[0:1]
	s_add_u32 s0, s0, 0x3000
	s_addc_u32 s1, s1, 0
	global_load_dword v120, v242, s[0:1]
	s_add_u32 s0, s0, 0x3000
	s_addc_u32 s1, s1, 0
	global_load_dword v121, v242, s[0:1]
	s_add_u32 s0, s0, 0x3000
	s_addc_u32 s1, s1, 0
	global_load_dword v122, v242, s[0:1]
	s_add_u32 s0, s0, 0x3000
	s_addc_u32 s1, s1, 0
	global_load_dword v123, v242, s[0:1]
	s_add_u32 s0, s0, 0x3000
	s_addc_u32 s1, s1, 0
	global_load_dword v124, v242, s[0:1]
	s_add_u32 s0, s0, 0x3000
	s_addc_u32 s1, s1, 0
	global_load_dword v125, v242, s[0:1]
	s_add_u32 s0, s0, 0x3000
	s_addc_u32 s1, s1, 0
	global_load_dword v126, v242, s[0:1]
	s_add_u32 s0, s0, 0x3000
	s_addc_u32 s1, s1, 0
	global_load_dword v127, v242, s[0:1]
	s_add_u32 s0, s0, 0x3000
	s_addc_u32 s1, s1, 0
	global_load_dword v128, v242, s[0:1]
	s_add_u32 s0, s0, 0x3000
	s_addc_u32 s1, s1, 0
	global_load_dword v129, v242, s[0:1]
	s_add_u32 s0, s0, 0x3000
	s_addc_u32 s1, s1, 0
	global_load_dword v130, v242, s[0:1]
	s_add_u32 s0, s0, 0x3000
	s_addc_u32 s1, s1, 0
	global_load_dword v131, v242, s[0:1]
	s_add_u32 s0, s0, 0x3000
	s_addc_u32 s1, s1, 0
	global_load_dword v132, v242, s[0:1]
	s_add_u32 s0, s0, 0x3000
	s_addc_u32 s1, s1, 0
	global_load_dword v133, v242, s[0:1]
	s_add_u32 s0, s0, 0x3000
	s_addc_u32 s1, s1, 0
	global_load_dword v134, v242, s[0:1]
	s_add_u32 s0, s0, 0x3000
	s_addc_u32 s1, s1, 0
	global_load_dword v135, v242, s[0:1]
	s_add_u32 s0, s0, 0x3000
	s_addc_u32 s1, s1, 0
	global_load_dword v136, v242, s[0:1]
	s_add_u32 s0, s0, 0x3000
	s_addc_u32 s1, s1, 0
	global_load_dword v137, v242, s[0:1]
	s_add_u32 s0, s0, 0x3000
	s_addc_u32 s1, s1, 0
	global_load_dword v138, v242, s[0:1]
	s_add_u32 s0, s0, 0x3000
	s_addc_u32 s1, s1, 0
	global_load_dword v139, v242, s[0:1]
	s_add_u32 s0, s0, 0x3000
	s_addc_u32 s1, s1, 0
	global_load_dword v140, v242, s[0:1]
	s_add_u32 s0, s0, 0x3000
	s_addc_u32 s1, s1, 0
	global_load_dword v141, v242, s[0:1]
	s_add_u32 s0, s0, 0x3000
	s_addc_u32 s1, s1, 0
	global_load_dword v142, v242, s[0:1]
	s_add_u32 s0, s0, 0x3000
	s_addc_u32 s1, s1, 0
	global_load_dword v143, v242, s[0:1]
	s_add_u32 s0, s0, 0x3000
	s_addc_u32 s1, s1, 0
	global_load_dword v144, v242, s[0:1]
	s_add_u32 s0, s0, 0x3000
	s_addc_u32 s1, s1, 0
	global_load_dword v145, v242, s[0:1]
	s_add_u32 s0, s0, 0x3000
	s_addc_u32 s1, s1, 0
	s_waitcnt vmcnt(60)
	v_mul_f32_e32 v178, 0xbfb8aa3b, v82
	v_mul_f32_e32 v243, 0xbfb8aa3b, v83
	v_mul_f32_e32 v244, 0xbfb8aa3b, v84
	v_mul_f32_e32 v245, 0xbfb8aa3b, v85
	v_exp_f32_e32 v178, v178
	v_exp_f32_e32 v243, v243
	v_exp_f32_e32 v244, v244
	v_exp_f32_e32 v245, v245
	v_add_f32_e32 v178, 1.0, v178
	v_add_f32_e32 v243, 1.0, v243
	v_add_f32_e32 v244, 1.0, v244
	v_add_f32_e32 v245, 1.0, v245
	v_rcp_f32_e32 v178, v178
	v_rcp_f32_e32 v243, v243
	v_rcp_f32_e32 v244, v244
	v_rcp_f32_e32 v245, v245
	v_mul_f32_e32 v82, v82, v178
	v_mul_f32_e32 v83, v83, v243
	v_mul_f32_e32 v84, v84, v244
	v_mul_f32_e32 v85, v85, v245
	ds_write_b32 v7, v82
	ds_write_b32 v7, v83 offset:256
	ds_write_b32 v7, v84 offset:512
	ds_write_b32 v7, v85 offset:768
	s_waitcnt vmcnt(56)
	v_mul_f32_e32 v178, 0xbfb8aa3b, v86
	v_mul_f32_e32 v243, 0xbfb8aa3b, v87
	v_mul_f32_e32 v244, 0xbfb8aa3b, v88
	v_mul_f32_e32 v245, 0xbfb8aa3b, v89
	v_exp_f32_e32 v178, v178
	v_exp_f32_e32 v243, v243
	v_exp_f32_e32 v244, v244
	v_exp_f32_e32 v245, v245
	v_add_f32_e32 v178, 1.0, v178
	v_add_f32_e32 v243, 1.0, v243
	v_add_f32_e32 v244, 1.0, v244
	v_add_f32_e32 v245, 1.0, v245
	v_rcp_f32_e32 v178, v178
	v_rcp_f32_e32 v243, v243
	v_rcp_f32_e32 v244, v244
	v_rcp_f32_e32 v245, v245
	v_mul_f32_e32 v86, v86, v178
	v_mul_f32_e32 v87, v87, v243
	v_mul_f32_e32 v88, v88, v244
	v_mul_f32_e32 v89, v89, v245
	ds_write_b32 v7, v86 offset:1024
	ds_write_b32 v7, v87 offset:1280
	ds_write_b32 v7, v88 offset:1536
	ds_write_b32 v7, v89 offset:1792
	s_waitcnt vmcnt(52)
; __device__ __forceinline__ float siluf_(float x) { return x * __builtin_amdgcn_rcpf(1.f + __expf(-x)); }
; __global__ void __launch_bounds__(NTHR, 2) hymba_fwd(Params P) {
;     ...
;             for (int idx = lane; idx < 2048; idx += 64) { const int kk = idx >> 4, b = idx & 15, k = wave * 128 + kk;
;                 const float c = (b < 8) ? P.c_prompt[b * DM + k] : P.c_sample[(b - 8) * DM + k]; sil[idx] = siluf_(c); }
;     ...
;             for (int kk = 0; kk < 128; ++kk) { const float wv = P.w_ada[(size_t)(wave * 128 + kk) * 3072 + col];
	v_mul_f32_e32 v178, 0xbfb8aa3b, v90
	v_mul_f32_e32 v243, 0xbfb8aa3b, v91
	v_mul_f32_e32 v244, 0xbfb8aa3b, v92
	v_mul_f32_e32 v245, 0xbfb8aa3b, v93
	v_exp_f32_e32 v178, v178
	v_exp_f32_e32 v243, v243
	v_exp_f32_e32 v244, v244
	v_exp_f32_e32 v245, v245
	v_add_f32_e32 v178, 1.0, v178
	v_add_f32_e32 v243, 1.0, v243
	v_add_f32_e32 v244, 1.0, v244
	v_add_f32_e32 v245, 1.0, v245
	v_rcp_f32_e32 v178, v178
	v_rcp_f32_e32 v243, v243
	v_rcp_f32_e32 v244, v244
	v_rcp_f32_e32 v245, v245
	v_mul_f32_e32 v90, v90, v178
	v_mul_f32_e32 v91, v91, v243
	v_mul_f32_e32 v92, v92, v244
	v_mul_f32_e32 v93, v93, v245
	ds_write_b32 v7, v90 offset:2048
	ds_write_b32 v7, v91 offset:2304
	ds_write_b32 v7, v92 offset:2560
	ds_write_b32 v7, v93 offset:2816
	s_waitcnt vmcnt(48)
	v_mul_f32_e32 v178, 0xbfb8aa3b, v94
	v_mul_f32_e32 v243, 0xbfb8aa3b, v95
	v_mul_f32_e32 v244, 0xbfb8aa3b, v96
	v_mul_f32_e32 v245, 0xbfb8aa3b, v97
	v_exp_f32_e32 v178, v178
	v_exp_f32_e32 v243, v243
	v_exp_f32_e32 v244, v244
	v_exp_f32_e32 v245, v245
	v_add_f32_e32 v178, 1.0, v178
	v_add_f32_e32 v243, 1.0, v243
	v_add_f32_e32 v244, 1.0, v244
	v_add_f32_e32 v245, 1.0, v245
	v_rcp_f32_e32 v178, v178
	v_rcp_f32_e32 v243, v243
	v_rcp_f32_e32 v244, v244
	v_rcp_f32_e32 v245, v245
	v_mul_f32_e32 v94, v94, v178
	v_mul_f32_e32 v95, v95, v243
	v_mul_f32_e32 v96, v96, v244
	v_mul_f32_e32 v97, v97, v245
	ds_write_b32 v7, v94 offset:3072
	ds_write_b32 v7, v95 offset:3328
	ds_write_b32 v7, v96 offset:3584
	ds_write_b32 v7, v97 offset:3840
	s_waitcnt vmcnt(44)
	v_mul_f32_e32 v178, 0xbfb8aa3b, v98
	v_mul_f32_e32 v243, 0xbfb8aa3b, v99
	v_mul_f32_e32 v244, 0xbfb8aa3b, v100
	v_mul_f32_e32 v245, 0xbfb8aa3b, v101
	v_exp_f32_e32 v178, v178
	v_exp_f32_e32 v243, v243
	v_exp_f32_e32 v244, v244
	v_exp_f32_e32 v245, v245
	v_add_f32_e32 v178, 1.0, v178
	v_add_f32_e32 v243, 1.0, v243
	v_add_f32_e32 v244, 1.0, v244
	v_add_f32_e32 v245, 1.0, v245
	v_rcp_f32_e32 v178, v178
	v_rcp_f32_e32 v243, v243
	v_rcp_f32_e32 v244, v244
	v_rcp_f32_e32 v245, v245
	v_mul_f32_e32 v98, v98, v178
	v_mul_f32_e32 v99, v99, v243
	v_mul_f32_e32 v100, v100, v244
	v_mul_f32_e32 v101, v101, v245
	ds_write_b32 v7, v98 offset:4096
	ds_write_b32 v7, v99 offset:4352
	ds_write_b32 v7, v100 offset:4608
	ds_write_b32 v7, v101 offset:4864
	s_waitcnt vmcnt(40)
	v_mul_f32_e32 v178, 0xbfb8aa3b, v102
	v_mul_f32_e32 v243, 0xbfb8aa3b, v103
	v_mul_f32_e32 v244, 0xbfb8aa3b, v104
	v_mul_f32_e32 v245, 0xbfb8aa3b, v105
	v_exp_f32_e32 v178, v178
	v_exp_f32_e32 v243, v243
	v_exp_f32_e32 v244, v244
	v_exp_f32_e32 v245, v245
	v_add_f32_e32 v178, 1.0, v178
	v_add_f32_e32 v243, 1.0, v243
	v_add_f32_e32 v244, 1.0, v244
	v_add_f32_e32 v245, 1.0, v245
	v_rcp_f32_e32 v178, v178
	v_rcp_f32_e32 v243, v243
	v_rcp_f32_e32 v244, v244
	v_rcp_f32_e32 v245, v245
	v_mul_f32_e32 v102, v102, v178
	v_mul_f32_e32 v103, v103, v243
	v_mul_f32_e32 v104, v104, v244
	v_mul_f32_e32 v105, v105, v245
	ds_write_b32 v7, v102 offset:5120
	ds_write_b32 v7, v103 offset:5376
	ds_write_b32 v7, v104 offset:5632
	ds_write_b32 v7, v105 offset:5888
	s_waitcnt vmcnt(36)
	v_mul_f32_e32 v178, 0xbfb8aa3b, v106
	v_mul_f32_e32 v243, 0xbfb8aa3b, v107
	v_mul_f32_e32 v244, 0xbfb8aa3b, v108
	v_mul_f32_e32 v245, 0xbfb8aa3b, v109
	v_exp_f32_e32 v178, v178
	v_exp_f32_e32 v243, v243
	v_exp_f32_e32 v244, v244
	v_exp_f32_e32 v245, v245
	v_add_f32_e32 v178, 1.0, v178
	v_add_f32_e32 v243, 1.0, v243
	v_add_f32_e32 v244, 1.0, v244
	v_add_f32_e32 v245, 1.0, v245
	v_rcp_f32_e32 v178, v178
	v_rcp_f32_e32 v243, v243
	v_rcp_f32_e32 v244, v244
	v_rcp_f32_e32 v245, v245
	v_mul_f32_e32 v106, v106, v178
	v_mul_f32_e32 v107, v107, v243
	v_mul_f32_e32 v108, v108, v244
	v_mul_f32_e32 v109, v109, v245
	ds_write_b32 v7, v106 offset:6144
	ds_write_b32 v7, v107 offset:6400
	ds_write_b32 v7, v108 offset:6656
	ds_write_b32 v7, v109 offset:6912
	s_waitcnt vmcnt(32)
	v_mul_f32_e32 v178, 0xbfb8aa3b, v110
	v_mul_f32_e32 v243, 0xbfb8aa3b, v111
	v_mul_f32_e32 v244, 0xbfb8aa3b, v112
	v_mul_f32_e32 v245, 0xbfb8aa3b, v113
	v_exp_f32_e32 v178, v178
	v_exp_f32_e32 v243, v243
	v_exp_f32_e32 v244, v244
	v_exp_f32_e32 v245, v245
	v_add_f32_e32 v178, 1.0, v178
	v_add_f32_e32 v243, 1.0, v243
	v_add_f32_e32 v244, 1.0, v244
	v_add_f32_e32 v245, 1.0, v245
	v_rcp_f32_e32 v178, v178
	v_rcp_f32_e32 v243, v243
	v_rcp_f32_e32 v244, v244
	v_rcp_f32_e32 v245, v245
	v_mul_f32_e32 v110, v110, v178
	v_mul_f32_e32 v111, v111, v243
	v_mul_f32_e32 v112, v112, v244
	v_mul_f32_e32 v113, v113, v245
	ds_write_b32 v7, v110 offset:7168
	ds_write_b32 v7, v111 offset:7424
	ds_write_b32 v7, v112 offset:7680
	ds_write_b32 v7, v113 offset:7936
	v_mov_b32_e32 v179, s5
	global_load_dword v146, v242, s[0:1]
	s_add_u32 s0, s0, 0x3000
	s_addc_u32 s1, s1, 0
	global_load_dword v147, v242, s[0:1]
	s_add_u32 s0, s0, 0x3000
	s_addc_u32 s1, s1, 0
	global_load_dword v148, v242, s[0:1]
	s_add_u32 s0, s0, 0x3000
	s_addc_u32 s1, s1, 0
	global_load_dword v149, v242, s[0:1]
	s_add_u32 s0, s0, 0x3000
	s_addc_u32 s1, s1, 0
	global_load_dword v150, v242, s[0:1]
	s_add_u32 s0, s0, 0x3000
	s_addc_u32 s1, s1, 0
	global_load_dword v151, v242, s[0:1]
	s_add_u32 s0, s0, 0x3000
	s_addc_u32 s1, s1, 0
	global_load_dword v152, v242, s[0:1]
	s_add_u32 s0, s0, 0x3000
	s_addc_u32 s1, s1, 0
	global_load_dword v153, v242, s[0:1]
	s_add_u32 s0, s0, 0x3000
	s_addc_u32 s1, s1, 0
	global_load_dword v154, v242, s[0:1]
	s_add_u32 s0, s0, 0x3000
	s_addc_u32 s1, s1, 0
	global_load_dword v155, v242, s[0:1]
	s_add_u32 s0, s0, 0x3000
	s_addc_u32 s1, s1, 0
	global_load_dword v156, v242, s[0:1]
	s_add_u32 s0, s0, 0x3000
	s_addc_u32 s1, s1, 0
	global_load_dword v157, v242, s[0:1]
	s_add_u32 s0, s0, 0x3000
	s_addc_u32 s1, s1, 0
; #define LAS __attribute__((address_space(3)))
; __global__ void __launch_bounds__(NTHR, 2) hymba_fwd(Params P) {
;     ...
;             for (int b = 0; b < 16; ++b) acc[b] = 0.f;
; #pragma unroll 32
;             for (int kk = 0; kk < 128; ++kk) { const float wv = P.w_ada[(size_t)(wave * 128 + kk) * 3072 + col];
; #pragma unroll
;                 for (int q = 0; q < 4; ++q) { const f32x4 s = *(const LAS f32x4*)(sil + kk * 16 + 4 * q); acc[4 * q] += s[0] * wv; acc[4 * q + 1] += s[1] * wv; acc[4 * q + 2] += s[2] * wv; acc[4 * q + 3] += s[3] * wv; } }
	global_load_dword v158, v242, s[0:1]
	s_add_u32 s0, s0, 0x3000
	s_addc_u32 s1, s1, 0
	global_load_dword v159, v242, s[0:1]
	s_add_u32 s0, s0, 0x3000
	s_addc_u32 s1, s1, 0
	global_load_dword v160, v242, s[0:1]
	s_add_u32 s0, s0, 0x3000
	s_addc_u32 s1, s1, 0
	global_load_dword v161, v242, s[0:1]
	s_add_u32 s0, s0, 0x3000
	s_addc_u32 s1, s1, 0
	global_load_dword v162, v242, s[0:1]
	s_add_u32 s0, s0, 0x3000
	s_addc_u32 s1, s1, 0
	global_load_dword v163, v242, s[0:1]
	s_add_u32 s0, s0, 0x3000
	s_addc_u32 s1, s1, 0
	global_load_dword v164, v242, s[0:1]
	s_add_u32 s0, s0, 0x3000
	s_addc_u32 s1, s1, 0
	global_load_dword v165, v242, s[0:1]
	s_add_u32 s0, s0, 0x3000
	s_addc_u32 s1, s1, 0
	global_load_dword v166, v242, s[0:1]
	s_add_u32 s0, s0, 0x3000
	s_addc_u32 s1, s1, 0
	global_load_dword v167, v242, s[0:1]
	s_add_u32 s0, s0, 0x3000
	s_addc_u32 s1, s1, 0
	global_load_dword v168, v242, s[0:1]
	s_add_u32 s0, s0, 0x3000
	s_addc_u32 s1, s1, 0
	global_load_dword v169, v242, s[0:1]
	s_add_u32 s0, s0, 0x3000
	s_addc_u32 s1, s1, 0
	global_load_dword v170, v242, s[0:1]
	s_add_u32 s0, s0, 0x3000
	s_addc_u32 s1, s1, 0
	global_load_dword v171, v242, s[0:1]
	s_add_u32 s0, s0, 0x3000
	s_addc_u32 s1, s1, 0
	global_load_dword v172, v242, s[0:1]
	s_add_u32 s0, s0, 0x3000
	s_addc_u32 s1, s1, 0
	global_load_dword v173, v242, s[0:1]
	s_add_u32 s0, s0, 0x3000
	s_addc_u32 s1, s1, 0
	global_load_dword v174, v242, s[0:1]
	s_add_u32 s0, s0, 0x3000
	s_addc_u32 s1, s1, 0
	global_load_dword v175, v242, s[0:1]
	s_add_u32 s0, s0, 0x3000
	s_addc_u32 s1, s1, 0
	global_load_dword v176, v242, s[0:1]
	s_add_u32 s0, s0, 0x3000
	s_addc_u32 s1, s1, 0
	global_load_dword v177, v242, s[0:1]
	s_add_u32 s0, s0, 0x3000
	s_addc_u32 s1, s1, 0
	v_mov_b32_e32 v226, 0
	v_mov_b32_e32 v227, 0
	v_mov_b32_e32 v228, 0
	v_mov_b32_e32 v229, 0
	v_mov_b32_e32 v230, 0
	v_mov_b32_e32 v231, 0
	v_mov_b32_e32 v232, 0
	v_mov_b32_e32 v233, 0
	v_mov_b32_e32 v234, 0
	v_mov_b32_e32 v235, 0
	v_mov_b32_e32 v236, 0
	v_mov_b32_e32 v237, 0
	v_mov_b32_e32 v238, 0
	v_mov_b32_e32 v239, 0
	v_mov_b32_e32 v240, 0
	v_mov_b32_e32 v241, 0
	s_waitcnt lgkmcnt(0)
	ds_read_b128 v[180:183], v179
	ds_read_b128 v[184:187], v179 offset:16
	ds_read_b128 v[188:191], v179 offset:32
	ds_read_b128 v[192:195], v179 offset:48
	ds_read_b128 v[210:213], v179 offset:64
	ds_read_b128 v[214:217], v179 offset:80
	ds_read_b128 v[218:221], v179 offset:96
	ds_read_b128 v[222:225], v179 offset:112
	s_waitcnt vmcnt(63) lgkmcnt(4)
	v_pk_fma_f32 v[226:227], v[114:115], v[180:181], v[226:227] op_sel:[0,0,0] op_sel_hi:[0,1,1]
	v_pk_fma_f32 v[228:229], v[114:115], v[182:183], v[228:229] op_sel:[0,0,0] op_sel_hi:[0,1,1]
	v_pk_fma_f32 v[230:231], v[114:115], v[184:185], v[230:231] op_sel:[0,0,0] op_sel_hi:[0,1,1]
	v_pk_fma_f32 v[232:233], v[114:115], v[186:187], v[232:233] op_sel:[0,0,0] op_sel_hi:[0,1,1]
	v_pk_fma_f32 v[234:235], v[114:115], v[188:189], v[234:235] op_sel:[0,0,0] op_sel_hi:[0,1,1]
	v_pk_fma_f32 v[236:237], v[114:115], v[190:191], v[236:237] op_sel:[0,0,0] op_sel_hi:[0,1,1]
	v_pk_fma_f32 v[238:239], v[114:115], v[192:193], v[238:239] op_sel:[0,0,0] op_sel_hi:[0,1,1]
	v_pk_fma_f32 v[240:241], v[114:115], v[194:195], v[240:241] op_sel:[0,0,0] op_sel_hi:[0,1,1]
	ds_read_b128 v[180:183], v179 offset:128
	ds_read_b128 v[184:187], v179 offset:144
	ds_read_b128 v[188:191], v179 offset:160
	ds_read_b128 v[192:195], v179 offset:176
	s_waitcnt vmcnt(62) lgkmcnt(4)
	v_pk_fma_f32 v[226:227], v[114:115], v[210:211], v[226:227] op_sel:[1,0,0] op_sel_hi:[1,1,1]
	v_pk_fma_f32 v[228:229], v[114:115], v[212:213], v[228:229] op_sel:[1,0,0] op_sel_hi:[1,1,1]
	v_pk_fma_f32 v[230:231], v[114:115], v[214:215], v[230:231] op_sel:[1,0,0] op_sel_hi:[1,1,1]
	v_pk_fma_f32 v[232:233], v[114:115], v[216:217], v[232:233] op_sel:[1,0,0] op_sel_hi:[1,1,1]
	v_pk_fma_f32 v[234:235], v[114:115], v[218:219], v[234:235] op_sel:[1,0,0] op_sel_hi:[1,1,1]
	v_pk_fma_f32 v[236:237], v[114:115], v[220:221], v[236:237] op_sel:[1,0,0] op_sel_hi:[1,1,1]
	v_pk_fma_f32 v[238:239], v[114:115], v[222:223], v[238:239] op_sel:[1,0,0] op_sel_hi:[1,1,1]
	v_pk_fma_f32 v[240:241], v[114:115], v[224:225], v[240:241] op_sel:[1,0,0] op_sel_hi:[1,1,1]
	ds_read_b128 v[210:213], v179 offset:192
	ds_read_b128 v[214:217], v179 offset:208
	ds_read_b128 v[218:221], v179 offset:224
	ds_read_b128 v[222:225], v179 offset:240
	s_waitcnt vmcnt(61) lgkmcnt(4)
	v_pk_fma_f32 v[226:227], v[116:117], v[180:181], v[226:227] op_sel:[0,0,0] op_sel_hi:[0,1,1]
	v_pk_fma_f32 v[228:229], v[116:117], v[182:183], v[228:229] op_sel:[0,0,0] op_sel_hi:[0,1,1]
	v_pk_fma_f32 v[230:231], v[116:117], v[184:185], v[230:231] op_sel:[0,0,0] op_sel_hi:[0,1,1]
	v_pk_fma_f32 v[232:233], v[116:117], v[186:187], v[232:233] op_sel:[0,0,0] op_sel_hi:[0,1,1]
	v_pk_fma_f32 v[234:235], v[116:117], v[188:189], v[234:235] op_sel:[0,0,0] op_sel_hi:[0,1,1]
	v_pk_fma_f32 v[236:237], v[116:117], v[190:191], v[236:237] op_sel:[0,0,0] op_sel_hi:[0,1,1]
	v_pk_fma_f32 v[238:239], v[116:117], v[192:193], v[238:239] op_sel:[0,0,0] op_sel_hi:[0,1,1]
	v_pk_fma_f32 v[240:241], v[116:117], v[194:195], v[240:241] op_sel:[0,0,0] op_sel_hi:[0,1,1]
	ds_read_b128 v[180:183], v179 offset:256
	ds_read_b128 v[184:187], v179 offset:272
	ds_read_b128 v[188:191], v179 offset:288
	ds_read_b128 v[192:195], v179 offset:304
	s_waitcnt vmcnt(60) lgkmcnt(4)
; #define LAS __attribute__((address_space(3)))
; __global__ void __launch_bounds__(NTHR, 2) hymba_fwd(Params P) {
;     ...
;             for (int kk = 0; kk < 128; ++kk) { const float wv = P.w_ada[(size_t)(wave * 128 + kk) * 3072 + col];
; #pragma unroll
;                 for (int q = 0; q < 4; ++q) { const f32x4 s = *(const LAS f32x4*)(sil + kk * 16 + 4 * q); acc[4 * q] += s[0] * wv; acc[4 * q + 1] += s[1] * wv; acc[4 * q + 2] += s[2] * wv; acc[4 * q + 3] += s[3] * wv; } }
	v_pk_fma_f32 v[226:227], v[116:117], v[210:211], v[226:227] op_sel:[1,0,0] op_sel_hi:[1,1,1]
	v_pk_fma_f32 v[228:229], v[116:117], v[212:213], v[228:229] op_sel:[1,0,0] op_sel_hi:[1,1,1]
	v_pk_fma_f32 v[230:231], v[116:117], v[214:215], v[230:231] op_sel:[1,0,0] op_sel_hi:[1,1,1]
	v_pk_fma_f32 v[232:233], v[116:117], v[216:217], v[232:233] op_sel:[1,0,0] op_sel_hi:[1,1,1]
	v_pk_fma_f32 v[234:235], v[116:117], v[218:219], v[234:235] op_sel:[1,0,0] op_sel_hi:[1,1,1]
	v_pk_fma_f32 v[236:237], v[116:117], v[220:221], v[236:237] op_sel:[1,0,0] op_sel_hi:[1,1,1]
	v_pk_fma_f32 v[238:239], v[116:117], v[222:223], v[238:239] op_sel:[1,0,0] op_sel_hi:[1,1,1]
	v_pk_fma_f32 v[240:241], v[116:117], v[224:225], v[240:241] op_sel:[1,0,0] op_sel_hi:[1,1,1]
	ds_read_b128 v[210:213], v179 offset:320
	ds_read_b128 v[214:217], v179 offset:336
	ds_read_b128 v[218:221], v179 offset:352
	ds_read_b128 v[222:225], v179 offset:368
	s_waitcnt vmcnt(59) lgkmcnt(4)
	v_pk_fma_f32 v[226:227], v[118:119], v[180:181], v[226:227] op_sel:[0,0,0] op_sel_hi:[0,1,1]
	v_pk_fma_f32 v[228:229], v[118:119], v[182:183], v[228:229] op_sel:[0,0,0] op_sel_hi:[0,1,1]
	v_pk_fma_f32 v[230:231], v[118:119], v[184:185], v[230:231] op_sel:[0,0,0] op_sel_hi:[0,1,1]
	v_pk_fma_f32 v[232:233], v[118:119], v[186:187], v[232:233] op_sel:[0,0,0] op_sel_hi:[0,1,1]
	v_pk_fma_f32 v[234:235], v[118:119], v[188:189], v[234:235] op_sel:[0,0,0] op_sel_hi:[0,1,1]
	v_pk_fma_f32 v[236:237], v[118:119], v[190:191], v[236:237] op_sel:[0,0,0] op_sel_hi:[0,1,1]
	v_pk_fma_f32 v[238:239], v[118:119], v[192:193], v[238:239] op_sel:[0,0,0] op_sel_hi:[0,1,1]
	v_pk_fma_f32 v[240:241], v[118:119], v[194:195], v[240:241] op_sel:[0,0,0] op_sel_hi:[0,1,1]
	ds_read_b128 v[180:183], v179 offset:384
	ds_read_b128 v[184:187], v179 offset:400
	ds_read_b128 v[188:191], v179 offset:416
	ds_read_b128 v[192:195], v179 offset:432
	s_waitcnt vmcnt(58) lgkmcnt(4)
	v_pk_fma_f32 v[226:227], v[118:119], v[210:211], v[226:227] op_sel:[1,0,0] op_sel_hi:[1,1,1]
	v_pk_fma_f32 v[228:229], v[118:119], v[212:213], v[228:229] op_sel:[1,0,0] op_sel_hi:[1,1,1]
	v_pk_fma_f32 v[230:231], v[118:119], v[214:215], v[230:231] op_sel:[1,0,0] op_sel_hi:[1,1,1]
	v_pk_fma_f32 v[232:233], v[118:119], v[216:217], v[232:233] op_sel:[1,0,0] op_sel_hi:[1,1,1]
	v_pk_fma_f32 v[234:235], v[118:119], v[218:219], v[234:235] op_sel:[1,0,0] op_sel_hi:[1,1,1]
	v_pk_fma_f32 v[236:237], v[118:119], v[220:221], v[236:237] op_sel:[1,0,0] op_sel_hi:[1,1,1]
	v_pk_fma_f32 v[238:239], v[118:119], v[222:223], v[238:239] op_sel:[1,0,0] op_sel_hi:[1,1,1]
	v_pk_fma_f32 v[240:241], v[118:119], v[224:225], v[240:241] op_sel:[1,0,0] op_sel_hi:[1,1,1]
	ds_read_b128 v[210:213], v179 offset:448
	ds_read_b128 v[214:217], v179 offset:464
	ds_read_b128 v[218:221], v179 offset:480
	ds_read_b128 v[222:225], v179 offset:496
	s_waitcnt vmcnt(57) lgkmcnt(4)
	v_pk_fma_f32 v[226:227], v[120:121], v[180:181], v[226:227] op_sel:[0,0,0] op_sel_hi:[0,1,1]
	v_pk_fma_f32 v[228:229], v[120:121], v[182:183], v[228:229] op_sel:[0,0,0] op_sel_hi:[0,1,1]
	v_pk_fma_f32 v[230:231], v[120:121], v[184:185], v[230:231] op_sel:[0,0,0] op_sel_hi:[0,1,1]
	v_pk_fma_f32 v[232:233], v[120:121], v[186:187], v[232:233] op_sel:[0,0,0] op_sel_hi:[0,1,1]
	v_pk_fma_f32 v[234:235], v[120:121], v[188:189], v[234:235] op_sel:[0,0,0] op_sel_hi:[0,1,1]
	v_pk_fma_f32 v[236:237], v[120:121], v[190:191], v[236:237] op_sel:[0,0,0] op_sel_hi:[0,1,1]
	v_pk_fma_f32 v[238:239], v[120:121], v[192:193], v[238:239] op_sel:[0,0,0] op_sel_hi:[0,1,1]
	v_pk_fma_f32 v[240:241], v[120:121], v[194:195], v[240:241] op_sel:[0,0,0] op_sel_hi:[0,1,1]
	ds_read_b128 v[180:183], v179 offset:512
	ds_read_b128 v[184:187], v179 offset:528
	ds_read_b128 v[188:191], v179 offset:544
	ds_read_b128 v[192:195], v179 offset:560
	s_waitcnt vmcnt(56) lgkmcnt(4)
	v_pk_fma_f32 v[226:227], v[120:121], v[210:211], v[226:227] op_sel:[1,0,0] op_sel_hi:[1,1,1]
	v_pk_fma_f32 v[228:229], v[120:121], v[212:213], v[228:229] op_sel:[1,0,0] op_sel_hi:[1,1,1]
	v_pk_fma_f32 v[230:231], v[120:121], v[214:215], v[230:231] op_sel:[1,0,0] op_sel_hi:[1,1,1]
	v_pk_fma_f32 v[232:233], v[120:121], v[216:217], v[232:233] op_sel:[1,0,0] op_sel_hi:[1,1,1]
	v_pk_fma_f32 v[234:235], v[120:121], v[218:219], v[234:235] op_sel:[1,0,0] op_sel_hi:[1,1,1]
	v_pk_fma_f32 v[236:237], v[120:121], v[220:221], v[236:237] op_sel:[1,0,0] op_sel_hi:[1,1,1]
	v_pk_fma_f32 v[238:239], v[120:121], v[222:223], v[238:239] op_sel:[1,0,0] op_sel_hi:[1,1,1]
	v_pk_fma_f32 v[240:241], v[120:121], v[224:225], v[240:241] op_sel:[1,0,0] op_sel_hi:[1,1,1]
	ds_read_b128 v[210:213], v179 offset:576
	ds_read_b128 v[214:217], v179 offset:592
	ds_read_b128 v[218:221], v179 offset:608
	ds_read_b128 v[222:225], v179 offset:624
	s_waitcnt vmcnt(55) lgkmcnt(4)
	v_pk_fma_f32 v[226:227], v[122:123], v[180:181], v[226:227] op_sel:[0,0,0] op_sel_hi:[0,1,1]
	v_pk_fma_f32 v[228:229], v[122:123], v[182:183], v[228:229] op_sel:[0,0,0] op_sel_hi:[0,1,1]
	v_pk_fma_f32 v[230:231], v[122:123], v[184:185], v[230:231] op_sel:[0,0,0] op_sel_hi:[0,1,1]
	v_pk_fma_f32 v[232:233], v[122:123], v[186:187], v[232:233] op_sel:[0,0,0] op_sel_hi:[0,1,1]
	v_pk_fma_f32 v[234:235], v[122:123], v[188:189], v[234:235] op_sel:[0,0,0] op_sel_hi:[0,1,1]
	v_pk_fma_f32 v[236:237], v[122:123], v[190:191], v[236:237] op_sel:[0,0,0] op_sel_hi:[0,1,1]
	v_pk_fma_f32 v[238:239], v[122:123], v[192:193], v[238:239] op_sel:[0,0,0] op_sel_hi:[0,1,1]
	v_pk_fma_f32 v[240:241], v[122:123], v[194:195], v[240:241] op_sel:[0,0,0] op_sel_hi:[0,1,1]
	ds_read_b128 v[180:183], v179 offset:640
	ds_read_b128 v[184:187], v179 offset:656
	ds_read_b128 v[188:191], v179 offset:672
	ds_read_b128 v[192:195], v179 offset:688
	s_waitcnt vmcnt(54) lgkmcnt(4)
; #define LAS __attribute__((address_space(3)))
; __global__ void __launch_bounds__(NTHR, 2) hymba_fwd(Params P) {
;     ...
;             for (int kk = 0; kk < 128; ++kk) { const float wv = P.w_ada[(size_t)(wave * 128 + kk) * 3072 + col];
; #pragma unroll
;                 for (int q = 0; q < 4; ++q) { const f32x4 s = *(const LAS f32x4*)(sil + kk * 16 + 4 * q); acc[4 * q] += s[0] * wv; acc[4 * q + 1] += s[1] * wv; acc[4 * q + 2] += s[2] * wv; acc[4 * q + 3] += s[3] * wv; } }
	v_pk_fma_f32 v[226:227], v[122:123], v[210:211], v[226:227] op_sel:[1,0,0] op_sel_hi:[1,1,1]
	v_pk_fma_f32 v[228:229], v[122:123], v[212:213], v[228:229] op_sel:[1,0,0] op_sel_hi:[1,1,1]
	v_pk_fma_f32 v[230:231], v[122:123], v[214:215], v[230:231] op_sel:[1,0,0] op_sel_hi:[1,1,1]
	v_pk_fma_f32 v[232:233], v[122:123], v[216:217], v[232:233] op_sel:[1,0,0] op_sel_hi:[1,1,1]
	v_pk_fma_f32 v[234:235], v[122:123], v[218:219], v[234:235] op_sel:[1,0,0] op_sel_hi:[1,1,1]
	v_pk_fma_f32 v[236:237], v[122:123], v[220:221], v[236:237] op_sel:[1,0,0] op_sel_hi:[1,1,1]
	v_pk_fma_f32 v[238:239], v[122:123], v[222:223], v[238:239] op_sel:[1,0,0] op_sel_hi:[1,1,1]
	v_pk_fma_f32 v[240:241], v[122:123], v[224:225], v[240:241] op_sel:[1,0,0] op_sel_hi:[1,1,1]
	ds_read_b128 v[210:213], v179 offset:704
	ds_read_b128 v[214:217], v179 offset:720
	ds_read_b128 v[218:221], v179 offset:736
	ds_read_b128 v[222:225], v179 offset:752
	s_waitcnt vmcnt(53) lgkmcnt(4)
	v_pk_fma_f32 v[226:227], v[124:125], v[180:181], v[226:227] op_sel:[0,0,0] op_sel_hi:[0,1,1]
	v_pk_fma_f32 v[228:229], v[124:125], v[182:183], v[228:229] op_sel:[0,0,0] op_sel_hi:[0,1,1]
	v_pk_fma_f32 v[230:231], v[124:125], v[184:185], v[230:231] op_sel:[0,0,0] op_sel_hi:[0,1,1]
	v_pk_fma_f32 v[232:233], v[124:125], v[186:187], v[232:233] op_sel:[0,0,0] op_sel_hi:[0,1,1]
	v_pk_fma_f32 v[234:235], v[124:125], v[188:189], v[234:235] op_sel:[0,0,0] op_sel_hi:[0,1,1]
	v_pk_fma_f32 v[236:237], v[124:125], v[190:191], v[236:237] op_sel:[0,0,0] op_sel_hi:[0,1,1]
	v_pk_fma_f32 v[238:239], v[124:125], v[192:193], v[238:239] op_sel:[0,0,0] op_sel_hi:[0,1,1]
	v_pk_fma_f32 v[240:241], v[124:125], v[194:195], v[240:241] op_sel:[0,0,0] op_sel_hi:[0,1,1]
	ds_read_b128 v[180:183], v179 offset:768
	ds_read_b128 v[184:187], v179 offset:784
	ds_read_b128 v[188:191], v179 offset:800
	ds_read_b128 v[192:195], v179 offset:816
	s_waitcnt vmcnt(52) lgkmcnt(4)
	v_pk_fma_f32 v[226:227], v[124:125], v[210:211], v[226:227] op_sel:[1,0,0] op_sel_hi:[1,1,1]
	v_pk_fma_f32 v[228:229], v[124:125], v[212:213], v[228:229] op_sel:[1,0,0] op_sel_hi:[1,1,1]
	v_pk_fma_f32 v[230:231], v[124:125], v[214:215], v[230:231] op_sel:[1,0,0] op_sel_hi:[1,1,1]
	v_pk_fma_f32 v[232:233], v[124:125], v[216:217], v[232:233] op_sel:[1,0,0] op_sel_hi:[1,1,1]
	v_pk_fma_f32 v[234:235], v[124:125], v[218:219], v[234:235] op_sel:[1,0,0] op_sel_hi:[1,1,1]
	v_pk_fma_f32 v[236:237], v[124:125], v[220:221], v[236:237] op_sel:[1,0,0] op_sel_hi:[1,1,1]
	v_pk_fma_f32 v[238:239], v[124:125], v[222:223], v[238:239] op_sel:[1,0,0] op_sel_hi:[1,1,1]
	v_pk_fma_f32 v[240:241], v[124:125], v[224:225], v[240:241] op_sel:[1,0,0] op_sel_hi:[1,1,1]
	ds_read_b128 v[210:213], v179 offset:832
	ds_read_b128 v[214:217], v179 offset:848
	ds_read_b128 v[218:221], v179 offset:864
	ds_read_b128 v[222:225], v179 offset:880
	s_waitcnt vmcnt(51) lgkmcnt(4)
	v_pk_fma_f32 v[226:227], v[126:127], v[180:181], v[226:227] op_sel:[0,0,0] op_sel_hi:[0,1,1]
	v_pk_fma_f32 v[228:229], v[126:127], v[182:183], v[228:229] op_sel:[0,0,0] op_sel_hi:[0,1,1]
	v_pk_fma_f32 v[230:231], v[126:127], v[184:185], v[230:231] op_sel:[0,0,0] op_sel_hi:[0,1,1]
	v_pk_fma_f32 v[232:233], v[126:127], v[186:187], v[232:233] op_sel:[0,0,0] op_sel_hi:[0,1,1]
	v_pk_fma_f32 v[234:235], v[126:127], v[188:189], v[234:235] op_sel:[0,0,0] op_sel_hi:[0,1,1]
	v_pk_fma_f32 v[236:237], v[126:127], v[190:191], v[236:237] op_sel:[0,0,0] op_sel_hi:[0,1,1]
	v_pk_fma_f32 v[238:239], v[126:127], v[192:193], v[238:239] op_sel:[0,0,0] op_sel_hi:[0,1,1]
	v_pk_fma_f32 v[240:241], v[126:127], v[194:195], v[240:241] op_sel:[0,0,0] op_sel_hi:[0,1,1]
	ds_read_b128 v[180:183], v179 offset:896
	ds_read_b128 v[184:187], v179 offset:912
	ds_read_b128 v[188:191], v179 offset:928
	ds_read_b128 v[192:195], v179 offset:944
	s_waitcnt vmcnt(50) lgkmcnt(4)
	v_pk_fma_f32 v[226:227], v[126:127], v[210:211], v[226:227] op_sel:[1,0,0] op_sel_hi:[1,1,1]
	v_pk_fma_f32 v[228:229], v[126:127], v[212:213], v[228:229] op_sel:[1,0,0] op_sel_hi:[1,1,1]
	v_pk_fma_f32 v[230:231], v[126:127], v[214:215], v[230:231] op_sel:[1,0,0] op_sel_hi:[1,1,1]
	v_pk_fma_f32 v[232:233], v[126:127], v[216:217], v[232:233] op_sel:[1,0,0] op_sel_hi:[1,1,1]
	v_pk_fma_f32 v[234:235], v[126:127], v[218:219], v[234:235] op_sel:[1,0,0] op_sel_hi:[1,1,1]
	v_pk_fma_f32 v[236:237], v[126:127], v[220:221], v[236:237] op_sel:[1,0,0] op_sel_hi:[1,1,1]
	v_pk_fma_f32 v[238:239], v[126:127], v[222:223], v[238:239] op_sel:[1,0,0] op_sel_hi:[1,1,1]
	v_pk_fma_f32 v[240:241], v[126:127], v[224:225], v[240:241] op_sel:[1,0,0] op_sel_hi:[1,1,1]
	ds_read_b128 v[210:213], v179 offset:960
	ds_read_b128 v[214:217], v179 offset:976
	ds_read_b128 v[218:221], v179 offset:992
	ds_read_b128 v[222:225], v179 offset:1008
	s_waitcnt vmcnt(49) lgkmcnt(4)
	v_pk_fma_f32 v[226:227], v[128:129], v[180:181], v[226:227] op_sel:[0,0,0] op_sel_hi:[0,1,1]
	v_pk_fma_f32 v[228:229], v[128:129], v[182:183], v[228:229] op_sel:[0,0,0] op_sel_hi:[0,1,1]
	v_pk_fma_f32 v[230:231], v[128:129], v[184:185], v[230:231] op_sel:[0,0,0] op_sel_hi:[0,1,1]
	v_pk_fma_f32 v[232:233], v[128:129], v[186:187], v[232:233] op_sel:[0,0,0] op_sel_hi:[0,1,1]
	v_pk_fma_f32 v[234:235], v[128:129], v[188:189], v[234:235] op_sel:[0,0,0] op_sel_hi:[0,1,1]
	v_pk_fma_f32 v[236:237], v[128:129], v[190:191], v[236:237] op_sel:[0,0,0] op_sel_hi:[0,1,1]
	v_pk_fma_f32 v[238:239], v[128:129], v[192:193], v[238:239] op_sel:[0,0,0] op_sel_hi:[0,1,1]
	v_pk_fma_f32 v[240:241], v[128:129], v[194:195], v[240:241] op_sel:[0,0,0] op_sel_hi:[0,1,1]
	ds_read_b128 v[180:183], v179 offset:1024
	ds_read_b128 v[184:187], v179 offset:1040
	ds_read_b128 v[188:191], v179 offset:1056
	ds_read_b128 v[192:195], v179 offset:1072
	s_waitcnt vmcnt(48) lgkmcnt(4)
; #define LAS __attribute__((address_space(3)))
; __global__ void __launch_bounds__(NTHR, 2) hymba_fwd(Params P) {
;     ...
;             for (int kk = 0; kk < 128; ++kk) { const float wv = P.w_ada[(size_t)(wave * 128 + kk) * 3072 + col];
; #pragma unroll
;                 for (int q = 0; q < 4; ++q) { const f32x4 s = *(const LAS f32x4*)(sil + kk * 16 + 4 * q); acc[4 * q] += s[0] * wv; acc[4 * q + 1] += s[1] * wv; acc[4 * q + 2] += s[2] * wv; acc[4 * q + 3] += s[3] * wv; } }
	v_pk_fma_f32 v[226:227], v[128:129], v[210:211], v[226:227] op_sel:[1,0,0] op_sel_hi:[1,1,1]
	v_pk_fma_f32 v[228:229], v[128:129], v[212:213], v[228:229] op_sel:[1,0,0] op_sel_hi:[1,1,1]
	v_pk_fma_f32 v[230:231], v[128:129], v[214:215], v[230:231] op_sel:[1,0,0] op_sel_hi:[1,1,1]
	v_pk_fma_f32 v[232:233], v[128:129], v[216:217], v[232:233] op_sel:[1,0,0] op_sel_hi:[1,1,1]
	v_pk_fma_f32 v[234:235], v[128:129], v[218:219], v[234:235] op_sel:[1,0,0] op_sel_hi:[1,1,1]
	v_pk_fma_f32 v[236:237], v[128:129], v[220:221], v[236:237] op_sel:[1,0,0] op_sel_hi:[1,1,1]
	v_pk_fma_f32 v[238:239], v[128:129], v[222:223], v[238:239] op_sel:[1,0,0] op_sel_hi:[1,1,1]
	v_pk_fma_f32 v[240:241], v[128:129], v[224:225], v[240:241] op_sel:[1,0,0] op_sel_hi:[1,1,1]
	ds_read_b128 v[210:213], v179 offset:1088
	ds_read_b128 v[214:217], v179 offset:1104
	ds_read_b128 v[218:221], v179 offset:1120
	ds_read_b128 v[222:225], v179 offset:1136
	s_waitcnt vmcnt(47) lgkmcnt(4)
	v_pk_fma_f32 v[226:227], v[130:131], v[180:181], v[226:227] op_sel:[0,0,0] op_sel_hi:[0,1,1]
	v_pk_fma_f32 v[228:229], v[130:131], v[182:183], v[228:229] op_sel:[0,0,0] op_sel_hi:[0,1,1]
	v_pk_fma_f32 v[230:231], v[130:131], v[184:185], v[230:231] op_sel:[0,0,0] op_sel_hi:[0,1,1]
	v_pk_fma_f32 v[232:233], v[130:131], v[186:187], v[232:233] op_sel:[0,0,0] op_sel_hi:[0,1,1]
	v_pk_fma_f32 v[234:235], v[130:131], v[188:189], v[234:235] op_sel:[0,0,0] op_sel_hi:[0,1,1]
	v_pk_fma_f32 v[236:237], v[130:131], v[190:191], v[236:237] op_sel:[0,0,0] op_sel_hi:[0,1,1]
	v_pk_fma_f32 v[238:239], v[130:131], v[192:193], v[238:239] op_sel:[0,0,0] op_sel_hi:[0,1,1]
	v_pk_fma_f32 v[240:241], v[130:131], v[194:195], v[240:241] op_sel:[0,0,0] op_sel_hi:[0,1,1]
	ds_read_b128 v[180:183], v179 offset:1152
	ds_read_b128 v[184:187], v179 offset:1168
	ds_read_b128 v[188:191], v179 offset:1184
	ds_read_b128 v[192:195], v179 offset:1200
	s_waitcnt vmcnt(46) lgkmcnt(4)
	v_pk_fma_f32 v[226:227], v[130:131], v[210:211], v[226:227] op_sel:[1,0,0] op_sel_hi:[1,1,1]
	v_pk_fma_f32 v[228:229], v[130:131], v[212:213], v[228:229] op_sel:[1,0,0] op_sel_hi:[1,1,1]
	v_pk_fma_f32 v[230:231], v[130:131], v[214:215], v[230:231] op_sel:[1,0,0] op_sel_hi:[1,1,1]
	v_pk_fma_f32 v[232:233], v[130:131], v[216:217], v[232:233] op_sel:[1,0,0] op_sel_hi:[1,1,1]
	v_pk_fma_f32 v[234:235], v[130:131], v[218:219], v[234:235] op_sel:[1,0,0] op_sel_hi:[1,1,1]
	v_pk_fma_f32 v[236:237], v[130:131], v[220:221], v[236:237] op_sel:[1,0,0] op_sel_hi:[1,1,1]
	v_pk_fma_f32 v[238:239], v[130:131], v[222:223], v[238:239] op_sel:[1,0,0] op_sel_hi:[1,1,1]
	v_pk_fma_f32 v[240:241], v[130:131], v[224:225], v[240:241] op_sel:[1,0,0] op_sel_hi:[1,1,1]
	ds_read_b128 v[210:213], v179 offset:1216
	ds_read_b128 v[214:217], v179 offset:1232
	ds_read_b128 v[218:221], v179 offset:1248
	ds_read_b128 v[222:225], v179 offset:1264
	s_waitcnt vmcnt(45) lgkmcnt(4)
	v_pk_fma_f32 v[226:227], v[132:133], v[180:181], v[226:227] op_sel:[0,0,0] op_sel_hi:[0,1,1]
	v_pk_fma_f32 v[228:229], v[132:133], v[182:183], v[228:229] op_sel:[0,0,0] op_sel_hi:[0,1,1]
	v_pk_fma_f32 v[230:231], v[132:133], v[184:185], v[230:231] op_sel:[0,0,0] op_sel_hi:[0,1,1]
	v_pk_fma_f32 v[232:233], v[132:133], v[186:187], v[232:233] op_sel:[0,0,0] op_sel_hi:[0,1,1]
	v_pk_fma_f32 v[234:235], v[132:133], v[188:189], v[234:235] op_sel:[0,0,0] op_sel_hi:[0,1,1]
	v_pk_fma_f32 v[236:237], v[132:133], v[190:191], v[236:237] op_sel:[0,0,0] op_sel_hi:[0,1,1]
	v_pk_fma_f32 v[238:239], v[132:133], v[192:193], v[238:239] op_sel:[0,0,0] op_sel_hi:[0,1,1]
	v_pk_fma_f32 v[240:241], v[132:133], v[194:195], v[240:241] op_sel:[0,0,0] op_sel_hi:[0,1,1]
	ds_read_b128 v[180:183], v179 offset:1280
	ds_read_b128 v[184:187], v179 offset:1296
	ds_read_b128 v[188:191], v179 offset:1312
	ds_read_b128 v[192:195], v179 offset:1328
	s_waitcnt vmcnt(44) lgkmcnt(4)
	v_pk_fma_f32 v[226:227], v[132:133], v[210:211], v[226:227] op_sel:[1,0,0] op_sel_hi:[1,1,1]
	v_pk_fma_f32 v[228:229], v[132:133], v[212:213], v[228:229] op_sel:[1,0,0] op_sel_hi:[1,1,1]
	v_pk_fma_f32 v[230:231], v[132:133], v[214:215], v[230:231] op_sel:[1,0,0] op_sel_hi:[1,1,1]
	v_pk_fma_f32 v[232:233], v[132:133], v[216:217], v[232:233] op_sel:[1,0,0] op_sel_hi:[1,1,1]
	v_pk_fma_f32 v[234:235], v[132:133], v[218:219], v[234:235] op_sel:[1,0,0] op_sel_hi:[1,1,1]
	v_pk_fma_f32 v[236:237], v[132:133], v[220:221], v[236:237] op_sel:[1,0,0] op_sel_hi:[1,1,1]
	v_pk_fma_f32 v[238:239], v[132:133], v[222:223], v[238:239] op_sel:[1,0,0] op_sel_hi:[1,1,1]
	v_pk_fma_f32 v[240:241], v[132:133], v[224:225], v[240:241] op_sel:[1,0,0] op_sel_hi:[1,1,1]
	ds_read_b128 v[210:213], v179 offset:1344
	ds_read_b128 v[214:217], v179 offset:1360
	ds_read_b128 v[218:221], v179 offset:1376
	ds_read_b128 v[222:225], v179 offset:1392
	s_waitcnt vmcnt(43) lgkmcnt(4)
	v_pk_fma_f32 v[226:227], v[134:135], v[180:181], v[226:227] op_sel:[0,0,0] op_sel_hi:[0,1,1]
	v_pk_fma_f32 v[228:229], v[134:135], v[182:183], v[228:229] op_sel:[0,0,0] op_sel_hi:[0,1,1]
	v_pk_fma_f32 v[230:231], v[134:135], v[184:185], v[230:231] op_sel:[0,0,0] op_sel_hi:[0,1,1]
	v_pk_fma_f32 v[232:233], v[134:135], v[186:187], v[232:233] op_sel:[0,0,0] op_sel_hi:[0,1,1]
	v_pk_fma_f32 v[234:235], v[134:135], v[188:189], v[234:235] op_sel:[0,0,0] op_sel_hi:[0,1,1]
	v_pk_fma_f32 v[236:237], v[134:135], v[190:191], v[236:237] op_sel:[0,0,0] op_sel_hi:[0,1,1]
	v_pk_fma_f32 v[238:239], v[134:135], v[192:193], v[238:239] op_sel:[0,0,0] op_sel_hi:[0,1,1]
	v_pk_fma_f32 v[240:241], v[134:135], v[194:195], v[240:241] op_sel:[0,0,0] op_sel_hi:[0,1,1]
	ds_read_b128 v[180:183], v179 offset:1408
	ds_read_b128 v[184:187], v179 offset:1424
	ds_read_b128 v[188:191], v179 offset:1440
	ds_read_b128 v[192:195], v179 offset:1456
	s_waitcnt vmcnt(42) lgkmcnt(4)
; #define LAS __attribute__((address_space(3)))
; __global__ void __launch_bounds__(NTHR, 2) hymba_fwd(Params P) {
;     ...
;             for (int kk = 0; kk < 128; ++kk) { const float wv = P.w_ada[(size_t)(wave * 128 + kk) * 3072 + col];
; #pragma unroll
;                 for (int q = 0; q < 4; ++q) { const f32x4 s = *(const LAS f32x4*)(sil + kk * 16 + 4 * q); acc[4 * q] += s[0] * wv; acc[4 * q + 1] += s[1] * wv; acc[4 * q + 2] += s[2] * wv; acc[4 * q + 3] += s[3] * wv; } }
	v_pk_fma_f32 v[226:227], v[134:135], v[210:211], v[226:227] op_sel:[1,0,0] op_sel_hi:[1,1,1]
	v_pk_fma_f32 v[228:229], v[134:135], v[212:213], v[228:229] op_sel:[1,0,0] op_sel_hi:[1,1,1]
	v_pk_fma_f32 v[230:231], v[134:135], v[214:215], v[230:231] op_sel:[1,0,0] op_sel_hi:[1,1,1]
	v_pk_fma_f32 v[232:233], v[134:135], v[216:217], v[232:233] op_sel:[1,0,0] op_sel_hi:[1,1,1]
	v_pk_fma_f32 v[234:235], v[134:135], v[218:219], v[234:235] op_sel:[1,0,0] op_sel_hi:[1,1,1]
	v_pk_fma_f32 v[236:237], v[134:135], v[220:221], v[236:237] op_sel:[1,0,0] op_sel_hi:[1,1,1]
	v_pk_fma_f32 v[238:239], v[134:135], v[222:223], v[238:239] op_sel:[1,0,0] op_sel_hi:[1,1,1]
	v_pk_fma_f32 v[240:241], v[134:135], v[224:225], v[240:241] op_sel:[1,0,0] op_sel_hi:[1,1,1]
	ds_read_b128 v[210:213], v179 offset:1472
	ds_read_b128 v[214:217], v179 offset:1488
	ds_read_b128 v[218:221], v179 offset:1504
	ds_read_b128 v[222:225], v179 offset:1520
	s_waitcnt vmcnt(41) lgkmcnt(4)
	v_pk_fma_f32 v[226:227], v[136:137], v[180:181], v[226:227] op_sel:[0,0,0] op_sel_hi:[0,1,1]
	v_pk_fma_f32 v[228:229], v[136:137], v[182:183], v[228:229] op_sel:[0,0,0] op_sel_hi:[0,1,1]
	v_pk_fma_f32 v[230:231], v[136:137], v[184:185], v[230:231] op_sel:[0,0,0] op_sel_hi:[0,1,1]
	v_pk_fma_f32 v[232:233], v[136:137], v[186:187], v[232:233] op_sel:[0,0,0] op_sel_hi:[0,1,1]
	v_pk_fma_f32 v[234:235], v[136:137], v[188:189], v[234:235] op_sel:[0,0,0] op_sel_hi:[0,1,1]
	v_pk_fma_f32 v[236:237], v[136:137], v[190:191], v[236:237] op_sel:[0,0,0] op_sel_hi:[0,1,1]
	v_pk_fma_f32 v[238:239], v[136:137], v[192:193], v[238:239] op_sel:[0,0,0] op_sel_hi:[0,1,1]
	v_pk_fma_f32 v[240:241], v[136:137], v[194:195], v[240:241] op_sel:[0,0,0] op_sel_hi:[0,1,1]
	ds_read_b128 v[180:183], v179 offset:1536
	ds_read_b128 v[184:187], v179 offset:1552
	ds_read_b128 v[188:191], v179 offset:1568
	ds_read_b128 v[192:195], v179 offset:1584
	s_waitcnt vmcnt(40) lgkmcnt(4)
	v_pk_fma_f32 v[226:227], v[136:137], v[210:211], v[226:227] op_sel:[1,0,0] op_sel_hi:[1,1,1]
	v_pk_fma_f32 v[228:229], v[136:137], v[212:213], v[228:229] op_sel:[1,0,0] op_sel_hi:[1,1,1]
	v_pk_fma_f32 v[230:231], v[136:137], v[214:215], v[230:231] op_sel:[1,0,0] op_sel_hi:[1,1,1]
	v_pk_fma_f32 v[232:233], v[136:137], v[216:217], v[232:233] op_sel:[1,0,0] op_sel_hi:[1,1,1]
	v_pk_fma_f32 v[234:235], v[136:137], v[218:219], v[234:235] op_sel:[1,0,0] op_sel_hi:[1,1,1]
	v_pk_fma_f32 v[236:237], v[136:137], v[220:221], v[236:237] op_sel:[1,0,0] op_sel_hi:[1,1,1]
	v_pk_fma_f32 v[238:239], v[136:137], v[222:223], v[238:239] op_sel:[1,0,0] op_sel_hi:[1,1,1]
	v_pk_fma_f32 v[240:241], v[136:137], v[224:225], v[240:241] op_sel:[1,0,0] op_sel_hi:[1,1,1]
	ds_read_b128 v[210:213], v179 offset:1600
	ds_read_b128 v[214:217], v179 offset:1616
	ds_read_b128 v[218:221], v179 offset:1632
	ds_read_b128 v[222:225], v179 offset:1648
	s_waitcnt vmcnt(39) lgkmcnt(4)
	v_pk_fma_f32 v[226:227], v[138:139], v[180:181], v[226:227] op_sel:[0,0,0] op_sel_hi:[0,1,1]
	v_pk_fma_f32 v[228:229], v[138:139], v[182:183], v[228:229] op_sel:[0,0,0] op_sel_hi:[0,1,1]
	v_pk_fma_f32 v[230:231], v[138:139], v[184:185], v[230:231] op_sel:[0,0,0] op_sel_hi:[0,1,1]
	v_pk_fma_f32 v[232:233], v[138:139], v[186:187], v[232:233] op_sel:[0,0,0] op_sel_hi:[0,1,1]
	v_pk_fma_f32 v[234:235], v[138:139], v[188:189], v[234:235] op_sel:[0,0,0] op_sel_hi:[0,1,1]
	v_pk_fma_f32 v[236:237], v[138:139], v[190:191], v[236:237] op_sel:[0,0,0] op_sel_hi:[0,1,1]
	v_pk_fma_f32 v[238:239], v[138:139], v[192:193], v[238:239] op_sel:[0,0,0] op_sel_hi:[0,1,1]
	v_pk_fma_f32 v[240:241], v[138:139], v[194:195], v[240:241] op_sel:[0,0,0] op_sel_hi:[0,1,1]
	ds_read_b128 v[180:183], v179 offset:1664
	ds_read_b128 v[184:187], v179 offset:1680
	ds_read_b128 v[188:191], v179 offset:1696
	ds_read_b128 v[192:195], v179 offset:1712
	s_waitcnt vmcnt(38) lgkmcnt(4)
	v_pk_fma_f32 v[226:227], v[138:139], v[210:211], v[226:227] op_sel:[1,0,0] op_sel_hi:[1,1,1]
	v_pk_fma_f32 v[228:229], v[138:139], v[212:213], v[228:229] op_sel:[1,0,0] op_sel_hi:[1,1,1]
	v_pk_fma_f32 v[230:231], v[138:139], v[214:215], v[230:231] op_sel:[1,0,0] op_sel_hi:[1,1,1]
	v_pk_fma_f32 v[232:233], v[138:139], v[216:217], v[232:233] op_sel:[1,0,0] op_sel_hi:[1,1,1]
	v_pk_fma_f32 v[234:235], v[138:139], v[218:219], v[234:235] op_sel:[1,0,0] op_sel_hi:[1,1,1]
	v_pk_fma_f32 v[236:237], v[138:139], v[220:221], v[236:237] op_sel:[1,0,0] op_sel_hi:[1,1,1]
	v_pk_fma_f32 v[238:239], v[138:139], v[222:223], v[238:239] op_sel:[1,0,0] op_sel_hi:[1,1,1]
	v_pk_fma_f32 v[240:241], v[138:139], v[224:225], v[240:241] op_sel:[1,0,0] op_sel_hi:[1,1,1]
	ds_read_b128 v[210:213], v179 offset:1728
	ds_read_b128 v[214:217], v179 offset:1744
	ds_read_b128 v[218:221], v179 offset:1760
	ds_read_b128 v[222:225], v179 offset:1776
	s_waitcnt vmcnt(37) lgkmcnt(4)
	v_pk_fma_f32 v[226:227], v[140:141], v[180:181], v[226:227] op_sel:[0,0,0] op_sel_hi:[0,1,1]
	v_pk_fma_f32 v[228:229], v[140:141], v[182:183], v[228:229] op_sel:[0,0,0] op_sel_hi:[0,1,1]
	v_pk_fma_f32 v[230:231], v[140:141], v[184:185], v[230:231] op_sel:[0,0,0] op_sel_hi:[0,1,1]
	v_pk_fma_f32 v[232:233], v[140:141], v[186:187], v[232:233] op_sel:[0,0,0] op_sel_hi:[0,1,1]
	v_pk_fma_f32 v[234:235], v[140:141], v[188:189], v[234:235] op_sel:[0,0,0] op_sel_hi:[0,1,1]
	v_pk_fma_f32 v[236:237], v[140:141], v[190:191], v[236:237] op_sel:[0,0,0] op_sel_hi:[0,1,1]
	v_pk_fma_f32 v[238:239], v[140:141], v[192:193], v[238:239] op_sel:[0,0,0] op_sel_hi:[0,1,1]
	v_pk_fma_f32 v[240:241], v[140:141], v[194:195], v[240:241] op_sel:[0,0,0] op_sel_hi:[0,1,1]
	ds_read_b128 v[180:183], v179 offset:1792
	ds_read_b128 v[184:187], v179 offset:1808
	ds_read_b128 v[188:191], v179 offset:1824
	ds_read_b128 v[192:195], v179 offset:1840
	s_waitcnt vmcnt(36) lgkmcnt(4)
; #define LAS __attribute__((address_space(3)))
; __global__ void __launch_bounds__(NTHR, 2) hymba_fwd(Params P) {
;     ...
;             for (int kk = 0; kk < 128; ++kk) { const float wv = P.w_ada[(size_t)(wave * 128 + kk) * 3072 + col];
; #pragma unroll
;                 for (int q = 0; q < 4; ++q) { const f32x4 s = *(const LAS f32x4*)(sil + kk * 16 + 4 * q); acc[4 * q] += s[0] * wv; acc[4 * q + 1] += s[1] * wv; acc[4 * q + 2] += s[2] * wv; acc[4 * q + 3] += s[3] * wv; } }
	v_pk_fma_f32 v[226:227], v[140:141], v[210:211], v[226:227] op_sel:[1,0,0] op_sel_hi:[1,1,1]
	v_pk_fma_f32 v[228:229], v[140:141], v[212:213], v[228:229] op_sel:[1,0,0] op_sel_hi:[1,1,1]
	v_pk_fma_f32 v[230:231], v[140:141], v[214:215], v[230:231] op_sel:[1,0,0] op_sel_hi:[1,1,1]
	v_pk_fma_f32 v[232:233], v[140:141], v[216:217], v[232:233] op_sel:[1,0,0] op_sel_hi:[1,1,1]
	v_pk_fma_f32 v[234:235], v[140:141], v[218:219], v[234:235] op_sel:[1,0,0] op_sel_hi:[1,1,1]
	v_pk_fma_f32 v[236:237], v[140:141], v[220:221], v[236:237] op_sel:[1,0,0] op_sel_hi:[1,1,1]
	v_pk_fma_f32 v[238:239], v[140:141], v[222:223], v[238:239] op_sel:[1,0,0] op_sel_hi:[1,1,1]
	v_pk_fma_f32 v[240:241], v[140:141], v[224:225], v[240:241] op_sel:[1,0,0] op_sel_hi:[1,1,1]
	ds_read_b128 v[210:213], v179 offset:1856
	ds_read_b128 v[214:217], v179 offset:1872
	ds_read_b128 v[218:221], v179 offset:1888
	ds_read_b128 v[222:225], v179 offset:1904
	s_waitcnt vmcnt(35) lgkmcnt(4)
	v_pk_fma_f32 v[226:227], v[142:143], v[180:181], v[226:227] op_sel:[0,0,0] op_sel_hi:[0,1,1]
	v_pk_fma_f32 v[228:229], v[142:143], v[182:183], v[228:229] op_sel:[0,0,0] op_sel_hi:[0,1,1]
	v_pk_fma_f32 v[230:231], v[142:143], v[184:185], v[230:231] op_sel:[0,0,0] op_sel_hi:[0,1,1]
	v_pk_fma_f32 v[232:233], v[142:143], v[186:187], v[232:233] op_sel:[0,0,0] op_sel_hi:[0,1,1]
	v_pk_fma_f32 v[234:235], v[142:143], v[188:189], v[234:235] op_sel:[0,0,0] op_sel_hi:[0,1,1]
	v_pk_fma_f32 v[236:237], v[142:143], v[190:191], v[236:237] op_sel:[0,0,0] op_sel_hi:[0,1,1]
	v_pk_fma_f32 v[238:239], v[142:143], v[192:193], v[238:239] op_sel:[0,0,0] op_sel_hi:[0,1,1]
	v_pk_fma_f32 v[240:241], v[142:143], v[194:195], v[240:241] op_sel:[0,0,0] op_sel_hi:[0,1,1]
	ds_read_b128 v[180:183], v179 offset:1920
	ds_read_b128 v[184:187], v179 offset:1936
	ds_read_b128 v[188:191], v179 offset:1952
	ds_read_b128 v[192:195], v179 offset:1968
	s_waitcnt vmcnt(34) lgkmcnt(4)
	v_pk_fma_f32 v[226:227], v[142:143], v[210:211], v[226:227] op_sel:[1,0,0] op_sel_hi:[1,1,1]
	v_pk_fma_f32 v[228:229], v[142:143], v[212:213], v[228:229] op_sel:[1,0,0] op_sel_hi:[1,1,1]
	v_pk_fma_f32 v[230:231], v[142:143], v[214:215], v[230:231] op_sel:[1,0,0] op_sel_hi:[1,1,1]
	v_pk_fma_f32 v[232:233], v[142:143], v[216:217], v[232:233] op_sel:[1,0,0] op_sel_hi:[1,1,1]
	v_pk_fma_f32 v[234:235], v[142:143], v[218:219], v[234:235] op_sel:[1,0,0] op_sel_hi:[1,1,1]
	v_pk_fma_f32 v[236:237], v[142:143], v[220:221], v[236:237] op_sel:[1,0,0] op_sel_hi:[1,1,1]
	v_pk_fma_f32 v[238:239], v[142:143], v[222:223], v[238:239] op_sel:[1,0,0] op_sel_hi:[1,1,1]
	v_pk_fma_f32 v[240:241], v[142:143], v[224:225], v[240:241] op_sel:[1,0,0] op_sel_hi:[1,1,1]
	ds_read_b128 v[210:213], v179 offset:1984
	ds_read_b128 v[214:217], v179 offset:2000
	ds_read_b128 v[218:221], v179 offset:2016
	ds_read_b128 v[222:225], v179 offset:2032
	s_waitcnt vmcnt(33) lgkmcnt(4)
	v_pk_fma_f32 v[226:227], v[144:145], v[180:181], v[226:227] op_sel:[0,0,0] op_sel_hi:[0,1,1]
	v_pk_fma_f32 v[228:229], v[144:145], v[182:183], v[228:229] op_sel:[0,0,0] op_sel_hi:[0,1,1]
	v_pk_fma_f32 v[230:231], v[144:145], v[184:185], v[230:231] op_sel:[0,0,0] op_sel_hi:[0,1,1]
	v_pk_fma_f32 v[232:233], v[144:145], v[186:187], v[232:233] op_sel:[0,0,0] op_sel_hi:[0,1,1]
	v_pk_fma_f32 v[234:235], v[144:145], v[188:189], v[234:235] op_sel:[0,0,0] op_sel_hi:[0,1,1]
	v_pk_fma_f32 v[236:237], v[144:145], v[190:191], v[236:237] op_sel:[0,0,0] op_sel_hi:[0,1,1]
	v_pk_fma_f32 v[238:239], v[144:145], v[192:193], v[238:239] op_sel:[0,0,0] op_sel_hi:[0,1,1]
	v_pk_fma_f32 v[240:241], v[144:145], v[194:195], v[240:241] op_sel:[0,0,0] op_sel_hi:[0,1,1]
	ds_read_b128 v[180:183], v179 offset:2048
	ds_read_b128 v[184:187], v179 offset:2064
	ds_read_b128 v[188:191], v179 offset:2080
	ds_read_b128 v[192:195], v179 offset:2096
	s_waitcnt vmcnt(32) lgkmcnt(4)
	v_pk_fma_f32 v[226:227], v[144:145], v[210:211], v[226:227] op_sel:[1,0,0] op_sel_hi:[1,1,1]
	v_pk_fma_f32 v[228:229], v[144:145], v[212:213], v[228:229] op_sel:[1,0,0] op_sel_hi:[1,1,1]
	v_pk_fma_f32 v[230:231], v[144:145], v[214:215], v[230:231] op_sel:[1,0,0] op_sel_hi:[1,1,1]
	v_pk_fma_f32 v[232:233], v[144:145], v[216:217], v[232:233] op_sel:[1,0,0] op_sel_hi:[1,1,1]
	v_pk_fma_f32 v[234:235], v[144:145], v[218:219], v[234:235] op_sel:[1,0,0] op_sel_hi:[1,1,1]
	v_pk_fma_f32 v[236:237], v[144:145], v[220:221], v[236:237] op_sel:[1,0,0] op_sel_hi:[1,1,1]
	v_pk_fma_f32 v[238:239], v[144:145], v[222:223], v[238:239] op_sel:[1,0,0] op_sel_hi:[1,1,1]
	v_pk_fma_f32 v[240:241], v[144:145], v[224:225], v[240:241] op_sel:[1,0,0] op_sel_hi:[1,1,1]
	global_load_dword v114, v242, s[0:1]
	s_add_u32 s0, s0, 0x3000
	s_addc_u32 s1, s1, 0
	global_load_dword v115, v242, s[0:1]
	s_add_u32 s0, s0, 0x3000
	s_addc_u32 s1, s1, 0
	global_load_dword v116, v242, s[0:1]
	s_add_u32 s0, s0, 0x3000
	s_addc_u32 s1, s1, 0
	global_load_dword v117, v242, s[0:1]
	s_add_u32 s0, s0, 0x3000
	s_addc_u32 s1, s1, 0
	global_load_dword v118, v242, s[0:1]
	s_add_u32 s0, s0, 0x3000
	s_addc_u32 s1, s1, 0
	global_load_dword v119, v242, s[0:1]
	s_add_u32 s0, s0, 0x3000
	s_addc_u32 s1, s1, 0
	global_load_dword v120, v242, s[0:1]
	s_add_u32 s0, s0, 0x3000
	s_addc_u32 s1, s1, 0
	global_load_dword v121, v242, s[0:1]
	s_add_u32 s0, s0, 0x3000
	s_addc_u32 s1, s1, 0
	global_load_dword v122, v242, s[0:1]
	s_add_u32 s0, s0, 0x3000
	s_addc_u32 s1, s1, 0
	global_load_dword v123, v242, s[0:1]
	s_add_u32 s0, s0, 0x3000
	s_addc_u32 s1, s1, 0
	global_load_dword v124, v242, s[0:1]
	s_add_u32 s0, s0, 0x3000
	s_addc_u32 s1, s1, 0
	global_load_dword v125, v242, s[0:1]
	s_add_u32 s0, s0, 0x3000
	s_addc_u32 s1, s1, 0
	global_load_dword v126, v242, s[0:1]
; #define LAS __attribute__((address_space(3)))
; __global__ void __launch_bounds__(NTHR, 2) hymba_fwd(Params P) {
;     ...
;             for (int kk = 0; kk < 128; ++kk) { const float wv = P.w_ada[(size_t)(wave * 128 + kk) * 3072 + col];
; #pragma unroll
;                 for (int q = 0; q < 4; ++q) { const f32x4 s = *(const LAS f32x4*)(sil + kk * 16 + 4 * q); acc[4 * q] += s[0] * wv; acc[4 * q + 1] += s[1] * wv; acc[4 * q + 2] += s[2] * wv; acc[4 * q + 3] += s[3] * wv; } }
	s_add_u32 s0, s0, 0x3000
	s_addc_u32 s1, s1, 0
	global_load_dword v127, v242, s[0:1]
	s_add_u32 s0, s0, 0x3000
	s_addc_u32 s1, s1, 0
	global_load_dword v128, v242, s[0:1]
	s_add_u32 s0, s0, 0x3000
	s_addc_u32 s1, s1, 0
	global_load_dword v129, v242, s[0:1]
	s_add_u32 s0, s0, 0x3000
	s_addc_u32 s1, s1, 0
	global_load_dword v130, v242, s[0:1]
	s_add_u32 s0, s0, 0x3000
	s_addc_u32 s1, s1, 0
	global_load_dword v131, v242, s[0:1]
	s_add_u32 s0, s0, 0x3000
	s_addc_u32 s1, s1, 0
	global_load_dword v132, v242, s[0:1]
	s_add_u32 s0, s0, 0x3000
	s_addc_u32 s1, s1, 0
	global_load_dword v133, v242, s[0:1]
	s_add_u32 s0, s0, 0x3000
	s_addc_u32 s1, s1, 0
	global_load_dword v134, v242, s[0:1]
	s_add_u32 s0, s0, 0x3000
	s_addc_u32 s1, s1, 0
	global_load_dword v135, v242, s[0:1]
	s_add_u32 s0, s0, 0x3000
	s_addc_u32 s1, s1, 0
	global_load_dword v136, v242, s[0:1]
	s_add_u32 s0, s0, 0x3000
	s_addc_u32 s1, s1, 0
	global_load_dword v137, v242, s[0:1]
	s_add_u32 s0, s0, 0x3000
	s_addc_u32 s1, s1, 0
	global_load_dword v138, v242, s[0:1]
	s_add_u32 s0, s0, 0x3000
	s_addc_u32 s1, s1, 0
	global_load_dword v139, v242, s[0:1]
	s_add_u32 s0, s0, 0x3000
	s_addc_u32 s1, s1, 0
	global_load_dword v140, v242, s[0:1]
	s_add_u32 s0, s0, 0x3000
	s_addc_u32 s1, s1, 0
	global_load_dword v141, v242, s[0:1]
	s_add_u32 s0, s0, 0x3000
	s_addc_u32 s1, s1, 0
	global_load_dword v142, v242, s[0:1]
	s_add_u32 s0, s0, 0x3000
	s_addc_u32 s1, s1, 0
	global_load_dword v143, v242, s[0:1]
	s_add_u32 s0, s0, 0x3000
	s_addc_u32 s1, s1, 0
	global_load_dword v144, v242, s[0:1]
	s_add_u32 s0, s0, 0x3000
	s_addc_u32 s1, s1, 0
	global_load_dword v145, v242, s[0:1]
	s_add_u32 s0, s0, 0x3000
	s_addc_u32 s1, s1, 0
	ds_read_b128 v[210:213], v179 offset:2112
	ds_read_b128 v[214:217], v179 offset:2128
	ds_read_b128 v[218:221], v179 offset:2144
	ds_read_b128 v[222:225], v179 offset:2160
	s_waitcnt vmcnt(63) lgkmcnt(4)
	v_pk_fma_f32 v[226:227], v[146:147], v[180:181], v[226:227] op_sel:[0,0,0] op_sel_hi:[0,1,1]
	v_pk_fma_f32 v[228:229], v[146:147], v[182:183], v[228:229] op_sel:[0,0,0] op_sel_hi:[0,1,1]
	v_pk_fma_f32 v[230:231], v[146:147], v[184:185], v[230:231] op_sel:[0,0,0] op_sel_hi:[0,1,1]
	v_pk_fma_f32 v[232:233], v[146:147], v[186:187], v[232:233] op_sel:[0,0,0] op_sel_hi:[0,1,1]
	v_pk_fma_f32 v[234:235], v[146:147], v[188:189], v[234:235] op_sel:[0,0,0] op_sel_hi:[0,1,1]
	v_pk_fma_f32 v[236:237], v[146:147], v[190:191], v[236:237] op_sel:[0,0,0] op_sel_hi:[0,1,1]
	v_pk_fma_f32 v[238:239], v[146:147], v[192:193], v[238:239] op_sel:[0,0,0] op_sel_hi:[0,1,1]
	v_pk_fma_f32 v[240:241], v[146:147], v[194:195], v[240:241] op_sel:[0,0,0] op_sel_hi:[0,1,1]
	ds_read_b128 v[180:183], v179 offset:2176
	ds_read_b128 v[184:187], v179 offset:2192
	ds_read_b128 v[188:191], v179 offset:2208
	ds_read_b128 v[192:195], v179 offset:2224
	s_waitcnt vmcnt(62) lgkmcnt(4)
	v_pk_fma_f32 v[226:227], v[146:147], v[210:211], v[226:227] op_sel:[1,0,0] op_sel_hi:[1,1,1]
	v_pk_fma_f32 v[228:229], v[146:147], v[212:213], v[228:229] op_sel:[1,0,0] op_sel_hi:[1,1,1]
	v_pk_fma_f32 v[230:231], v[146:147], v[214:215], v[230:231] op_sel:[1,0,0] op_sel_hi:[1,1,1]
	v_pk_fma_f32 v[232:233], v[146:147], v[216:217], v[232:233] op_sel:[1,0,0] op_sel_hi:[1,1,1]
	v_pk_fma_f32 v[234:235], v[146:147], v[218:219], v[234:235] op_sel:[1,0,0] op_sel_hi:[1,1,1]
	v_pk_fma_f32 v[236:237], v[146:147], v[220:221], v[236:237] op_sel:[1,0,0] op_sel_hi:[1,1,1]
	v_pk_fma_f32 v[238:239], v[146:147], v[222:223], v[238:239] op_sel:[1,0,0] op_sel_hi:[1,1,1]
	v_pk_fma_f32 v[240:241], v[146:147], v[224:225], v[240:241] op_sel:[1,0,0] op_sel_hi:[1,1,1]
	ds_read_b128 v[210:213], v179 offset:2240
	ds_read_b128 v[214:217], v179 offset:2256
	ds_read_b128 v[218:221], v179 offset:2272
	ds_read_b128 v[222:225], v179 offset:2288
	s_waitcnt vmcnt(61) lgkmcnt(4)
	v_pk_fma_f32 v[226:227], v[148:149], v[180:181], v[226:227] op_sel:[0,0,0] op_sel_hi:[0,1,1]
	v_pk_fma_f32 v[228:229], v[148:149], v[182:183], v[228:229] op_sel:[0,0,0] op_sel_hi:[0,1,1]
	v_pk_fma_f32 v[230:231], v[148:149], v[184:185], v[230:231] op_sel:[0,0,0] op_sel_hi:[0,1,1]
	v_pk_fma_f32 v[232:233], v[148:149], v[186:187], v[232:233] op_sel:[0,0,0] op_sel_hi:[0,1,1]
	v_pk_fma_f32 v[234:235], v[148:149], v[188:189], v[234:235] op_sel:[0,0,0] op_sel_hi:[0,1,1]
	v_pk_fma_f32 v[236:237], v[148:149], v[190:191], v[236:237] op_sel:[0,0,0] op_sel_hi:[0,1,1]
	v_pk_fma_f32 v[238:239], v[148:149], v[192:193], v[238:239] op_sel:[0,0,0] op_sel_hi:[0,1,1]
	v_pk_fma_f32 v[240:241], v[148:149], v[194:195], v[240:241] op_sel:[0,0,0] op_sel_hi:[0,1,1]
	ds_read_b128 v[180:183], v179 offset:2304
	ds_read_b128 v[184:187], v179 offset:2320
	ds_read_b128 v[188:191], v179 offset:2336
	ds_read_b128 v[192:195], v179 offset:2352
	s_waitcnt vmcnt(60) lgkmcnt(4)
	v_pk_fma_f32 v[226:227], v[148:149], v[210:211], v[226:227] op_sel:[1,0,0] op_sel_hi:[1,1,1]
	v_pk_fma_f32 v[228:229], v[148:149], v[212:213], v[228:229] op_sel:[1,0,0] op_sel_hi:[1,1,1]
	v_pk_fma_f32 v[230:231], v[148:149], v[214:215], v[230:231] op_sel:[1,0,0] op_sel_hi:[1,1,1]
	v_pk_fma_f32 v[232:233], v[148:149], v[216:217], v[232:233] op_sel:[1,0,0] op_sel_hi:[1,1,1]
	v_pk_fma_f32 v[234:235], v[148:149], v[218:219], v[234:235] op_sel:[1,0,0] op_sel_hi:[1,1,1]
	v_pk_fma_f32 v[236:237], v[148:149], v[220:221], v[236:237] op_sel:[1,0,0] op_sel_hi:[1,1,1]
	v_pk_fma_f32 v[238:239], v[148:149], v[222:223], v[238:239] op_sel:[1,0,0] op_sel_hi:[1,1,1]
	v_pk_fma_f32 v[240:241], v[148:149], v[224:225], v[240:241] op_sel:[1,0,0] op_sel_hi:[1,1,1]
	ds_read_b128 v[210:213], v179 offset:2368
	ds_read_b128 v[214:217], v179 offset:2384
	ds_read_b128 v[218:221], v179 offset:2400
	ds_read_b128 v[222:225], v179 offset:2416
	s_waitcnt vmcnt(59) lgkmcnt(4)
; #define LAS __attribute__((address_space(3)))
; __global__ void __launch_bounds__(NTHR, 2) hymba_fwd(Params P) {
;     ...
;             for (int kk = 0; kk < 128; ++kk) { const float wv = P.w_ada[(size_t)(wave * 128 + kk) * 3072 + col];
; #pragma unroll
;                 for (int q = 0; q < 4; ++q) { const f32x4 s = *(const LAS f32x4*)(sil + kk * 16 + 4 * q); acc[4 * q] += s[0] * wv; acc[4 * q + 1] += s[1] * wv; acc[4 * q + 2] += s[2] * wv; acc[4 * q + 3] += s[3] * wv; } }
	v_pk_fma_f32 v[226:227], v[150:151], v[180:181], v[226:227] op_sel:[0,0,0] op_sel_hi:[0,1,1]
	v_pk_fma_f32 v[228:229], v[150:151], v[182:183], v[228:229] op_sel:[0,0,0] op_sel_hi:[0,1,1]
	v_pk_fma_f32 v[230:231], v[150:151], v[184:185], v[230:231] op_sel:[0,0,0] op_sel_hi:[0,1,1]
	v_pk_fma_f32 v[232:233], v[150:151], v[186:187], v[232:233] op_sel:[0,0,0] op_sel_hi:[0,1,1]
	v_pk_fma_f32 v[234:235], v[150:151], v[188:189], v[234:235] op_sel:[0,0,0] op_sel_hi:[0,1,1]
	v_pk_fma_f32 v[236:237], v[150:151], v[190:191], v[236:237] op_sel:[0,0,0] op_sel_hi:[0,1,1]
	v_pk_fma_f32 v[238:239], v[150:151], v[192:193], v[238:239] op_sel:[0,0,0] op_sel_hi:[0,1,1]
	v_pk_fma_f32 v[240:241], v[150:151], v[194:195], v[240:241] op_sel:[0,0,0] op_sel_hi:[0,1,1]
	ds_read_b128 v[180:183], v179 offset:2432
	ds_read_b128 v[184:187], v179 offset:2448
	ds_read_b128 v[188:191], v179 offset:2464
	ds_read_b128 v[192:195], v179 offset:2480
	s_waitcnt vmcnt(58) lgkmcnt(4)
	v_pk_fma_f32 v[226:227], v[150:151], v[210:211], v[226:227] op_sel:[1,0,0] op_sel_hi:[1,1,1]
	v_pk_fma_f32 v[228:229], v[150:151], v[212:213], v[228:229] op_sel:[1,0,0] op_sel_hi:[1,1,1]
	v_pk_fma_f32 v[230:231], v[150:151], v[214:215], v[230:231] op_sel:[1,0,0] op_sel_hi:[1,1,1]
	v_pk_fma_f32 v[232:233], v[150:151], v[216:217], v[232:233] op_sel:[1,0,0] op_sel_hi:[1,1,1]
	v_pk_fma_f32 v[234:235], v[150:151], v[218:219], v[234:235] op_sel:[1,0,0] op_sel_hi:[1,1,1]
	v_pk_fma_f32 v[236:237], v[150:151], v[220:221], v[236:237] op_sel:[1,0,0] op_sel_hi:[1,1,1]
	v_pk_fma_f32 v[238:239], v[150:151], v[222:223], v[238:239] op_sel:[1,0,0] op_sel_hi:[1,1,1]
	v_pk_fma_f32 v[240:241], v[150:151], v[224:225], v[240:241] op_sel:[1,0,0] op_sel_hi:[1,1,1]
	ds_read_b128 v[210:213], v179 offset:2496
	ds_read_b128 v[214:217], v179 offset:2512
	ds_read_b128 v[218:221], v179 offset:2528
	ds_read_b128 v[222:225], v179 offset:2544
	s_waitcnt vmcnt(57) lgkmcnt(4)
	v_pk_fma_f32 v[226:227], v[152:153], v[180:181], v[226:227] op_sel:[0,0,0] op_sel_hi:[0,1,1]
	v_pk_fma_f32 v[228:229], v[152:153], v[182:183], v[228:229] op_sel:[0,0,0] op_sel_hi:[0,1,1]
	v_pk_fma_f32 v[230:231], v[152:153], v[184:185], v[230:231] op_sel:[0,0,0] op_sel_hi:[0,1,1]
	v_pk_fma_f32 v[232:233], v[152:153], v[186:187], v[232:233] op_sel:[0,0,0] op_sel_hi:[0,1,1]
	v_pk_fma_f32 v[234:235], v[152:153], v[188:189], v[234:235] op_sel:[0,0,0] op_sel_hi:[0,1,1]
	v_pk_fma_f32 v[236:237], v[152:153], v[190:191], v[236:237] op_sel:[0,0,0] op_sel_hi:[0,1,1]
	v_pk_fma_f32 v[238:239], v[152:153], v[192:193], v[238:239] op_sel:[0,0,0] op_sel_hi:[0,1,1]
	v_pk_fma_f32 v[240:241], v[152:153], v[194:195], v[240:241] op_sel:[0,0,0] op_sel_hi:[0,1,1]
	ds_read_b128 v[180:183], v179 offset:2560
	ds_read_b128 v[184:187], v179 offset:2576
	ds_read_b128 v[188:191], v179 offset:2592
	ds_read_b128 v[192:195], v179 offset:2608
	s_waitcnt vmcnt(56) lgkmcnt(4)
	v_pk_fma_f32 v[226:227], v[152:153], v[210:211], v[226:227] op_sel:[1,0,0] op_sel_hi:[1,1,1]
	v_pk_fma_f32 v[228:229], v[152:153], v[212:213], v[228:229] op_sel:[1,0,0] op_sel_hi:[1,1,1]
	v_pk_fma_f32 v[230:231], v[152:153], v[214:215], v[230:231] op_sel:[1,0,0] op_sel_hi:[1,1,1]
	v_pk_fma_f32 v[232:233], v[152:153], v[216:217], v[232:233] op_sel:[1,0,0] op_sel_hi:[1,1,1]
	v_pk_fma_f32 v[234:235], v[152:153], v[218:219], v[234:235] op_sel:[1,0,0] op_sel_hi:[1,1,1]
	v_pk_fma_f32 v[236:237], v[152:153], v[220:221], v[236:237] op_sel:[1,0,0] op_sel_hi:[1,1,1]
	v_pk_fma_f32 v[238:239], v[152:153], v[222:223], v[238:239] op_sel:[1,0,0] op_sel_hi:[1,1,1]
	v_pk_fma_f32 v[240:241], v[152:153], v[224:225], v[240:241] op_sel:[1,0,0] op_sel_hi:[1,1,1]
	ds_read_b128 v[210:213], v179 offset:2624
	ds_read_b128 v[214:217], v179 offset:2640
	ds_read_b128 v[218:221], v179 offset:2656
	ds_read_b128 v[222:225], v179 offset:2672
	s_waitcnt vmcnt(55) lgkmcnt(4)
	v_pk_fma_f32 v[226:227], v[154:155], v[180:181], v[226:227] op_sel:[0,0,0] op_sel_hi:[0,1,1]
	v_pk_fma_f32 v[228:229], v[154:155], v[182:183], v[228:229] op_sel:[0,0,0] op_sel_hi:[0,1,1]
	v_pk_fma_f32 v[230:231], v[154:155], v[184:185], v[230:231] op_sel:[0,0,0] op_sel_hi:[0,1,1]
	v_pk_fma_f32 v[232:233], v[154:155], v[186:187], v[232:233] op_sel:[0,0,0] op_sel_hi:[0,1,1]
	v_pk_fma_f32 v[234:235], v[154:155], v[188:189], v[234:235] op_sel:[0,0,0] op_sel_hi:[0,1,1]
	v_pk_fma_f32 v[236:237], v[154:155], v[190:191], v[236:237] op_sel:[0,0,0] op_sel_hi:[0,1,1]
	v_pk_fma_f32 v[238:239], v[154:155], v[192:193], v[238:239] op_sel:[0,0,0] op_sel_hi:[0,1,1]
	v_pk_fma_f32 v[240:241], v[154:155], v[194:195], v[240:241] op_sel:[0,0,0] op_sel_hi:[0,1,1]
	ds_read_b128 v[180:183], v179 offset:2688
	ds_read_b128 v[184:187], v179 offset:2704
	ds_read_b128 v[188:191], v179 offset:2720
	ds_read_b128 v[192:195], v179 offset:2736
	s_waitcnt vmcnt(54) lgkmcnt(4)
	v_pk_fma_f32 v[226:227], v[154:155], v[210:211], v[226:227] op_sel:[1,0,0] op_sel_hi:[1,1,1]
	v_pk_fma_f32 v[228:229], v[154:155], v[212:213], v[228:229] op_sel:[1,0,0] op_sel_hi:[1,1,1]
	v_pk_fma_f32 v[230:231], v[154:155], v[214:215], v[230:231] op_sel:[1,0,0] op_sel_hi:[1,1,1]
	v_pk_fma_f32 v[232:233], v[154:155], v[216:217], v[232:233] op_sel:[1,0,0] op_sel_hi:[1,1,1]
	v_pk_fma_f32 v[234:235], v[154:155], v[218:219], v[234:235] op_sel:[1,0,0] op_sel_hi:[1,1,1]
	v_pk_fma_f32 v[236:237], v[154:155], v[220:221], v[236:237] op_sel:[1,0,0] op_sel_hi:[1,1,1]
	v_pk_fma_f32 v[238:239], v[154:155], v[222:223], v[238:239] op_sel:[1,0,0] op_sel_hi:[1,1,1]
	v_pk_fma_f32 v[240:241], v[154:155], v[224:225], v[240:241] op_sel:[1,0,0] op_sel_hi:[1,1,1]
	ds_read_b128 v[210:213], v179 offset:2752
	ds_read_b128 v[214:217], v179 offset:2768
	ds_read_b128 v[218:221], v179 offset:2784
	ds_read_b128 v[222:225], v179 offset:2800
	s_waitcnt vmcnt(53) lgkmcnt(4)
; #define LAS __attribute__((address_space(3)))
; __global__ void __launch_bounds__(NTHR, 2) hymba_fwd(Params P) {
;     ...
;             for (int kk = 0; kk < 128; ++kk) { const float wv = P.w_ada[(size_t)(wave * 128 + kk) * 3072 + col];
; #pragma unroll
;                 for (int q = 0; q < 4; ++q) { const f32x4 s = *(const LAS f32x4*)(sil + kk * 16 + 4 * q); acc[4 * q] += s[0] * wv; acc[4 * q + 1] += s[1] * wv; acc[4 * q + 2] += s[2] * wv; acc[4 * q + 3] += s[3] * wv; } }
	v_pk_fma_f32 v[226:227], v[156:157], v[180:181], v[226:227] op_sel:[0,0,0] op_sel_hi:[0,1,1]
	v_pk_fma_f32 v[228:229], v[156:157], v[182:183], v[228:229] op_sel:[0,0,0] op_sel_hi:[0,1,1]
	v_pk_fma_f32 v[230:231], v[156:157], v[184:185], v[230:231] op_sel:[0,0,0] op_sel_hi:[0,1,1]
	v_pk_fma_f32 v[232:233], v[156:157], v[186:187], v[232:233] op_sel:[0,0,0] op_sel_hi:[0,1,1]
	v_pk_fma_f32 v[234:235], v[156:157], v[188:189], v[234:235] op_sel:[0,0,0] op_sel_hi:[0,1,1]
	v_pk_fma_f32 v[236:237], v[156:157], v[190:191], v[236:237] op_sel:[0,0,0] op_sel_hi:[0,1,1]
	v_pk_fma_f32 v[238:239], v[156:157], v[192:193], v[238:239] op_sel:[0,0,0] op_sel_hi:[0,1,1]
	v_pk_fma_f32 v[240:241], v[156:157], v[194:195], v[240:241] op_sel:[0,0,0] op_sel_hi:[0,1,1]
	ds_read_b128 v[180:183], v179 offset:2816
	ds_read_b128 v[184:187], v179 offset:2832
	ds_read_b128 v[188:191], v179 offset:2848
	ds_read_b128 v[192:195], v179 offset:2864
	s_waitcnt vmcnt(52) lgkmcnt(4)
	v_pk_fma_f32 v[226:227], v[156:157], v[210:211], v[226:227] op_sel:[1,0,0] op_sel_hi:[1,1,1]
	v_pk_fma_f32 v[228:229], v[156:157], v[212:213], v[228:229] op_sel:[1,0,0] op_sel_hi:[1,1,1]
	v_pk_fma_f32 v[230:231], v[156:157], v[214:215], v[230:231] op_sel:[1,0,0] op_sel_hi:[1,1,1]
	v_pk_fma_f32 v[232:233], v[156:157], v[216:217], v[232:233] op_sel:[1,0,0] op_sel_hi:[1,1,1]
	v_pk_fma_f32 v[234:235], v[156:157], v[218:219], v[234:235] op_sel:[1,0,0] op_sel_hi:[1,1,1]
	v_pk_fma_f32 v[236:237], v[156:157], v[220:221], v[236:237] op_sel:[1,0,0] op_sel_hi:[1,1,1]
	v_pk_fma_f32 v[238:239], v[156:157], v[222:223], v[238:239] op_sel:[1,0,0] op_sel_hi:[1,1,1]
	v_pk_fma_f32 v[240:241], v[156:157], v[224:225], v[240:241] op_sel:[1,0,0] op_sel_hi:[1,1,1]
	ds_read_b128 v[210:213], v179 offset:2880
	ds_read_b128 v[214:217], v179 offset:2896
	ds_read_b128 v[218:221], v179 offset:2912
	ds_read_b128 v[222:225], v179 offset:2928
	s_waitcnt vmcnt(51) lgkmcnt(4)
	v_pk_fma_f32 v[226:227], v[158:159], v[180:181], v[226:227] op_sel:[0,0,0] op_sel_hi:[0,1,1]
	v_pk_fma_f32 v[228:229], v[158:159], v[182:183], v[228:229] op_sel:[0,0,0] op_sel_hi:[0,1,1]
	v_pk_fma_f32 v[230:231], v[158:159], v[184:185], v[230:231] op_sel:[0,0,0] op_sel_hi:[0,1,1]
	v_pk_fma_f32 v[232:233], v[158:159], v[186:187], v[232:233] op_sel:[0,0,0] op_sel_hi:[0,1,1]
	v_pk_fma_f32 v[234:235], v[158:159], v[188:189], v[234:235] op_sel:[0,0,0] op_sel_hi:[0,1,1]
	v_pk_fma_f32 v[236:237], v[158:159], v[190:191], v[236:237] op_sel:[0,0,0] op_sel_hi:[0,1,1]
	v_pk_fma_f32 v[238:239], v[158:159], v[192:193], v[238:239] op_sel:[0,0,0] op_sel_hi:[0,1,1]
	v_pk_fma_f32 v[240:241], v[158:159], v[194:195], v[240:241] op_sel:[0,0,0] op_sel_hi:[0,1,1]
	ds_read_b128 v[180:183], v179 offset:2944
	ds_read_b128 v[184:187], v179 offset:2960
	ds_read_b128 v[188:191], v179 offset:2976
	ds_read_b128 v[192:195], v179 offset:2992
	s_waitcnt vmcnt(50) lgkmcnt(4)
	v_pk_fma_f32 v[226:227], v[158:159], v[210:211], v[226:227] op_sel:[1,0,0] op_sel_hi:[1,1,1]
	v_pk_fma_f32 v[228:229], v[158:159], v[212:213], v[228:229] op_sel:[1,0,0] op_sel_hi:[1,1,1]
	v_pk_fma_f32 v[230:231], v[158:159], v[214:215], v[230:231] op_sel:[1,0,0] op_sel_hi:[1,1,1]
	v_pk_fma_f32 v[232:233], v[158:159], v[216:217], v[232:233] op_sel:[1,0,0] op_sel_hi:[1,1,1]
	v_pk_fma_f32 v[234:235], v[158:159], v[218:219], v[234:235] op_sel:[1,0,0] op_sel_hi:[1,1,1]
	v_pk_fma_f32 v[236:237], v[158:159], v[220:221], v[236:237] op_sel:[1,0,0] op_sel_hi:[1,1,1]
	v_pk_fma_f32 v[238:239], v[158:159], v[222:223], v[238:239] op_sel:[1,0,0] op_sel_hi:[1,1,1]
	v_pk_fma_f32 v[240:241], v[158:159], v[224:225], v[240:241] op_sel:[1,0,0] op_sel_hi:[1,1,1]
	ds_read_b128 v[210:213], v179 offset:3008
	ds_read_b128 v[214:217], v179 offset:3024
	ds_read_b128 v[218:221], v179 offset:3040
	ds_read_b128 v[222:225], v179 offset:3056
	s_waitcnt vmcnt(49) lgkmcnt(4)
	v_pk_fma_f32 v[226:227], v[160:161], v[180:181], v[226:227] op_sel:[0,0,0] op_sel_hi:[0,1,1]
	v_pk_fma_f32 v[228:229], v[160:161], v[182:183], v[228:229] op_sel:[0,0,0] op_sel_hi:[0,1,1]
	v_pk_fma_f32 v[230:231], v[160:161], v[184:185], v[230:231] op_sel:[0,0,0] op_sel_hi:[0,1,1]
	v_pk_fma_f32 v[232:233], v[160:161], v[186:187], v[232:233] op_sel:[0,0,0] op_sel_hi:[0,1,1]
	v_pk_fma_f32 v[234:235], v[160:161], v[188:189], v[234:235] op_sel:[0,0,0] op_sel_hi:[0,1,1]
	v_pk_fma_f32 v[236:237], v[160:161], v[190:191], v[236:237] op_sel:[0,0,0] op_sel_hi:[0,1,1]
	v_pk_fma_f32 v[238:239], v[160:161], v[192:193], v[238:239] op_sel:[0,0,0] op_sel_hi:[0,1,1]
	v_pk_fma_f32 v[240:241], v[160:161], v[194:195], v[240:241] op_sel:[0,0,0] op_sel_hi:[0,1,1]
	ds_read_b128 v[180:183], v179 offset:3072
	ds_read_b128 v[184:187], v179 offset:3088
	ds_read_b128 v[188:191], v179 offset:3104
	ds_read_b128 v[192:195], v179 offset:3120
	s_waitcnt vmcnt(48) lgkmcnt(4)
	v_pk_fma_f32 v[226:227], v[160:161], v[210:211], v[226:227] op_sel:[1,0,0] op_sel_hi:[1,1,1]
	v_pk_fma_f32 v[228:229], v[160:161], v[212:213], v[228:229] op_sel:[1,0,0] op_sel_hi:[1,1,1]
	v_pk_fma_f32 v[230:231], v[160:161], v[214:215], v[230:231] op_sel:[1,0,0] op_sel_hi:[1,1,1]
	v_pk_fma_f32 v[232:233], v[160:161], v[216:217], v[232:233] op_sel:[1,0,0] op_sel_hi:[1,1,1]
	v_pk_fma_f32 v[234:235], v[160:161], v[218:219], v[234:235] op_sel:[1,0,0] op_sel_hi:[1,1,1]
	v_pk_fma_f32 v[236:237], v[160:161], v[220:221], v[236:237] op_sel:[1,0,0] op_sel_hi:[1,1,1]
	v_pk_fma_f32 v[238:239], v[160:161], v[222:223], v[238:239] op_sel:[1,0,0] op_sel_hi:[1,1,1]
	v_pk_fma_f32 v[240:241], v[160:161], v[224:225], v[240:241] op_sel:[1,0,0] op_sel_hi:[1,1,1]
	ds_read_b128 v[210:213], v179 offset:3136
	ds_read_b128 v[214:217], v179 offset:3152
	ds_read_b128 v[218:221], v179 offset:3168
	ds_read_b128 v[222:225], v179 offset:3184
	s_waitcnt vmcnt(47) lgkmcnt(4)
; #define LAS __attribute__((address_space(3)))
; __global__ void __launch_bounds__(NTHR, 2) hymba_fwd(Params P) {
;     ...
;             for (int kk = 0; kk < 128; ++kk) { const float wv = P.w_ada[(size_t)(wave * 128 + kk) * 3072 + col];
; #pragma unroll
;                 for (int q = 0; q < 4; ++q) { const f32x4 s = *(const LAS f32x4*)(sil + kk * 16 + 4 * q); acc[4 * q] += s[0] * wv; acc[4 * q + 1] += s[1] * wv; acc[4 * q + 2] += s[2] * wv; acc[4 * q + 3] += s[3] * wv; } }
	v_pk_fma_f32 v[226:227], v[162:163], v[180:181], v[226:227] op_sel:[0,0,0] op_sel_hi:[0,1,1]
	v_pk_fma_f32 v[228:229], v[162:163], v[182:183], v[228:229] op_sel:[0,0,0] op_sel_hi:[0,1,1]
	v_pk_fma_f32 v[230:231], v[162:163], v[184:185], v[230:231] op_sel:[0,0,0] op_sel_hi:[0,1,1]
	v_pk_fma_f32 v[232:233], v[162:163], v[186:187], v[232:233] op_sel:[0,0,0] op_sel_hi:[0,1,1]
	v_pk_fma_f32 v[234:235], v[162:163], v[188:189], v[234:235] op_sel:[0,0,0] op_sel_hi:[0,1,1]
	v_pk_fma_f32 v[236:237], v[162:163], v[190:191], v[236:237] op_sel:[0,0,0] op_sel_hi:[0,1,1]
	v_pk_fma_f32 v[238:239], v[162:163], v[192:193], v[238:239] op_sel:[0,0,0] op_sel_hi:[0,1,1]
	v_pk_fma_f32 v[240:241], v[162:163], v[194:195], v[240:241] op_sel:[0,0,0] op_sel_hi:[0,1,1]
	ds_read_b128 v[180:183], v179 offset:3200
	ds_read_b128 v[184:187], v179 offset:3216
	ds_read_b128 v[188:191], v179 offset:3232
	ds_read_b128 v[192:195], v179 offset:3248
	s_waitcnt vmcnt(46) lgkmcnt(4)
	v_pk_fma_f32 v[226:227], v[162:163], v[210:211], v[226:227] op_sel:[1,0,0] op_sel_hi:[1,1,1]
	v_pk_fma_f32 v[228:229], v[162:163], v[212:213], v[228:229] op_sel:[1,0,0] op_sel_hi:[1,1,1]
	v_pk_fma_f32 v[230:231], v[162:163], v[214:215], v[230:231] op_sel:[1,0,0] op_sel_hi:[1,1,1]
	v_pk_fma_f32 v[232:233], v[162:163], v[216:217], v[232:233] op_sel:[1,0,0] op_sel_hi:[1,1,1]
	v_pk_fma_f32 v[234:235], v[162:163], v[218:219], v[234:235] op_sel:[1,0,0] op_sel_hi:[1,1,1]
	v_pk_fma_f32 v[236:237], v[162:163], v[220:221], v[236:237] op_sel:[1,0,0] op_sel_hi:[1,1,1]
	v_pk_fma_f32 v[238:239], v[162:163], v[222:223], v[238:239] op_sel:[1,0,0] op_sel_hi:[1,1,1]
	v_pk_fma_f32 v[240:241], v[162:163], v[224:225], v[240:241] op_sel:[1,0,0] op_sel_hi:[1,1,1]
	ds_read_b128 v[210:213], v179 offset:3264
	ds_read_b128 v[214:217], v179 offset:3280
	ds_read_b128 v[218:221], v179 offset:3296
	ds_read_b128 v[222:225], v179 offset:3312
	s_waitcnt vmcnt(45) lgkmcnt(4)
	v_pk_fma_f32 v[226:227], v[164:165], v[180:181], v[226:227] op_sel:[0,0,0] op_sel_hi:[0,1,1]
	v_pk_fma_f32 v[228:229], v[164:165], v[182:183], v[228:229] op_sel:[0,0,0] op_sel_hi:[0,1,1]
	v_pk_fma_f32 v[230:231], v[164:165], v[184:185], v[230:231] op_sel:[0,0,0] op_sel_hi:[0,1,1]
	v_pk_fma_f32 v[232:233], v[164:165], v[186:187], v[232:233] op_sel:[0,0,0] op_sel_hi:[0,1,1]
	v_pk_fma_f32 v[234:235], v[164:165], v[188:189], v[234:235] op_sel:[0,0,0] op_sel_hi:[0,1,1]
	v_pk_fma_f32 v[236:237], v[164:165], v[190:191], v[236:237] op_sel:[0,0,0] op_sel_hi:[0,1,1]
	v_pk_fma_f32 v[238:239], v[164:165], v[192:193], v[238:239] op_sel:[0,0,0] op_sel_hi:[0,1,1]
	v_pk_fma_f32 v[240:241], v[164:165], v[194:195], v[240:241] op_sel:[0,0,0] op_sel_hi:[0,1,1]
	ds_read_b128 v[180:183], v179 offset:3328
	ds_read_b128 v[184:187], v179 offset:3344
	ds_read_b128 v[188:191], v179 offset:3360
	ds_read_b128 v[192:195], v179 offset:3376
	s_waitcnt vmcnt(44) lgkmcnt(4)
	v_pk_fma_f32 v[226:227], v[164:165], v[210:211], v[226:227] op_sel:[1,0,0] op_sel_hi:[1,1,1]
	v_pk_fma_f32 v[228:229], v[164:165], v[212:213], v[228:229] op_sel:[1,0,0] op_sel_hi:[1,1,1]
	v_pk_fma_f32 v[230:231], v[164:165], v[214:215], v[230:231] op_sel:[1,0,0] op_sel_hi:[1,1,1]
	v_pk_fma_f32 v[232:233], v[164:165], v[216:217], v[232:233] op_sel:[1,0,0] op_sel_hi:[1,1,1]
	v_pk_fma_f32 v[234:235], v[164:165], v[218:219], v[234:235] op_sel:[1,0,0] op_sel_hi:[1,1,1]
	v_pk_fma_f32 v[236:237], v[164:165], v[220:221], v[236:237] op_sel:[1,0,0] op_sel_hi:[1,1,1]
	v_pk_fma_f32 v[238:239], v[164:165], v[222:223], v[238:239] op_sel:[1,0,0] op_sel_hi:[1,1,1]
	v_pk_fma_f32 v[240:241], v[164:165], v[224:225], v[240:241] op_sel:[1,0,0] op_sel_hi:[1,1,1]
	ds_read_b128 v[210:213], v179 offset:3392
	ds_read_b128 v[214:217], v179 offset:3408
	ds_read_b128 v[218:221], v179 offset:3424
	ds_read_b128 v[222:225], v179 offset:3440
	s_waitcnt vmcnt(43) lgkmcnt(4)
	v_pk_fma_f32 v[226:227], v[166:167], v[180:181], v[226:227] op_sel:[0,0,0] op_sel_hi:[0,1,1]
	v_pk_fma_f32 v[228:229], v[166:167], v[182:183], v[228:229] op_sel:[0,0,0] op_sel_hi:[0,1,1]
	v_pk_fma_f32 v[230:231], v[166:167], v[184:185], v[230:231] op_sel:[0,0,0] op_sel_hi:[0,1,1]
	v_pk_fma_f32 v[232:233], v[166:167], v[186:187], v[232:233] op_sel:[0,0,0] op_sel_hi:[0,1,1]
	v_pk_fma_f32 v[234:235], v[166:167], v[188:189], v[234:235] op_sel:[0,0,0] op_sel_hi:[0,1,1]
	v_pk_fma_f32 v[236:237], v[166:167], v[190:191], v[236:237] op_sel:[0,0,0] op_sel_hi:[0,1,1]
	v_pk_fma_f32 v[238:239], v[166:167], v[192:193], v[238:239] op_sel:[0,0,0] op_sel_hi:[0,1,1]
	v_pk_fma_f32 v[240:241], v[166:167], v[194:195], v[240:241] op_sel:[0,0,0] op_sel_hi:[0,1,1]
	ds_read_b128 v[180:183], v179 offset:3456
	ds_read_b128 v[184:187], v179 offset:3472
	ds_read_b128 v[188:191], v179 offset:3488
	ds_read_b128 v[192:195], v179 offset:3504
	s_waitcnt vmcnt(42) lgkmcnt(4)
	v_pk_fma_f32 v[226:227], v[166:167], v[210:211], v[226:227] op_sel:[1,0,0] op_sel_hi:[1,1,1]
	v_pk_fma_f32 v[228:229], v[166:167], v[212:213], v[228:229] op_sel:[1,0,0] op_sel_hi:[1,1,1]
	v_pk_fma_f32 v[230:231], v[166:167], v[214:215], v[230:231] op_sel:[1,0,0] op_sel_hi:[1,1,1]
	v_pk_fma_f32 v[232:233], v[166:167], v[216:217], v[232:233] op_sel:[1,0,0] op_sel_hi:[1,1,1]
	v_pk_fma_f32 v[234:235], v[166:167], v[218:219], v[234:235] op_sel:[1,0,0] op_sel_hi:[1,1,1]
	v_pk_fma_f32 v[236:237], v[166:167], v[220:221], v[236:237] op_sel:[1,0,0] op_sel_hi:[1,1,1]
	v_pk_fma_f32 v[238:239], v[166:167], v[222:223], v[238:239] op_sel:[1,0,0] op_sel_hi:[1,1,1]
	v_pk_fma_f32 v[240:241], v[166:167], v[224:225], v[240:241] op_sel:[1,0,0] op_sel_hi:[1,1,1]
	ds_read_b128 v[210:213], v179 offset:3520
	ds_read_b128 v[214:217], v179 offset:3536
	ds_read_b128 v[218:221], v179 offset:3552
	ds_read_b128 v[222:225], v179 offset:3568
	s_waitcnt vmcnt(41) lgkmcnt(4)
; #define LAS __attribute__((address_space(3)))
; __global__ void __launch_bounds__(NTHR, 2) hymba_fwd(Params P) {
;     ...
;             for (int kk = 0; kk < 128; ++kk) { const float wv = P.w_ada[(size_t)(wave * 128 + kk) * 3072 + col];
; #pragma unroll
;                 for (int q = 0; q < 4; ++q) { const f32x4 s = *(const LAS f32x4*)(sil + kk * 16 + 4 * q); acc[4 * q] += s[0] * wv; acc[4 * q + 1] += s[1] * wv; acc[4 * q + 2] += s[2] * wv; acc[4 * q + 3] += s[3] * wv; } }
	v_pk_fma_f32 v[226:227], v[168:169], v[180:181], v[226:227] op_sel:[0,0,0] op_sel_hi:[0,1,1]
	v_pk_fma_f32 v[228:229], v[168:169], v[182:183], v[228:229] op_sel:[0,0,0] op_sel_hi:[0,1,1]
	v_pk_fma_f32 v[230:231], v[168:169], v[184:185], v[230:231] op_sel:[0,0,0] op_sel_hi:[0,1,1]
	v_pk_fma_f32 v[232:233], v[168:169], v[186:187], v[232:233] op_sel:[0,0,0] op_sel_hi:[0,1,1]
	v_pk_fma_f32 v[234:235], v[168:169], v[188:189], v[234:235] op_sel:[0,0,0] op_sel_hi:[0,1,1]
	v_pk_fma_f32 v[236:237], v[168:169], v[190:191], v[236:237] op_sel:[0,0,0] op_sel_hi:[0,1,1]
	v_pk_fma_f32 v[238:239], v[168:169], v[192:193], v[238:239] op_sel:[0,0,0] op_sel_hi:[0,1,1]
	v_pk_fma_f32 v[240:241], v[168:169], v[194:195], v[240:241] op_sel:[0,0,0] op_sel_hi:[0,1,1]
	ds_read_b128 v[180:183], v179 offset:3584
	ds_read_b128 v[184:187], v179 offset:3600
	ds_read_b128 v[188:191], v179 offset:3616
	ds_read_b128 v[192:195], v179 offset:3632
	s_waitcnt vmcnt(40) lgkmcnt(4)
	v_pk_fma_f32 v[226:227], v[168:169], v[210:211], v[226:227] op_sel:[1,0,0] op_sel_hi:[1,1,1]
	v_pk_fma_f32 v[228:229], v[168:169], v[212:213], v[228:229] op_sel:[1,0,0] op_sel_hi:[1,1,1]
	v_pk_fma_f32 v[230:231], v[168:169], v[214:215], v[230:231] op_sel:[1,0,0] op_sel_hi:[1,1,1]
	v_pk_fma_f32 v[232:233], v[168:169], v[216:217], v[232:233] op_sel:[1,0,0] op_sel_hi:[1,1,1]
	v_pk_fma_f32 v[234:235], v[168:169], v[218:219], v[234:235] op_sel:[1,0,0] op_sel_hi:[1,1,1]
	v_pk_fma_f32 v[236:237], v[168:169], v[220:221], v[236:237] op_sel:[1,0,0] op_sel_hi:[1,1,1]
	v_pk_fma_f32 v[238:239], v[168:169], v[222:223], v[238:239] op_sel:[1,0,0] op_sel_hi:[1,1,1]
	v_pk_fma_f32 v[240:241], v[168:169], v[224:225], v[240:241] op_sel:[1,0,0] op_sel_hi:[1,1,1]
	ds_read_b128 v[210:213], v179 offset:3648
	ds_read_b128 v[214:217], v179 offset:3664
	ds_read_b128 v[218:221], v179 offset:3680
	ds_read_b128 v[222:225], v179 offset:3696
	s_waitcnt vmcnt(39) lgkmcnt(4)
	v_pk_fma_f32 v[226:227], v[170:171], v[180:181], v[226:227] op_sel:[0,0,0] op_sel_hi:[0,1,1]
	v_pk_fma_f32 v[228:229], v[170:171], v[182:183], v[228:229] op_sel:[0,0,0] op_sel_hi:[0,1,1]
	v_pk_fma_f32 v[230:231], v[170:171], v[184:185], v[230:231] op_sel:[0,0,0] op_sel_hi:[0,1,1]
	v_pk_fma_f32 v[232:233], v[170:171], v[186:187], v[232:233] op_sel:[0,0,0] op_sel_hi:[0,1,1]
	v_pk_fma_f32 v[234:235], v[170:171], v[188:189], v[234:235] op_sel:[0,0,0] op_sel_hi:[0,1,1]
	v_pk_fma_f32 v[236:237], v[170:171], v[190:191], v[236:237] op_sel:[0,0,0] op_sel_hi:[0,1,1]
	v_pk_fma_f32 v[238:239], v[170:171], v[192:193], v[238:239] op_sel:[0,0,0] op_sel_hi:[0,1,1]
	v_pk_fma_f32 v[240:241], v[170:171], v[194:195], v[240:241] op_sel:[0,0,0] op_sel_hi:[0,1,1]
	ds_read_b128 v[180:183], v179 offset:3712
	ds_read_b128 v[184:187], v179 offset:3728
	ds_read_b128 v[188:191], v179 offset:3744
	ds_read_b128 v[192:195], v179 offset:3760
	s_waitcnt vmcnt(38) lgkmcnt(4)
	v_pk_fma_f32 v[226:227], v[170:171], v[210:211], v[226:227] op_sel:[1,0,0] op_sel_hi:[1,1,1]
	v_pk_fma_f32 v[228:229], v[170:171], v[212:213], v[228:229] op_sel:[1,0,0] op_sel_hi:[1,1,1]
	v_pk_fma_f32 v[230:231], v[170:171], v[214:215], v[230:231] op_sel:[1,0,0] op_sel_hi:[1,1,1]
	v_pk_fma_f32 v[232:233], v[170:171], v[216:217], v[232:233] op_sel:[1,0,0] op_sel_hi:[1,1,1]
	v_pk_fma_f32 v[234:235], v[170:171], v[218:219], v[234:235] op_sel:[1,0,0] op_sel_hi:[1,1,1]
	v_pk_fma_f32 v[236:237], v[170:171], v[220:221], v[236:237] op_sel:[1,0,0] op_sel_hi:[1,1,1]
	v_pk_fma_f32 v[238:239], v[170:171], v[222:223], v[238:239] op_sel:[1,0,0] op_sel_hi:[1,1,1]
	v_pk_fma_f32 v[240:241], v[170:171], v[224:225], v[240:241] op_sel:[1,0,0] op_sel_hi:[1,1,1]
	ds_read_b128 v[210:213], v179 offset:3776
	ds_read_b128 v[214:217], v179 offset:3792
	ds_read_b128 v[218:221], v179 offset:3808
	ds_read_b128 v[222:225], v179 offset:3824
	s_waitcnt vmcnt(37) lgkmcnt(4)
	v_pk_fma_f32 v[226:227], v[172:173], v[180:181], v[226:227] op_sel:[0,0,0] op_sel_hi:[0,1,1]
	v_pk_fma_f32 v[228:229], v[172:173], v[182:183], v[228:229] op_sel:[0,0,0] op_sel_hi:[0,1,1]
	v_pk_fma_f32 v[230:231], v[172:173], v[184:185], v[230:231] op_sel:[0,0,0] op_sel_hi:[0,1,1]
	v_pk_fma_f32 v[232:233], v[172:173], v[186:187], v[232:233] op_sel:[0,0,0] op_sel_hi:[0,1,1]
	v_pk_fma_f32 v[234:235], v[172:173], v[188:189], v[234:235] op_sel:[0,0,0] op_sel_hi:[0,1,1]
	v_pk_fma_f32 v[236:237], v[172:173], v[190:191], v[236:237] op_sel:[0,0,0] op_sel_hi:[0,1,1]
	v_pk_fma_f32 v[238:239], v[172:173], v[192:193], v[238:239] op_sel:[0,0,0] op_sel_hi:[0,1,1]
	v_pk_fma_f32 v[240:241], v[172:173], v[194:195], v[240:241] op_sel:[0,0,0] op_sel_hi:[0,1,1]
	ds_read_b128 v[180:183], v179 offset:3840
	ds_read_b128 v[184:187], v179 offset:3856
	ds_read_b128 v[188:191], v179 offset:3872
	ds_read_b128 v[192:195], v179 offset:3888
	s_waitcnt vmcnt(36) lgkmcnt(4)
	v_pk_fma_f32 v[226:227], v[172:173], v[210:211], v[226:227] op_sel:[1,0,0] op_sel_hi:[1,1,1]
	v_pk_fma_f32 v[228:229], v[172:173], v[212:213], v[228:229] op_sel:[1,0,0] op_sel_hi:[1,1,1]
	v_pk_fma_f32 v[230:231], v[172:173], v[214:215], v[230:231] op_sel:[1,0,0] op_sel_hi:[1,1,1]
	v_pk_fma_f32 v[232:233], v[172:173], v[216:217], v[232:233] op_sel:[1,0,0] op_sel_hi:[1,1,1]
	v_pk_fma_f32 v[234:235], v[172:173], v[218:219], v[234:235] op_sel:[1,0,0] op_sel_hi:[1,1,1]
	v_pk_fma_f32 v[236:237], v[172:173], v[220:221], v[236:237] op_sel:[1,0,0] op_sel_hi:[1,1,1]
	v_pk_fma_f32 v[238:239], v[172:173], v[222:223], v[238:239] op_sel:[1,0,0] op_sel_hi:[1,1,1]
	v_pk_fma_f32 v[240:241], v[172:173], v[224:225], v[240:241] op_sel:[1,0,0] op_sel_hi:[1,1,1]
	ds_read_b128 v[210:213], v179 offset:3904
	ds_read_b128 v[214:217], v179 offset:3920
	ds_read_b128 v[218:221], v179 offset:3936
	ds_read_b128 v[222:225], v179 offset:3952
	s_waitcnt vmcnt(35) lgkmcnt(4)
; #define LAS __attribute__((address_space(3)))
; __global__ void __launch_bounds__(NTHR, 2) hymba_fwd(Params P) {
;     ...
;             for (int kk = 0; kk < 128; ++kk) { const float wv = P.w_ada[(size_t)(wave * 128 + kk) * 3072 + col];
; #pragma unroll
;                 for (int q = 0; q < 4; ++q) { const f32x4 s = *(const LAS f32x4*)(sil + kk * 16 + 4 * q); acc[4 * q] += s[0] * wv; acc[4 * q + 1] += s[1] * wv; acc[4 * q + 2] += s[2] * wv; acc[4 * q + 3] += s[3] * wv; } }
	v_pk_fma_f32 v[226:227], v[174:175], v[180:181], v[226:227] op_sel:[0,0,0] op_sel_hi:[0,1,1]
	v_pk_fma_f32 v[228:229], v[174:175], v[182:183], v[228:229] op_sel:[0,0,0] op_sel_hi:[0,1,1]
	v_pk_fma_f32 v[230:231], v[174:175], v[184:185], v[230:231] op_sel:[0,0,0] op_sel_hi:[0,1,1]
	v_pk_fma_f32 v[232:233], v[174:175], v[186:187], v[232:233] op_sel:[0,0,0] op_sel_hi:[0,1,1]
	v_pk_fma_f32 v[234:235], v[174:175], v[188:189], v[234:235] op_sel:[0,0,0] op_sel_hi:[0,1,1]
	v_pk_fma_f32 v[236:237], v[174:175], v[190:191], v[236:237] op_sel:[0,0,0] op_sel_hi:[0,1,1]
	v_pk_fma_f32 v[238:239], v[174:175], v[192:193], v[238:239] op_sel:[0,0,0] op_sel_hi:[0,1,1]
	v_pk_fma_f32 v[240:241], v[174:175], v[194:195], v[240:241] op_sel:[0,0,0] op_sel_hi:[0,1,1]
	ds_read_b128 v[180:183], v179 offset:3968
	ds_read_b128 v[184:187], v179 offset:3984
	ds_read_b128 v[188:191], v179 offset:4000
	ds_read_b128 v[192:195], v179 offset:4016
	s_waitcnt vmcnt(34) lgkmcnt(4)
	v_pk_fma_f32 v[226:227], v[174:175], v[210:211], v[226:227] op_sel:[1,0,0] op_sel_hi:[1,1,1]
	v_pk_fma_f32 v[228:229], v[174:175], v[212:213], v[228:229] op_sel:[1,0,0] op_sel_hi:[1,1,1]
	v_pk_fma_f32 v[230:231], v[174:175], v[214:215], v[230:231] op_sel:[1,0,0] op_sel_hi:[1,1,1]
	v_pk_fma_f32 v[232:233], v[174:175], v[216:217], v[232:233] op_sel:[1,0,0] op_sel_hi:[1,1,1]
	v_pk_fma_f32 v[234:235], v[174:175], v[218:219], v[234:235] op_sel:[1,0,0] op_sel_hi:[1,1,1]
	v_pk_fma_f32 v[236:237], v[174:175], v[220:221], v[236:237] op_sel:[1,0,0] op_sel_hi:[1,1,1]
	v_pk_fma_f32 v[238:239], v[174:175], v[222:223], v[238:239] op_sel:[1,0,0] op_sel_hi:[1,1,1]
	v_pk_fma_f32 v[240:241], v[174:175], v[224:225], v[240:241] op_sel:[1,0,0] op_sel_hi:[1,1,1]
	ds_read_b128 v[210:213], v179 offset:4032
	ds_read_b128 v[214:217], v179 offset:4048
	ds_read_b128 v[218:221], v179 offset:4064
	ds_read_b128 v[222:225], v179 offset:4080
	s_waitcnt vmcnt(33) lgkmcnt(4)
	v_pk_fma_f32 v[226:227], v[176:177], v[180:181], v[226:227] op_sel:[0,0,0] op_sel_hi:[0,1,1]
	v_pk_fma_f32 v[228:229], v[176:177], v[182:183], v[228:229] op_sel:[0,0,0] op_sel_hi:[0,1,1]
	v_pk_fma_f32 v[230:231], v[176:177], v[184:185], v[230:231] op_sel:[0,0,0] op_sel_hi:[0,1,1]
	v_pk_fma_f32 v[232:233], v[176:177], v[186:187], v[232:233] op_sel:[0,0,0] op_sel_hi:[0,1,1]
	v_pk_fma_f32 v[234:235], v[176:177], v[188:189], v[234:235] op_sel:[0,0,0] op_sel_hi:[0,1,1]
	v_pk_fma_f32 v[236:237], v[176:177], v[190:191], v[236:237] op_sel:[0,0,0] op_sel_hi:[0,1,1]
	v_pk_fma_f32 v[238:239], v[176:177], v[192:193], v[238:239] op_sel:[0,0,0] op_sel_hi:[0,1,1]
	v_pk_fma_f32 v[240:241], v[176:177], v[194:195], v[240:241] op_sel:[0,0,0] op_sel_hi:[0,1,1]
	ds_read_b128 v[180:183], v179 offset:4096
	ds_read_b128 v[184:187], v179 offset:4112
	ds_read_b128 v[188:191], v179 offset:4128
	ds_read_b128 v[192:195], v179 offset:4144
	s_waitcnt vmcnt(32) lgkmcnt(4)
	v_pk_fma_f32 v[226:227], v[176:177], v[210:211], v[226:227] op_sel:[1,0,0] op_sel_hi:[1,1,1]
	v_pk_fma_f32 v[228:229], v[176:177], v[212:213], v[228:229] op_sel:[1,0,0] op_sel_hi:[1,1,1]
	v_pk_fma_f32 v[230:231], v[176:177], v[214:215], v[230:231] op_sel:[1,0,0] op_sel_hi:[1,1,1]
	v_pk_fma_f32 v[232:233], v[176:177], v[216:217], v[232:233] op_sel:[1,0,0] op_sel_hi:[1,1,1]
	v_pk_fma_f32 v[234:235], v[176:177], v[218:219], v[234:235] op_sel:[1,0,0] op_sel_hi:[1,1,1]
	v_pk_fma_f32 v[236:237], v[176:177], v[220:221], v[236:237] op_sel:[1,0,0] op_sel_hi:[1,1,1]
	v_pk_fma_f32 v[238:239], v[176:177], v[222:223], v[238:239] op_sel:[1,0,0] op_sel_hi:[1,1,1]
	v_pk_fma_f32 v[240:241], v[176:177], v[224:225], v[240:241] op_sel:[1,0,0] op_sel_hi:[1,1,1]
	global_load_dword v146, v242, s[0:1]
	s_add_u32 s0, s0, 0x3000
	s_addc_u32 s1, s1, 0
	global_load_dword v147, v242, s[0:1]
	s_add_u32 s0, s0, 0x3000
	s_addc_u32 s1, s1, 0
	global_load_dword v148, v242, s[0:1]
	s_add_u32 s0, s0, 0x3000
	s_addc_u32 s1, s1, 0
	global_load_dword v149, v242, s[0:1]
	s_add_u32 s0, s0, 0x3000
	s_addc_u32 s1, s1, 0
	global_load_dword v150, v242, s[0:1]
	s_add_u32 s0, s0, 0x3000
	s_addc_u32 s1, s1, 0
	global_load_dword v151, v242, s[0:1]
	s_add_u32 s0, s0, 0x3000
	s_addc_u32 s1, s1, 0
	global_load_dword v152, v242, s[0:1]
	s_add_u32 s0, s0, 0x3000
	s_addc_u32 s1, s1, 0
	global_load_dword v153, v242, s[0:1]
	s_add_u32 s0, s0, 0x3000
	s_addc_u32 s1, s1, 0
	global_load_dword v154, v242, s[0:1]
	s_add_u32 s0, s0, 0x3000
	s_addc_u32 s1, s1, 0
	global_load_dword v155, v242, s[0:1]
	s_add_u32 s0, s0, 0x3000
	s_addc_u32 s1, s1, 0
	global_load_dword v156, v242, s[0:1]
	s_add_u32 s0, s0, 0x3000
	s_addc_u32 s1, s1, 0
	global_load_dword v157, v242, s[0:1]
	s_add_u32 s0, s0, 0x3000
	s_addc_u32 s1, s1, 0
	global_load_dword v158, v242, s[0:1]
	s_add_u32 s0, s0, 0x3000
	s_addc_u32 s1, s1, 0
	global_load_dword v159, v242, s[0:1]
	s_add_u32 s0, s0, 0x3000
	s_addc_u32 s1, s1, 0
	global_load_dword v160, v242, s[0:1]
	s_add_u32 s0, s0, 0x3000
	s_addc_u32 s1, s1, 0
	global_load_dword v161, v242, s[0:1]
	s_add_u32 s0, s0, 0x3000
	s_addc_u32 s1, s1, 0
	global_load_dword v162, v242, s[0:1]
	s_add_u32 s0, s0, 0x3000
	s_addc_u32 s1, s1, 0
	global_load_dword v163, v242, s[0:1]
	s_add_u32 s0, s0, 0x3000
	s_addc_u32 s1, s1, 0
	global_load_dword v164, v242, s[0:1]
	s_add_u32 s0, s0, 0x3000
	s_addc_u32 s1, s1, 0
	global_load_dword v165, v242, s[0:1]
	s_add_u32 s0, s0, 0x3000
	s_addc_u32 s1, s1, 0
	global_load_dword v166, v242, s[0:1]
	s_add_u32 s0, s0, 0x3000
	s_addc_u32 s1, s1, 0
	global_load_dword v167, v242, s[0:1]
	s_add_u32 s0, s0, 0x3000
	s_addc_u32 s1, s1, 0
	global_load_dword v168, v242, s[0:1]
	s_add_u32 s0, s0, 0x3000
	s_addc_u32 s1, s1, 0
	global_load_dword v169, v242, s[0:1]
	s_add_u32 s0, s0, 0x3000
	s_addc_u32 s1, s1, 0
	global_load_dword v170, v242, s[0:1]
	s_add_u32 s0, s0, 0x3000
	s_addc_u32 s1, s1, 0
	global_load_dword v171, v242, s[0:1]
	s_add_u32 s0, s0, 0x3000
	s_addc_u32 s1, s1, 0
	global_load_dword v172, v242, s[0:1]
	s_add_u32 s0, s0, 0x3000
	s_addc_u32 s1, s1, 0
	global_load_dword v173, v242, s[0:1]
	s_add_u32 s0, s0, 0x3000
	s_addc_u32 s1, s1, 0
	global_load_dword v174, v242, s[0:1]
	s_add_u32 s0, s0, 0x3000
	s_addc_u32 s1, s1, 0
	global_load_dword v175, v242, s[0:1]
	s_add_u32 s0, s0, 0x3000
	s_addc_u32 s1, s1, 0
	global_load_dword v176, v242, s[0:1]
	s_add_u32 s0, s0, 0x3000
	s_addc_u32 s1, s1, 0
	global_load_dword v177, v242, s[0:1]
	s_add_u32 s0, s0, 0x3000
	s_addc_u32 s1, s1, 0
	ds_read_b128 v[210:213], v179 offset:4160
	ds_read_b128 v[214:217], v179 offset:4176
	ds_read_b128 v[218:221], v179 offset:4192
	ds_read_b128 v[222:225], v179 offset:4208
	s_waitcnt vmcnt(63) lgkmcnt(4)
; #define LAS __attribute__((address_space(3)))
; __global__ void __launch_bounds__(NTHR, 2) hymba_fwd(Params P) {
;     ...
;             for (int kk = 0; kk < 128; ++kk) { const float wv = P.w_ada[(size_t)(wave * 128 + kk) * 3072 + col];
; #pragma unroll
;                 for (int q = 0; q < 4; ++q) { const f32x4 s = *(const LAS f32x4*)(sil + kk * 16 + 4 * q); acc[4 * q] += s[0] * wv; acc[4 * q + 1] += s[1] * wv; acc[4 * q + 2] += s[2] * wv; acc[4 * q + 3] += s[3] * wv; } }
	v_pk_fma_f32 v[226:227], v[114:115], v[180:181], v[226:227] op_sel:[0,0,0] op_sel_hi:[0,1,1]
	v_pk_fma_f32 v[228:229], v[114:115], v[182:183], v[228:229] op_sel:[0,0,0] op_sel_hi:[0,1,1]
	v_pk_fma_f32 v[230:231], v[114:115], v[184:185], v[230:231] op_sel:[0,0,0] op_sel_hi:[0,1,1]
	v_pk_fma_f32 v[232:233], v[114:115], v[186:187], v[232:233] op_sel:[0,0,0] op_sel_hi:[0,1,1]
	v_pk_fma_f32 v[234:235], v[114:115], v[188:189], v[234:235] op_sel:[0,0,0] op_sel_hi:[0,1,1]
	v_pk_fma_f32 v[236:237], v[114:115], v[190:191], v[236:237] op_sel:[0,0,0] op_sel_hi:[0,1,1]
	v_pk_fma_f32 v[238:239], v[114:115], v[192:193], v[238:239] op_sel:[0,0,0] op_sel_hi:[0,1,1]
	v_pk_fma_f32 v[240:241], v[114:115], v[194:195], v[240:241] op_sel:[0,0,0] op_sel_hi:[0,1,1]
	ds_read_b128 v[180:183], v179 offset:4224
	ds_read_b128 v[184:187], v179 offset:4240
	ds_read_b128 v[188:191], v179 offset:4256
	ds_read_b128 v[192:195], v179 offset:4272
	s_waitcnt vmcnt(62) lgkmcnt(4)
	v_pk_fma_f32 v[226:227], v[114:115], v[210:211], v[226:227] op_sel:[1,0,0] op_sel_hi:[1,1,1]
	v_pk_fma_f32 v[228:229], v[114:115], v[212:213], v[228:229] op_sel:[1,0,0] op_sel_hi:[1,1,1]
	v_pk_fma_f32 v[230:231], v[114:115], v[214:215], v[230:231] op_sel:[1,0,0] op_sel_hi:[1,1,1]
	v_pk_fma_f32 v[232:233], v[114:115], v[216:217], v[232:233] op_sel:[1,0,0] op_sel_hi:[1,1,1]
	v_pk_fma_f32 v[234:235], v[114:115], v[218:219], v[234:235] op_sel:[1,0,0] op_sel_hi:[1,1,1]
	v_pk_fma_f32 v[236:237], v[114:115], v[220:221], v[236:237] op_sel:[1,0,0] op_sel_hi:[1,1,1]
	v_pk_fma_f32 v[238:239], v[114:115], v[222:223], v[238:239] op_sel:[1,0,0] op_sel_hi:[1,1,1]
	v_pk_fma_f32 v[240:241], v[114:115], v[224:225], v[240:241] op_sel:[1,0,0] op_sel_hi:[1,1,1]
	ds_read_b128 v[210:213], v179 offset:4288
	ds_read_b128 v[214:217], v179 offset:4304
	ds_read_b128 v[218:221], v179 offset:4320
	ds_read_b128 v[222:225], v179 offset:4336
	s_waitcnt vmcnt(61) lgkmcnt(4)
	v_pk_fma_f32 v[226:227], v[116:117], v[180:181], v[226:227] op_sel:[0,0,0] op_sel_hi:[0,1,1]
	v_pk_fma_f32 v[228:229], v[116:117], v[182:183], v[228:229] op_sel:[0,0,0] op_sel_hi:[0,1,1]
	v_pk_fma_f32 v[230:231], v[116:117], v[184:185], v[230:231] op_sel:[0,0,0] op_sel_hi:[0,1,1]
	v_pk_fma_f32 v[232:233], v[116:117], v[186:187], v[232:233] op_sel:[0,0,0] op_sel_hi:[0,1,1]
	v_pk_fma_f32 v[234:235], v[116:117], v[188:189], v[234:235] op_sel:[0,0,0] op_sel_hi:[0,1,1]
	v_pk_fma_f32 v[236:237], v[116:117], v[190:191], v[236:237] op_sel:[0,0,0] op_sel_hi:[0,1,1]
	v_pk_fma_f32 v[238:239], v[116:117], v[192:193], v[238:239] op_sel:[0,0,0] op_sel_hi:[0,1,1]
	v_pk_fma_f32 v[240:241], v[116:117], v[194:195], v[240:241] op_sel:[0,0,0] op_sel_hi:[0,1,1]
	ds_read_b128 v[180:183], v179 offset:4352
	ds_read_b128 v[184:187], v179 offset:4368
	ds_read_b128 v[188:191], v179 offset:4384
	ds_read_b128 v[192:195], v179 offset:4400
	s_waitcnt vmcnt(60) lgkmcnt(4)
	v_pk_fma_f32 v[226:227], v[116:117], v[210:211], v[226:227] op_sel:[1,0,0] op_sel_hi:[1,1,1]
	v_pk_fma_f32 v[228:229], v[116:117], v[212:213], v[228:229] op_sel:[1,0,0] op_sel_hi:[1,1,1]
	v_pk_fma_f32 v[230:231], v[116:117], v[214:215], v[230:231] op_sel:[1,0,0] op_sel_hi:[1,1,1]
	v_pk_fma_f32 v[232:233], v[116:117], v[216:217], v[232:233] op_sel:[1,0,0] op_sel_hi:[1,1,1]
	v_pk_fma_f32 v[234:235], v[116:117], v[218:219], v[234:235] op_sel:[1,0,0] op_sel_hi:[1,1,1]
	v_pk_fma_f32 v[236:237], v[116:117], v[220:221], v[236:237] op_sel:[1,0,0] op_sel_hi:[1,1,1]
	v_pk_fma_f32 v[238:239], v[116:117], v[222:223], v[238:239] op_sel:[1,0,0] op_sel_hi:[1,1,1]
	v_pk_fma_f32 v[240:241], v[116:117], v[224:225], v[240:241] op_sel:[1,0,0] op_sel_hi:[1,1,1]
	ds_read_b128 v[210:213], v179 offset:4416
	ds_read_b128 v[214:217], v179 offset:4432
	ds_read_b128 v[218:221], v179 offset:4448
	ds_read_b128 v[222:225], v179 offset:4464
	s_waitcnt vmcnt(59) lgkmcnt(4)
	v_pk_fma_f32 v[226:227], v[118:119], v[180:181], v[226:227] op_sel:[0,0,0] op_sel_hi:[0,1,1]
	v_pk_fma_f32 v[228:229], v[118:119], v[182:183], v[228:229] op_sel:[0,0,0] op_sel_hi:[0,1,1]
	v_pk_fma_f32 v[230:231], v[118:119], v[184:185], v[230:231] op_sel:[0,0,0] op_sel_hi:[0,1,1]
	v_pk_fma_f32 v[232:233], v[118:119], v[186:187], v[232:233] op_sel:[0,0,0] op_sel_hi:[0,1,1]
	v_pk_fma_f32 v[234:235], v[118:119], v[188:189], v[234:235] op_sel:[0,0,0] op_sel_hi:[0,1,1]
	v_pk_fma_f32 v[236:237], v[118:119], v[190:191], v[236:237] op_sel:[0,0,0] op_sel_hi:[0,1,1]
	v_pk_fma_f32 v[238:239], v[118:119], v[192:193], v[238:239] op_sel:[0,0,0] op_sel_hi:[0,1,1]
	v_pk_fma_f32 v[240:241], v[118:119], v[194:195], v[240:241] op_sel:[0,0,0] op_sel_hi:[0,1,1]
	ds_read_b128 v[180:183], v179 offset:4480
	ds_read_b128 v[184:187], v179 offset:4496
	ds_read_b128 v[188:191], v179 offset:4512
	ds_read_b128 v[192:195], v179 offset:4528
	s_waitcnt vmcnt(58) lgkmcnt(4)
	v_pk_fma_f32 v[226:227], v[118:119], v[210:211], v[226:227] op_sel:[1,0,0] op_sel_hi:[1,1,1]
	v_pk_fma_f32 v[228:229], v[118:119], v[212:213], v[228:229] op_sel:[1,0,0] op_sel_hi:[1,1,1]
	v_pk_fma_f32 v[230:231], v[118:119], v[214:215], v[230:231] op_sel:[1,0,0] op_sel_hi:[1,1,1]
	v_pk_fma_f32 v[232:233], v[118:119], v[216:217], v[232:233] op_sel:[1,0,0] op_sel_hi:[1,1,1]
	v_pk_fma_f32 v[234:235], v[118:119], v[218:219], v[234:235] op_sel:[1,0,0] op_sel_hi:[1,1,1]
	v_pk_fma_f32 v[236:237], v[118:119], v[220:221], v[236:237] op_sel:[1,0,0] op_sel_hi:[1,1,1]
	v_pk_fma_f32 v[238:239], v[118:119], v[222:223], v[238:239] op_sel:[1,0,0] op_sel_hi:[1,1,1]
	v_pk_fma_f32 v[240:241], v[118:119], v[224:225], v[240:241] op_sel:[1,0,0] op_sel_hi:[1,1,1]
	ds_read_b128 v[210:213], v179 offset:4544
	ds_read_b128 v[214:217], v179 offset:4560
	ds_read_b128 v[218:221], v179 offset:4576
	ds_read_b128 v[222:225], v179 offset:4592
	s_waitcnt vmcnt(57) lgkmcnt(4)
; #define LAS __attribute__((address_space(3)))
; __global__ void __launch_bounds__(NTHR, 2) hymba_fwd(Params P) {
;     ...
;             for (int kk = 0; kk < 128; ++kk) { const float wv = P.w_ada[(size_t)(wave * 128 + kk) * 3072 + col];
; #pragma unroll
;                 for (int q = 0; q < 4; ++q) { const f32x4 s = *(const LAS f32x4*)(sil + kk * 16 + 4 * q); acc[4 * q] += s[0] * wv; acc[4 * q + 1] += s[1] * wv; acc[4 * q + 2] += s[2] * wv; acc[4 * q + 3] += s[3] * wv; } }
	v_pk_fma_f32 v[226:227], v[120:121], v[180:181], v[226:227] op_sel:[0,0,0] op_sel_hi:[0,1,1]
	v_pk_fma_f32 v[228:229], v[120:121], v[182:183], v[228:229] op_sel:[0,0,0] op_sel_hi:[0,1,1]
	v_pk_fma_f32 v[230:231], v[120:121], v[184:185], v[230:231] op_sel:[0,0,0] op_sel_hi:[0,1,1]
	v_pk_fma_f32 v[232:233], v[120:121], v[186:187], v[232:233] op_sel:[0,0,0] op_sel_hi:[0,1,1]
	v_pk_fma_f32 v[234:235], v[120:121], v[188:189], v[234:235] op_sel:[0,0,0] op_sel_hi:[0,1,1]
	v_pk_fma_f32 v[236:237], v[120:121], v[190:191], v[236:237] op_sel:[0,0,0] op_sel_hi:[0,1,1]
	v_pk_fma_f32 v[238:239], v[120:121], v[192:193], v[238:239] op_sel:[0,0,0] op_sel_hi:[0,1,1]
	v_pk_fma_f32 v[240:241], v[120:121], v[194:195], v[240:241] op_sel:[0,0,0] op_sel_hi:[0,1,1]
	ds_read_b128 v[180:183], v179 offset:4608
	ds_read_b128 v[184:187], v179 offset:4624
	ds_read_b128 v[188:191], v179 offset:4640
	ds_read_b128 v[192:195], v179 offset:4656
	s_waitcnt vmcnt(56) lgkmcnt(4)
	v_pk_fma_f32 v[226:227], v[120:121], v[210:211], v[226:227] op_sel:[1,0,0] op_sel_hi:[1,1,1]
	v_pk_fma_f32 v[228:229], v[120:121], v[212:213], v[228:229] op_sel:[1,0,0] op_sel_hi:[1,1,1]
	v_pk_fma_f32 v[230:231], v[120:121], v[214:215], v[230:231] op_sel:[1,0,0] op_sel_hi:[1,1,1]
	v_pk_fma_f32 v[232:233], v[120:121], v[216:217], v[232:233] op_sel:[1,0,0] op_sel_hi:[1,1,1]
	v_pk_fma_f32 v[234:235], v[120:121], v[218:219], v[234:235] op_sel:[1,0,0] op_sel_hi:[1,1,1]
	v_pk_fma_f32 v[236:237], v[120:121], v[220:221], v[236:237] op_sel:[1,0,0] op_sel_hi:[1,1,1]
	v_pk_fma_f32 v[238:239], v[120:121], v[222:223], v[238:239] op_sel:[1,0,0] op_sel_hi:[1,1,1]
	v_pk_fma_f32 v[240:241], v[120:121], v[224:225], v[240:241] op_sel:[1,0,0] op_sel_hi:[1,1,1]
	ds_read_b128 v[210:213], v179 offset:4672
	ds_read_b128 v[214:217], v179 offset:4688
	ds_read_b128 v[218:221], v179 offset:4704
	ds_read_b128 v[222:225], v179 offset:4720
	s_waitcnt vmcnt(55) lgkmcnt(4)
	v_pk_fma_f32 v[226:227], v[122:123], v[180:181], v[226:227] op_sel:[0,0,0] op_sel_hi:[0,1,1]
	v_pk_fma_f32 v[228:229], v[122:123], v[182:183], v[228:229] op_sel:[0,0,0] op_sel_hi:[0,1,1]
	v_pk_fma_f32 v[230:231], v[122:123], v[184:185], v[230:231] op_sel:[0,0,0] op_sel_hi:[0,1,1]
	v_pk_fma_f32 v[232:233], v[122:123], v[186:187], v[232:233] op_sel:[0,0,0] op_sel_hi:[0,1,1]
	v_pk_fma_f32 v[234:235], v[122:123], v[188:189], v[234:235] op_sel:[0,0,0] op_sel_hi:[0,1,1]
	v_pk_fma_f32 v[236:237], v[122:123], v[190:191], v[236:237] op_sel:[0,0,0] op_sel_hi:[0,1,1]
	v_pk_fma_f32 v[238:239], v[122:123], v[192:193], v[238:239] op_sel:[0,0,0] op_sel_hi:[0,1,1]
	v_pk_fma_f32 v[240:241], v[122:123], v[194:195], v[240:241] op_sel:[0,0,0] op_sel_hi:[0,1,1]
	ds_read_b128 v[180:183], v179 offset:4736
	ds_read_b128 v[184:187], v179 offset:4752
	ds_read_b128 v[188:191], v179 offset:4768
	ds_read_b128 v[192:195], v179 offset:4784
	s_waitcnt vmcnt(54) lgkmcnt(4)
	v_pk_fma_f32 v[226:227], v[122:123], v[210:211], v[226:227] op_sel:[1,0,0] op_sel_hi:[1,1,1]
	v_pk_fma_f32 v[228:229], v[122:123], v[212:213], v[228:229] op_sel:[1,0,0] op_sel_hi:[1,1,1]
	v_pk_fma_f32 v[230:231], v[122:123], v[214:215], v[230:231] op_sel:[1,0,0] op_sel_hi:[1,1,1]
	v_pk_fma_f32 v[232:233], v[122:123], v[216:217], v[232:233] op_sel:[1,0,0] op_sel_hi:[1,1,1]
	v_pk_fma_f32 v[234:235], v[122:123], v[218:219], v[234:235] op_sel:[1,0,0] op_sel_hi:[1,1,1]
	v_pk_fma_f32 v[236:237], v[122:123], v[220:221], v[236:237] op_sel:[1,0,0] op_sel_hi:[1,1,1]
	v_pk_fma_f32 v[238:239], v[122:123], v[222:223], v[238:239] op_sel:[1,0,0] op_sel_hi:[1,1,1]
	v_pk_fma_f32 v[240:241], v[122:123], v[224:225], v[240:241] op_sel:[1,0,0] op_sel_hi:[1,1,1]
	ds_read_b128 v[210:213], v179 offset:4800
	ds_read_b128 v[214:217], v179 offset:4816
	ds_read_b128 v[218:221], v179 offset:4832
	ds_read_b128 v[222:225], v179 offset:4848
	s_waitcnt vmcnt(53) lgkmcnt(4)
	v_pk_fma_f32 v[226:227], v[124:125], v[180:181], v[226:227] op_sel:[0,0,0] op_sel_hi:[0,1,1]
	v_pk_fma_f32 v[228:229], v[124:125], v[182:183], v[228:229] op_sel:[0,0,0] op_sel_hi:[0,1,1]
	v_pk_fma_f32 v[230:231], v[124:125], v[184:185], v[230:231] op_sel:[0,0,0] op_sel_hi:[0,1,1]
	v_pk_fma_f32 v[232:233], v[124:125], v[186:187], v[232:233] op_sel:[0,0,0] op_sel_hi:[0,1,1]
	v_pk_fma_f32 v[234:235], v[124:125], v[188:189], v[234:235] op_sel:[0,0,0] op_sel_hi:[0,1,1]
	v_pk_fma_f32 v[236:237], v[124:125], v[190:191], v[236:237] op_sel:[0,0,0] op_sel_hi:[0,1,1]
	v_pk_fma_f32 v[238:239], v[124:125], v[192:193], v[238:239] op_sel:[0,0,0] op_sel_hi:[0,1,1]
	v_pk_fma_f32 v[240:241], v[124:125], v[194:195], v[240:241] op_sel:[0,0,0] op_sel_hi:[0,1,1]
	ds_read_b128 v[180:183], v179 offset:4864
	ds_read_b128 v[184:187], v179 offset:4880
	ds_read_b128 v[188:191], v179 offset:4896
	ds_read_b128 v[192:195], v179 offset:4912
	s_waitcnt vmcnt(52) lgkmcnt(4)
	v_pk_fma_f32 v[226:227], v[124:125], v[210:211], v[226:227] op_sel:[1,0,0] op_sel_hi:[1,1,1]
	v_pk_fma_f32 v[228:229], v[124:125], v[212:213], v[228:229] op_sel:[1,0,0] op_sel_hi:[1,1,1]
	v_pk_fma_f32 v[230:231], v[124:125], v[214:215], v[230:231] op_sel:[1,0,0] op_sel_hi:[1,1,1]
	v_pk_fma_f32 v[232:233], v[124:125], v[216:217], v[232:233] op_sel:[1,0,0] op_sel_hi:[1,1,1]
	v_pk_fma_f32 v[234:235], v[124:125], v[218:219], v[234:235] op_sel:[1,0,0] op_sel_hi:[1,1,1]
	v_pk_fma_f32 v[236:237], v[124:125], v[220:221], v[236:237] op_sel:[1,0,0] op_sel_hi:[1,1,1]
	v_pk_fma_f32 v[238:239], v[124:125], v[222:223], v[238:239] op_sel:[1,0,0] op_sel_hi:[1,1,1]
	v_pk_fma_f32 v[240:241], v[124:125], v[224:225], v[240:241] op_sel:[1,0,0] op_sel_hi:[1,1,1]
	ds_read_b128 v[210:213], v179 offset:4928
	ds_read_b128 v[214:217], v179 offset:4944
	ds_read_b128 v[218:221], v179 offset:4960
	ds_read_b128 v[222:225], v179 offset:4976
	s_waitcnt vmcnt(51) lgkmcnt(4)
; #define LAS __attribute__((address_space(3)))
; __global__ void __launch_bounds__(NTHR, 2) hymba_fwd(Params P) {
;     ...
;             for (int kk = 0; kk < 128; ++kk) { const float wv = P.w_ada[(size_t)(wave * 128 + kk) * 3072 + col];
; #pragma unroll
;                 for (int q = 0; q < 4; ++q) { const f32x4 s = *(const LAS f32x4*)(sil + kk * 16 + 4 * q); acc[4 * q] += s[0] * wv; acc[4 * q + 1] += s[1] * wv; acc[4 * q + 2] += s[2] * wv; acc[4 * q + 3] += s[3] * wv; } }
	v_pk_fma_f32 v[226:227], v[126:127], v[180:181], v[226:227] op_sel:[0,0,0] op_sel_hi:[0,1,1]
	v_pk_fma_f32 v[228:229], v[126:127], v[182:183], v[228:229] op_sel:[0,0,0] op_sel_hi:[0,1,1]
	v_pk_fma_f32 v[230:231], v[126:127], v[184:185], v[230:231] op_sel:[0,0,0] op_sel_hi:[0,1,1]
	v_pk_fma_f32 v[232:233], v[126:127], v[186:187], v[232:233] op_sel:[0,0,0] op_sel_hi:[0,1,1]
	v_pk_fma_f32 v[234:235], v[126:127], v[188:189], v[234:235] op_sel:[0,0,0] op_sel_hi:[0,1,1]
	v_pk_fma_f32 v[236:237], v[126:127], v[190:191], v[236:237] op_sel:[0,0,0] op_sel_hi:[0,1,1]
	v_pk_fma_f32 v[238:239], v[126:127], v[192:193], v[238:239] op_sel:[0,0,0] op_sel_hi:[0,1,1]
	v_pk_fma_f32 v[240:241], v[126:127], v[194:195], v[240:241] op_sel:[0,0,0] op_sel_hi:[0,1,1]
	ds_read_b128 v[180:183], v179 offset:4992
	ds_read_b128 v[184:187], v179 offset:5008
	ds_read_b128 v[188:191], v179 offset:5024
	ds_read_b128 v[192:195], v179 offset:5040
	s_waitcnt vmcnt(50) lgkmcnt(4)
	v_pk_fma_f32 v[226:227], v[126:127], v[210:211], v[226:227] op_sel:[1,0,0] op_sel_hi:[1,1,1]
	v_pk_fma_f32 v[228:229], v[126:127], v[212:213], v[228:229] op_sel:[1,0,0] op_sel_hi:[1,1,1]
	v_pk_fma_f32 v[230:231], v[126:127], v[214:215], v[230:231] op_sel:[1,0,0] op_sel_hi:[1,1,1]
	v_pk_fma_f32 v[232:233], v[126:127], v[216:217], v[232:233] op_sel:[1,0,0] op_sel_hi:[1,1,1]
	v_pk_fma_f32 v[234:235], v[126:127], v[218:219], v[234:235] op_sel:[1,0,0] op_sel_hi:[1,1,1]
	v_pk_fma_f32 v[236:237], v[126:127], v[220:221], v[236:237] op_sel:[1,0,0] op_sel_hi:[1,1,1]
	v_pk_fma_f32 v[238:239], v[126:127], v[222:223], v[238:239] op_sel:[1,0,0] op_sel_hi:[1,1,1]
	v_pk_fma_f32 v[240:241], v[126:127], v[224:225], v[240:241] op_sel:[1,0,0] op_sel_hi:[1,1,1]
	ds_read_b128 v[210:213], v179 offset:5056
	ds_read_b128 v[214:217], v179 offset:5072
	ds_read_b128 v[218:221], v179 offset:5088
	ds_read_b128 v[222:225], v179 offset:5104
	s_waitcnt vmcnt(49) lgkmcnt(4)
	v_pk_fma_f32 v[226:227], v[128:129], v[180:181], v[226:227] op_sel:[0,0,0] op_sel_hi:[0,1,1]
	v_pk_fma_f32 v[228:229], v[128:129], v[182:183], v[228:229] op_sel:[0,0,0] op_sel_hi:[0,1,1]
	v_pk_fma_f32 v[230:231], v[128:129], v[184:185], v[230:231] op_sel:[0,0,0] op_sel_hi:[0,1,1]
	v_pk_fma_f32 v[232:233], v[128:129], v[186:187], v[232:233] op_sel:[0,0,0] op_sel_hi:[0,1,1]
	v_pk_fma_f32 v[234:235], v[128:129], v[188:189], v[234:235] op_sel:[0,0,0] op_sel_hi:[0,1,1]
	v_pk_fma_f32 v[236:237], v[128:129], v[190:191], v[236:237] op_sel:[0,0,0] op_sel_hi:[0,1,1]
	v_pk_fma_f32 v[238:239], v[128:129], v[192:193], v[238:239] op_sel:[0,0,0] op_sel_hi:[0,1,1]
	v_pk_fma_f32 v[240:241], v[128:129], v[194:195], v[240:241] op_sel:[0,0,0] op_sel_hi:[0,1,1]
	ds_read_b128 v[180:183], v179 offset:5120
	ds_read_b128 v[184:187], v179 offset:5136
	ds_read_b128 v[188:191], v179 offset:5152
	ds_read_b128 v[192:195], v179 offset:5168
	s_waitcnt vmcnt(48) lgkmcnt(4)
	v_pk_fma_f32 v[226:227], v[128:129], v[210:211], v[226:227] op_sel:[1,0,0] op_sel_hi:[1,1,1]
	v_pk_fma_f32 v[228:229], v[128:129], v[212:213], v[228:229] op_sel:[1,0,0] op_sel_hi:[1,1,1]
	v_pk_fma_f32 v[230:231], v[128:129], v[214:215], v[230:231] op_sel:[1,0,0] op_sel_hi:[1,1,1]
	v_pk_fma_f32 v[232:233], v[128:129], v[216:217], v[232:233] op_sel:[1,0,0] op_sel_hi:[1,1,1]
	v_pk_fma_f32 v[234:235], v[128:129], v[218:219], v[234:235] op_sel:[1,0,0] op_sel_hi:[1,1,1]
	v_pk_fma_f32 v[236:237], v[128:129], v[220:221], v[236:237] op_sel:[1,0,0] op_sel_hi:[1,1,1]
	v_pk_fma_f32 v[238:239], v[128:129], v[222:223], v[238:239] op_sel:[1,0,0] op_sel_hi:[1,1,1]
	v_pk_fma_f32 v[240:241], v[128:129], v[224:225], v[240:241] op_sel:[1,0,0] op_sel_hi:[1,1,1]
	ds_read_b128 v[210:213], v179 offset:5184
	ds_read_b128 v[214:217], v179 offset:5200
	ds_read_b128 v[218:221], v179 offset:5216
	ds_read_b128 v[222:225], v179 offset:5232
	s_waitcnt vmcnt(47) lgkmcnt(4)
	v_pk_fma_f32 v[226:227], v[130:131], v[180:181], v[226:227] op_sel:[0,0,0] op_sel_hi:[0,1,1]
	v_pk_fma_f32 v[228:229], v[130:131], v[182:183], v[228:229] op_sel:[0,0,0] op_sel_hi:[0,1,1]
	v_pk_fma_f32 v[230:231], v[130:131], v[184:185], v[230:231] op_sel:[0,0,0] op_sel_hi:[0,1,1]
	v_pk_fma_f32 v[232:233], v[130:131], v[186:187], v[232:233] op_sel:[0,0,0] op_sel_hi:[0,1,1]
	v_pk_fma_f32 v[234:235], v[130:131], v[188:189], v[234:235] op_sel:[0,0,0] op_sel_hi:[0,1,1]
	v_pk_fma_f32 v[236:237], v[130:131], v[190:191], v[236:237] op_sel:[0,0,0] op_sel_hi:[0,1,1]
	v_pk_fma_f32 v[238:239], v[130:131], v[192:193], v[238:239] op_sel:[0,0,0] op_sel_hi:[0,1,1]
	v_pk_fma_f32 v[240:241], v[130:131], v[194:195], v[240:241] op_sel:[0,0,0] op_sel_hi:[0,1,1]
	ds_read_b128 v[180:183], v179 offset:5248
	ds_read_b128 v[184:187], v179 offset:5264
	ds_read_b128 v[188:191], v179 offset:5280
	ds_read_b128 v[192:195], v179 offset:5296
	s_waitcnt vmcnt(46) lgkmcnt(4)
	v_pk_fma_f32 v[226:227], v[130:131], v[210:211], v[226:227] op_sel:[1,0,0] op_sel_hi:[1,1,1]
	v_pk_fma_f32 v[228:229], v[130:131], v[212:213], v[228:229] op_sel:[1,0,0] op_sel_hi:[1,1,1]
	v_pk_fma_f32 v[230:231], v[130:131], v[214:215], v[230:231] op_sel:[1,0,0] op_sel_hi:[1,1,1]
	v_pk_fma_f32 v[232:233], v[130:131], v[216:217], v[232:233] op_sel:[1,0,0] op_sel_hi:[1,1,1]
	v_pk_fma_f32 v[234:235], v[130:131], v[218:219], v[234:235] op_sel:[1,0,0] op_sel_hi:[1,1,1]
	v_pk_fma_f32 v[236:237], v[130:131], v[220:221], v[236:237] op_sel:[1,0,0] op_sel_hi:[1,1,1]
	v_pk_fma_f32 v[238:239], v[130:131], v[222:223], v[238:239] op_sel:[1,0,0] op_sel_hi:[1,1,1]
	v_pk_fma_f32 v[240:241], v[130:131], v[224:225], v[240:241] op_sel:[1,0,0] op_sel_hi:[1,1,1]
	ds_read_b128 v[210:213], v179 offset:5312
	ds_read_b128 v[214:217], v179 offset:5328
	ds_read_b128 v[218:221], v179 offset:5344
	ds_read_b128 v[222:225], v179 offset:5360
	s_waitcnt vmcnt(45) lgkmcnt(4)
; #define LAS __attribute__((address_space(3)))
; __global__ void __launch_bounds__(NTHR, 2) hymba_fwd(Params P) {
;     ...
;             for (int kk = 0; kk < 128; ++kk) { const float wv = P.w_ada[(size_t)(wave * 128 + kk) * 3072 + col];
; #pragma unroll
;                 for (int q = 0; q < 4; ++q) { const f32x4 s = *(const LAS f32x4*)(sil + kk * 16 + 4 * q); acc[4 * q] += s[0] * wv; acc[4 * q + 1] += s[1] * wv; acc[4 * q + 2] += s[2] * wv; acc[4 * q + 3] += s[3] * wv; } }
	v_pk_fma_f32 v[226:227], v[132:133], v[180:181], v[226:227] op_sel:[0,0,0] op_sel_hi:[0,1,1]
	v_pk_fma_f32 v[228:229], v[132:133], v[182:183], v[228:229] op_sel:[0,0,0] op_sel_hi:[0,1,1]
	v_pk_fma_f32 v[230:231], v[132:133], v[184:185], v[230:231] op_sel:[0,0,0] op_sel_hi:[0,1,1]
	v_pk_fma_f32 v[232:233], v[132:133], v[186:187], v[232:233] op_sel:[0,0,0] op_sel_hi:[0,1,1]
	v_pk_fma_f32 v[234:235], v[132:133], v[188:189], v[234:235] op_sel:[0,0,0] op_sel_hi:[0,1,1]
	v_pk_fma_f32 v[236:237], v[132:133], v[190:191], v[236:237] op_sel:[0,0,0] op_sel_hi:[0,1,1]
	v_pk_fma_f32 v[238:239], v[132:133], v[192:193], v[238:239] op_sel:[0,0,0] op_sel_hi:[0,1,1]
	v_pk_fma_f32 v[240:241], v[132:133], v[194:195], v[240:241] op_sel:[0,0,0] op_sel_hi:[0,1,1]
	ds_read_b128 v[180:183], v179 offset:5376
	ds_read_b128 v[184:187], v179 offset:5392
	ds_read_b128 v[188:191], v179 offset:5408
	ds_read_b128 v[192:195], v179 offset:5424
	s_waitcnt vmcnt(44) lgkmcnt(4)
	v_pk_fma_f32 v[226:227], v[132:133], v[210:211], v[226:227] op_sel:[1,0,0] op_sel_hi:[1,1,1]
	v_pk_fma_f32 v[228:229], v[132:133], v[212:213], v[228:229] op_sel:[1,0,0] op_sel_hi:[1,1,1]
	v_pk_fma_f32 v[230:231], v[132:133], v[214:215], v[230:231] op_sel:[1,0,0] op_sel_hi:[1,1,1]
	v_pk_fma_f32 v[232:233], v[132:133], v[216:217], v[232:233] op_sel:[1,0,0] op_sel_hi:[1,1,1]
	v_pk_fma_f32 v[234:235], v[132:133], v[218:219], v[234:235] op_sel:[1,0,0] op_sel_hi:[1,1,1]
	v_pk_fma_f32 v[236:237], v[132:133], v[220:221], v[236:237] op_sel:[1,0,0] op_sel_hi:[1,1,1]
	v_pk_fma_f32 v[238:239], v[132:133], v[222:223], v[238:239] op_sel:[1,0,0] op_sel_hi:[1,1,1]
	v_pk_fma_f32 v[240:241], v[132:133], v[224:225], v[240:241] op_sel:[1,0,0] op_sel_hi:[1,1,1]
	ds_read_b128 v[210:213], v179 offset:5440
	ds_read_b128 v[214:217], v179 offset:5456
	ds_read_b128 v[218:221], v179 offset:5472
	ds_read_b128 v[222:225], v179 offset:5488
	s_waitcnt vmcnt(43) lgkmcnt(4)
	v_pk_fma_f32 v[226:227], v[134:135], v[180:181], v[226:227] op_sel:[0,0,0] op_sel_hi:[0,1,1]
	v_pk_fma_f32 v[228:229], v[134:135], v[182:183], v[228:229] op_sel:[0,0,0] op_sel_hi:[0,1,1]
	v_pk_fma_f32 v[230:231], v[134:135], v[184:185], v[230:231] op_sel:[0,0,0] op_sel_hi:[0,1,1]
	v_pk_fma_f32 v[232:233], v[134:135], v[186:187], v[232:233] op_sel:[0,0,0] op_sel_hi:[0,1,1]
	v_pk_fma_f32 v[234:235], v[134:135], v[188:189], v[234:235] op_sel:[0,0,0] op_sel_hi:[0,1,1]
	v_pk_fma_f32 v[236:237], v[134:135], v[190:191], v[236:237] op_sel:[0,0,0] op_sel_hi:[0,1,1]
	v_pk_fma_f32 v[238:239], v[134:135], v[192:193], v[238:239] op_sel:[0,0,0] op_sel_hi:[0,1,1]
	v_pk_fma_f32 v[240:241], v[134:135], v[194:195], v[240:241] op_sel:[0,0,0] op_sel_hi:[0,1,1]
	ds_read_b128 v[180:183], v179 offset:5504
	ds_read_b128 v[184:187], v179 offset:5520
	ds_read_b128 v[188:191], v179 offset:5536
	ds_read_b128 v[192:195], v179 offset:5552
	s_waitcnt vmcnt(42) lgkmcnt(4)
	v_pk_fma_f32 v[226:227], v[134:135], v[210:211], v[226:227] op_sel:[1,0,0] op_sel_hi:[1,1,1]
	v_pk_fma_f32 v[228:229], v[134:135], v[212:213], v[228:229] op_sel:[1,0,0] op_sel_hi:[1,1,1]
	v_pk_fma_f32 v[230:231], v[134:135], v[214:215], v[230:231] op_sel:[1,0,0] op_sel_hi:[1,1,1]
	v_pk_fma_f32 v[232:233], v[134:135], v[216:217], v[232:233] op_sel:[1,0,0] op_sel_hi:[1,1,1]
	v_pk_fma_f32 v[234:235], v[134:135], v[218:219], v[234:235] op_sel:[1,0,0] op_sel_hi:[1,1,1]
	v_pk_fma_f32 v[236:237], v[134:135], v[220:221], v[236:237] op_sel:[1,0,0] op_sel_hi:[1,1,1]
	v_pk_fma_f32 v[238:239], v[134:135], v[222:223], v[238:239] op_sel:[1,0,0] op_sel_hi:[1,1,1]
	v_pk_fma_f32 v[240:241], v[134:135], v[224:225], v[240:241] op_sel:[1,0,0] op_sel_hi:[1,1,1]
	ds_read_b128 v[210:213], v179 offset:5568
	ds_read_b128 v[214:217], v179 offset:5584
	ds_read_b128 v[218:221], v179 offset:5600
	ds_read_b128 v[222:225], v179 offset:5616
	s_waitcnt vmcnt(41) lgkmcnt(4)
	v_pk_fma_f32 v[226:227], v[136:137], v[180:181], v[226:227] op_sel:[0,0,0] op_sel_hi:[0,1,1]
	v_pk_fma_f32 v[228:229], v[136:137], v[182:183], v[228:229] op_sel:[0,0,0] op_sel_hi:[0,1,1]
	v_pk_fma_f32 v[230:231], v[136:137], v[184:185], v[230:231] op_sel:[0,0,0] op_sel_hi:[0,1,1]
	v_pk_fma_f32 v[232:233], v[136:137], v[186:187], v[232:233] op_sel:[0,0,0] op_sel_hi:[0,1,1]
	v_pk_fma_f32 v[234:235], v[136:137], v[188:189], v[234:235] op_sel:[0,0,0] op_sel_hi:[0,1,1]
	v_pk_fma_f32 v[236:237], v[136:137], v[190:191], v[236:237] op_sel:[0,0,0] op_sel_hi:[0,1,1]
	v_pk_fma_f32 v[238:239], v[136:137], v[192:193], v[238:239] op_sel:[0,0,0] op_sel_hi:[0,1,1]
	v_pk_fma_f32 v[240:241], v[136:137], v[194:195], v[240:241] op_sel:[0,0,0] op_sel_hi:[0,1,1]
	ds_read_b128 v[180:183], v179 offset:5632
	ds_read_b128 v[184:187], v179 offset:5648
	ds_read_b128 v[188:191], v179 offset:5664
	ds_read_b128 v[192:195], v179 offset:5680
	s_waitcnt vmcnt(40) lgkmcnt(4)
	v_pk_fma_f32 v[226:227], v[136:137], v[210:211], v[226:227] op_sel:[1,0,0] op_sel_hi:[1,1,1]
	v_pk_fma_f32 v[228:229], v[136:137], v[212:213], v[228:229] op_sel:[1,0,0] op_sel_hi:[1,1,1]
	v_pk_fma_f32 v[230:231], v[136:137], v[214:215], v[230:231] op_sel:[1,0,0] op_sel_hi:[1,1,1]
	v_pk_fma_f32 v[232:233], v[136:137], v[216:217], v[232:233] op_sel:[1,0,0] op_sel_hi:[1,1,1]
	v_pk_fma_f32 v[234:235], v[136:137], v[218:219], v[234:235] op_sel:[1,0,0] op_sel_hi:[1,1,1]
	v_pk_fma_f32 v[236:237], v[136:137], v[220:221], v[236:237] op_sel:[1,0,0] op_sel_hi:[1,1,1]
	v_pk_fma_f32 v[238:239], v[136:137], v[222:223], v[238:239] op_sel:[1,0,0] op_sel_hi:[1,1,1]
	v_pk_fma_f32 v[240:241], v[136:137], v[224:225], v[240:241] op_sel:[1,0,0] op_sel_hi:[1,1,1]
	ds_read_b128 v[210:213], v179 offset:5696
	ds_read_b128 v[214:217], v179 offset:5712
	ds_read_b128 v[218:221], v179 offset:5728
	ds_read_b128 v[222:225], v179 offset:5744
	s_waitcnt vmcnt(39) lgkmcnt(4)
; #define LAS __attribute__((address_space(3)))
; __global__ void __launch_bounds__(NTHR, 2) hymba_fwd(Params P) {
;     ...
;             for (int kk = 0; kk < 128; ++kk) { const float wv = P.w_ada[(size_t)(wave * 128 + kk) * 3072 + col];
; #pragma unroll
;                 for (int q = 0; q < 4; ++q) { const f32x4 s = *(const LAS f32x4*)(sil + kk * 16 + 4 * q); acc[4 * q] += s[0] * wv; acc[4 * q + 1] += s[1] * wv; acc[4 * q + 2] += s[2] * wv; acc[4 * q + 3] += s[3] * wv; } }
	v_pk_fma_f32 v[226:227], v[138:139], v[180:181], v[226:227] op_sel:[0,0,0] op_sel_hi:[0,1,1]
	v_pk_fma_f32 v[228:229], v[138:139], v[182:183], v[228:229] op_sel:[0,0,0] op_sel_hi:[0,1,1]
	v_pk_fma_f32 v[230:231], v[138:139], v[184:185], v[230:231] op_sel:[0,0,0] op_sel_hi:[0,1,1]
	v_pk_fma_f32 v[232:233], v[138:139], v[186:187], v[232:233] op_sel:[0,0,0] op_sel_hi:[0,1,1]
	v_pk_fma_f32 v[234:235], v[138:139], v[188:189], v[234:235] op_sel:[0,0,0] op_sel_hi:[0,1,1]
	v_pk_fma_f32 v[236:237], v[138:139], v[190:191], v[236:237] op_sel:[0,0,0] op_sel_hi:[0,1,1]
	v_pk_fma_f32 v[238:239], v[138:139], v[192:193], v[238:239] op_sel:[0,0,0] op_sel_hi:[0,1,1]
	v_pk_fma_f32 v[240:241], v[138:139], v[194:195], v[240:241] op_sel:[0,0,0] op_sel_hi:[0,1,1]
	ds_read_b128 v[180:183], v179 offset:5760
	ds_read_b128 v[184:187], v179 offset:5776
	ds_read_b128 v[188:191], v179 offset:5792
	ds_read_b128 v[192:195], v179 offset:5808
	s_waitcnt vmcnt(38) lgkmcnt(4)
	v_pk_fma_f32 v[226:227], v[138:139], v[210:211], v[226:227] op_sel:[1,0,0] op_sel_hi:[1,1,1]
	v_pk_fma_f32 v[228:229], v[138:139], v[212:213], v[228:229] op_sel:[1,0,0] op_sel_hi:[1,1,1]
	v_pk_fma_f32 v[230:231], v[138:139], v[214:215], v[230:231] op_sel:[1,0,0] op_sel_hi:[1,1,1]
	v_pk_fma_f32 v[232:233], v[138:139], v[216:217], v[232:233] op_sel:[1,0,0] op_sel_hi:[1,1,1]
	v_pk_fma_f32 v[234:235], v[138:139], v[218:219], v[234:235] op_sel:[1,0,0] op_sel_hi:[1,1,1]
	v_pk_fma_f32 v[236:237], v[138:139], v[220:221], v[236:237] op_sel:[1,0,0] op_sel_hi:[1,1,1]
	v_pk_fma_f32 v[238:239], v[138:139], v[222:223], v[238:239] op_sel:[1,0,0] op_sel_hi:[1,1,1]
	v_pk_fma_f32 v[240:241], v[138:139], v[224:225], v[240:241] op_sel:[1,0,0] op_sel_hi:[1,1,1]
	ds_read_b128 v[210:213], v179 offset:5824
	ds_read_b128 v[214:217], v179 offset:5840
	ds_read_b128 v[218:221], v179 offset:5856
	ds_read_b128 v[222:225], v179 offset:5872
	s_waitcnt vmcnt(37) lgkmcnt(4)
	v_pk_fma_f32 v[226:227], v[140:141], v[180:181], v[226:227] op_sel:[0,0,0] op_sel_hi:[0,1,1]
	v_pk_fma_f32 v[228:229], v[140:141], v[182:183], v[228:229] op_sel:[0,0,0] op_sel_hi:[0,1,1]
	v_pk_fma_f32 v[230:231], v[140:141], v[184:185], v[230:231] op_sel:[0,0,0] op_sel_hi:[0,1,1]
	v_pk_fma_f32 v[232:233], v[140:141], v[186:187], v[232:233] op_sel:[0,0,0] op_sel_hi:[0,1,1]
	v_pk_fma_f32 v[234:235], v[140:141], v[188:189], v[234:235] op_sel:[0,0,0] op_sel_hi:[0,1,1]
	v_pk_fma_f32 v[236:237], v[140:141], v[190:191], v[236:237] op_sel:[0,0,0] op_sel_hi:[0,1,1]
	v_pk_fma_f32 v[238:239], v[140:141], v[192:193], v[238:239] op_sel:[0,0,0] op_sel_hi:[0,1,1]
	v_pk_fma_f32 v[240:241], v[140:141], v[194:195], v[240:241] op_sel:[0,0,0] op_sel_hi:[0,1,1]
	ds_read_b128 v[180:183], v179 offset:5888
	ds_read_b128 v[184:187], v179 offset:5904
	ds_read_b128 v[188:191], v179 offset:5920
	ds_read_b128 v[192:195], v179 offset:5936
	s_waitcnt vmcnt(36) lgkmcnt(4)
	v_pk_fma_f32 v[226:227], v[140:141], v[210:211], v[226:227] op_sel:[1,0,0] op_sel_hi:[1,1,1]
	v_pk_fma_f32 v[228:229], v[140:141], v[212:213], v[228:229] op_sel:[1,0,0] op_sel_hi:[1,1,1]
	v_pk_fma_f32 v[230:231], v[140:141], v[214:215], v[230:231] op_sel:[1,0,0] op_sel_hi:[1,1,1]
	v_pk_fma_f32 v[232:233], v[140:141], v[216:217], v[232:233] op_sel:[1,0,0] op_sel_hi:[1,1,1]
	v_pk_fma_f32 v[234:235], v[140:141], v[218:219], v[234:235] op_sel:[1,0,0] op_sel_hi:[1,1,1]
	v_pk_fma_f32 v[236:237], v[140:141], v[220:221], v[236:237] op_sel:[1,0,0] op_sel_hi:[1,1,1]
	v_pk_fma_f32 v[238:239], v[140:141], v[222:223], v[238:239] op_sel:[1,0,0] op_sel_hi:[1,1,1]
	v_pk_fma_f32 v[240:241], v[140:141], v[224:225], v[240:241] op_sel:[1,0,0] op_sel_hi:[1,1,1]
	ds_read_b128 v[210:213], v179 offset:5952
	ds_read_b128 v[214:217], v179 offset:5968
	ds_read_b128 v[218:221], v179 offset:5984
	ds_read_b128 v[222:225], v179 offset:6000
	s_waitcnt vmcnt(35) lgkmcnt(4)
	v_pk_fma_f32 v[226:227], v[142:143], v[180:181], v[226:227] op_sel:[0,0,0] op_sel_hi:[0,1,1]
	v_pk_fma_f32 v[228:229], v[142:143], v[182:183], v[228:229] op_sel:[0,0,0] op_sel_hi:[0,1,1]
	v_pk_fma_f32 v[230:231], v[142:143], v[184:185], v[230:231] op_sel:[0,0,0] op_sel_hi:[0,1,1]
	v_pk_fma_f32 v[232:233], v[142:143], v[186:187], v[232:233] op_sel:[0,0,0] op_sel_hi:[0,1,1]
	v_pk_fma_f32 v[234:235], v[142:143], v[188:189], v[234:235] op_sel:[0,0,0] op_sel_hi:[0,1,1]
	v_pk_fma_f32 v[236:237], v[142:143], v[190:191], v[236:237] op_sel:[0,0,0] op_sel_hi:[0,1,1]
	v_pk_fma_f32 v[238:239], v[142:143], v[192:193], v[238:239] op_sel:[0,0,0] op_sel_hi:[0,1,1]
	v_pk_fma_f32 v[240:241], v[142:143], v[194:195], v[240:241] op_sel:[0,0,0] op_sel_hi:[0,1,1]
	ds_read_b128 v[180:183], v179 offset:6016
	ds_read_b128 v[184:187], v179 offset:6032
	ds_read_b128 v[188:191], v179 offset:6048
	ds_read_b128 v[192:195], v179 offset:6064
	s_waitcnt vmcnt(34) lgkmcnt(4)
	v_pk_fma_f32 v[226:227], v[142:143], v[210:211], v[226:227] op_sel:[1,0,0] op_sel_hi:[1,1,1]
	v_pk_fma_f32 v[228:229], v[142:143], v[212:213], v[228:229] op_sel:[1,0,0] op_sel_hi:[1,1,1]
	v_pk_fma_f32 v[230:231], v[142:143], v[214:215], v[230:231] op_sel:[1,0,0] op_sel_hi:[1,1,1]
	v_pk_fma_f32 v[232:233], v[142:143], v[216:217], v[232:233] op_sel:[1,0,0] op_sel_hi:[1,1,1]
	v_pk_fma_f32 v[234:235], v[142:143], v[218:219], v[234:235] op_sel:[1,0,0] op_sel_hi:[1,1,1]
	v_pk_fma_f32 v[236:237], v[142:143], v[220:221], v[236:237] op_sel:[1,0,0] op_sel_hi:[1,1,1]
	v_pk_fma_f32 v[238:239], v[142:143], v[222:223], v[238:239] op_sel:[1,0,0] op_sel_hi:[1,1,1]
	v_pk_fma_f32 v[240:241], v[142:143], v[224:225], v[240:241] op_sel:[1,0,0] op_sel_hi:[1,1,1]
	ds_read_b128 v[210:213], v179 offset:6080
	ds_read_b128 v[214:217], v179 offset:6096
	ds_read_b128 v[218:221], v179 offset:6112
	ds_read_b128 v[222:225], v179 offset:6128
	s_waitcnt vmcnt(33) lgkmcnt(4)
; #define LAS __attribute__((address_space(3)))
; __global__ void __launch_bounds__(NTHR, 2) hymba_fwd(Params P) {
;     ...
;             for (int kk = 0; kk < 128; ++kk) { const float wv = P.w_ada[(size_t)(wave * 128 + kk) * 3072 + col];
; #pragma unroll
;                 for (int q = 0; q < 4; ++q) { const f32x4 s = *(const LAS f32x4*)(sil + kk * 16 + 4 * q); acc[4 * q] += s[0] * wv; acc[4 * q + 1] += s[1] * wv; acc[4 * q + 2] += s[2] * wv; acc[4 * q + 3] += s[3] * wv; } }
	v_pk_fma_f32 v[226:227], v[144:145], v[180:181], v[226:227] op_sel:[0,0,0] op_sel_hi:[0,1,1]
	v_pk_fma_f32 v[228:229], v[144:145], v[182:183], v[228:229] op_sel:[0,0,0] op_sel_hi:[0,1,1]
	v_pk_fma_f32 v[230:231], v[144:145], v[184:185], v[230:231] op_sel:[0,0,0] op_sel_hi:[0,1,1]
	v_pk_fma_f32 v[232:233], v[144:145], v[186:187], v[232:233] op_sel:[0,0,0] op_sel_hi:[0,1,1]
	v_pk_fma_f32 v[234:235], v[144:145], v[188:189], v[234:235] op_sel:[0,0,0] op_sel_hi:[0,1,1]
	v_pk_fma_f32 v[236:237], v[144:145], v[190:191], v[236:237] op_sel:[0,0,0] op_sel_hi:[0,1,1]
	v_pk_fma_f32 v[238:239], v[144:145], v[192:193], v[238:239] op_sel:[0,0,0] op_sel_hi:[0,1,1]
	v_pk_fma_f32 v[240:241], v[144:145], v[194:195], v[240:241] op_sel:[0,0,0] op_sel_hi:[0,1,1]
	ds_read_b128 v[180:183], v179 offset:6144
	ds_read_b128 v[184:187], v179 offset:6160
	ds_read_b128 v[188:191], v179 offset:6176
	ds_read_b128 v[192:195], v179 offset:6192
	s_waitcnt vmcnt(32) lgkmcnt(4)
	v_pk_fma_f32 v[226:227], v[144:145], v[210:211], v[226:227] op_sel:[1,0,0] op_sel_hi:[1,1,1]
	v_pk_fma_f32 v[228:229], v[144:145], v[212:213], v[228:229] op_sel:[1,0,0] op_sel_hi:[1,1,1]
	v_pk_fma_f32 v[230:231], v[144:145], v[214:215], v[230:231] op_sel:[1,0,0] op_sel_hi:[1,1,1]
	v_pk_fma_f32 v[232:233], v[144:145], v[216:217], v[232:233] op_sel:[1,0,0] op_sel_hi:[1,1,1]
	v_pk_fma_f32 v[234:235], v[144:145], v[218:219], v[234:235] op_sel:[1,0,0] op_sel_hi:[1,1,1]
	v_pk_fma_f32 v[236:237], v[144:145], v[220:221], v[236:237] op_sel:[1,0,0] op_sel_hi:[1,1,1]
	v_pk_fma_f32 v[238:239], v[144:145], v[222:223], v[238:239] op_sel:[1,0,0] op_sel_hi:[1,1,1]
	v_pk_fma_f32 v[240:241], v[144:145], v[224:225], v[240:241] op_sel:[1,0,0] op_sel_hi:[1,1,1]
	ds_read_b128 v[210:213], v179 offset:6208
	ds_read_b128 v[214:217], v179 offset:6224
	ds_read_b128 v[218:221], v179 offset:6240
	ds_read_b128 v[222:225], v179 offset:6256
	s_waitcnt vmcnt(31) lgkmcnt(4)
	v_pk_fma_f32 v[226:227], v[146:147], v[180:181], v[226:227] op_sel:[0,0,0] op_sel_hi:[0,1,1]
	v_pk_fma_f32 v[228:229], v[146:147], v[182:183], v[228:229] op_sel:[0,0,0] op_sel_hi:[0,1,1]
	v_pk_fma_f32 v[230:231], v[146:147], v[184:185], v[230:231] op_sel:[0,0,0] op_sel_hi:[0,1,1]
	v_pk_fma_f32 v[232:233], v[146:147], v[186:187], v[232:233] op_sel:[0,0,0] op_sel_hi:[0,1,1]
	v_pk_fma_f32 v[234:235], v[146:147], v[188:189], v[234:235] op_sel:[0,0,0] op_sel_hi:[0,1,1]
	v_pk_fma_f32 v[236:237], v[146:147], v[190:191], v[236:237] op_sel:[0,0,0] op_sel_hi:[0,1,1]
	v_pk_fma_f32 v[238:239], v[146:147], v[192:193], v[238:239] op_sel:[0,0,0] op_sel_hi:[0,1,1]
	v_pk_fma_f32 v[240:241], v[146:147], v[194:195], v[240:241] op_sel:[0,0,0] op_sel_hi:[0,1,1]
	ds_read_b128 v[180:183], v179 offset:6272
	ds_read_b128 v[184:187], v179 offset:6288
	ds_read_b128 v[188:191], v179 offset:6304
	ds_read_b128 v[192:195], v179 offset:6320
	s_waitcnt vmcnt(30) lgkmcnt(4)
	v_pk_fma_f32 v[226:227], v[146:147], v[210:211], v[226:227] op_sel:[1,0,0] op_sel_hi:[1,1,1]
	v_pk_fma_f32 v[228:229], v[146:147], v[212:213], v[228:229] op_sel:[1,0,0] op_sel_hi:[1,1,1]
	v_pk_fma_f32 v[230:231], v[146:147], v[214:215], v[230:231] op_sel:[1,0,0] op_sel_hi:[1,1,1]
	v_pk_fma_f32 v[232:233], v[146:147], v[216:217], v[232:233] op_sel:[1,0,0] op_sel_hi:[1,1,1]
	v_pk_fma_f32 v[234:235], v[146:147], v[218:219], v[234:235] op_sel:[1,0,0] op_sel_hi:[1,1,1]
	v_pk_fma_f32 v[236:237], v[146:147], v[220:221], v[236:237] op_sel:[1,0,0] op_sel_hi:[1,1,1]
	v_pk_fma_f32 v[238:239], v[146:147], v[222:223], v[238:239] op_sel:[1,0,0] op_sel_hi:[1,1,1]
	v_pk_fma_f32 v[240:241], v[146:147], v[224:225], v[240:241] op_sel:[1,0,0] op_sel_hi:[1,1,1]
	ds_read_b128 v[210:213], v179 offset:6336
	ds_read_b128 v[214:217], v179 offset:6352
	ds_read_b128 v[218:221], v179 offset:6368
	ds_read_b128 v[222:225], v179 offset:6384
	s_waitcnt vmcnt(29) lgkmcnt(4)
	v_pk_fma_f32 v[226:227], v[148:149], v[180:181], v[226:227] op_sel:[0,0,0] op_sel_hi:[0,1,1]
	v_pk_fma_f32 v[228:229], v[148:149], v[182:183], v[228:229] op_sel:[0,0,0] op_sel_hi:[0,1,1]
	v_pk_fma_f32 v[230:231], v[148:149], v[184:185], v[230:231] op_sel:[0,0,0] op_sel_hi:[0,1,1]
	v_pk_fma_f32 v[232:233], v[148:149], v[186:187], v[232:233] op_sel:[0,0,0] op_sel_hi:[0,1,1]
	v_pk_fma_f32 v[234:235], v[148:149], v[188:189], v[234:235] op_sel:[0,0,0] op_sel_hi:[0,1,1]
	v_pk_fma_f32 v[236:237], v[148:149], v[190:191], v[236:237] op_sel:[0,0,0] op_sel_hi:[0,1,1]
	v_pk_fma_f32 v[238:239], v[148:149], v[192:193], v[238:239] op_sel:[0,0,0] op_sel_hi:[0,1,1]
	v_pk_fma_f32 v[240:241], v[148:149], v[194:195], v[240:241] op_sel:[0,0,0] op_sel_hi:[0,1,1]
	ds_read_b128 v[180:183], v179 offset:6400
	ds_read_b128 v[184:187], v179 offset:6416
	ds_read_b128 v[188:191], v179 offset:6432
	ds_read_b128 v[192:195], v179 offset:6448
	s_waitcnt vmcnt(28) lgkmcnt(4)
	v_pk_fma_f32 v[226:227], v[148:149], v[210:211], v[226:227] op_sel:[1,0,0] op_sel_hi:[1,1,1]
	v_pk_fma_f32 v[228:229], v[148:149], v[212:213], v[228:229] op_sel:[1,0,0] op_sel_hi:[1,1,1]
	v_pk_fma_f32 v[230:231], v[148:149], v[214:215], v[230:231] op_sel:[1,0,0] op_sel_hi:[1,1,1]
	v_pk_fma_f32 v[232:233], v[148:149], v[216:217], v[232:233] op_sel:[1,0,0] op_sel_hi:[1,1,1]
	v_pk_fma_f32 v[234:235], v[148:149], v[218:219], v[234:235] op_sel:[1,0,0] op_sel_hi:[1,1,1]
	v_pk_fma_f32 v[236:237], v[148:149], v[220:221], v[236:237] op_sel:[1,0,0] op_sel_hi:[1,1,1]
	v_pk_fma_f32 v[238:239], v[148:149], v[222:223], v[238:239] op_sel:[1,0,0] op_sel_hi:[1,1,1]
	v_pk_fma_f32 v[240:241], v[148:149], v[224:225], v[240:241] op_sel:[1,0,0] op_sel_hi:[1,1,1]
	ds_read_b128 v[210:213], v179 offset:6464
	ds_read_b128 v[214:217], v179 offset:6480
	ds_read_b128 v[218:221], v179 offset:6496
	ds_read_b128 v[222:225], v179 offset:6512
	s_waitcnt vmcnt(27) lgkmcnt(4)
; #define LAS __attribute__((address_space(3)))
; __global__ void __launch_bounds__(NTHR, 2) hymba_fwd(Params P) {
;     ...
;             for (int kk = 0; kk < 128; ++kk) { const float wv = P.w_ada[(size_t)(wave * 128 + kk) * 3072 + col];
; #pragma unroll
;                 for (int q = 0; q < 4; ++q) { const f32x4 s = *(const LAS f32x4*)(sil + kk * 16 + 4 * q); acc[4 * q] += s[0] * wv; acc[4 * q + 1] += s[1] * wv; acc[4 * q + 2] += s[2] * wv; acc[4 * q + 3] += s[3] * wv; } }
	v_pk_fma_f32 v[226:227], v[150:151], v[180:181], v[226:227] op_sel:[0,0,0] op_sel_hi:[0,1,1]
	v_pk_fma_f32 v[228:229], v[150:151], v[182:183], v[228:229] op_sel:[0,0,0] op_sel_hi:[0,1,1]
	v_pk_fma_f32 v[230:231], v[150:151], v[184:185], v[230:231] op_sel:[0,0,0] op_sel_hi:[0,1,1]
	v_pk_fma_f32 v[232:233], v[150:151], v[186:187], v[232:233] op_sel:[0,0,0] op_sel_hi:[0,1,1]
	v_pk_fma_f32 v[234:235], v[150:151], v[188:189], v[234:235] op_sel:[0,0,0] op_sel_hi:[0,1,1]
	v_pk_fma_f32 v[236:237], v[150:151], v[190:191], v[236:237] op_sel:[0,0,0] op_sel_hi:[0,1,1]
	v_pk_fma_f32 v[238:239], v[150:151], v[192:193], v[238:239] op_sel:[0,0,0] op_sel_hi:[0,1,1]
	v_pk_fma_f32 v[240:241], v[150:151], v[194:195], v[240:241] op_sel:[0,0,0] op_sel_hi:[0,1,1]
	ds_read_b128 v[180:183], v179 offset:6528
	ds_read_b128 v[184:187], v179 offset:6544
	ds_read_b128 v[188:191], v179 offset:6560
	ds_read_b128 v[192:195], v179 offset:6576
	s_waitcnt vmcnt(26) lgkmcnt(4)
	v_pk_fma_f32 v[226:227], v[150:151], v[210:211], v[226:227] op_sel:[1,0,0] op_sel_hi:[1,1,1]
	v_pk_fma_f32 v[228:229], v[150:151], v[212:213], v[228:229] op_sel:[1,0,0] op_sel_hi:[1,1,1]
	v_pk_fma_f32 v[230:231], v[150:151], v[214:215], v[230:231] op_sel:[1,0,0] op_sel_hi:[1,1,1]
	v_pk_fma_f32 v[232:233], v[150:151], v[216:217], v[232:233] op_sel:[1,0,0] op_sel_hi:[1,1,1]
	v_pk_fma_f32 v[234:235], v[150:151], v[218:219], v[234:235] op_sel:[1,0,0] op_sel_hi:[1,1,1]
	v_pk_fma_f32 v[236:237], v[150:151], v[220:221], v[236:237] op_sel:[1,0,0] op_sel_hi:[1,1,1]
	v_pk_fma_f32 v[238:239], v[150:151], v[222:223], v[238:239] op_sel:[1,0,0] op_sel_hi:[1,1,1]
	v_pk_fma_f32 v[240:241], v[150:151], v[224:225], v[240:241] op_sel:[1,0,0] op_sel_hi:[1,1,1]
	ds_read_b128 v[210:213], v179 offset:6592
	ds_read_b128 v[214:217], v179 offset:6608
	ds_read_b128 v[218:221], v179 offset:6624
	ds_read_b128 v[222:225], v179 offset:6640
	s_waitcnt vmcnt(25) lgkmcnt(4)
	v_pk_fma_f32 v[226:227], v[152:153], v[180:181], v[226:227] op_sel:[0,0,0] op_sel_hi:[0,1,1]
	v_pk_fma_f32 v[228:229], v[152:153], v[182:183], v[228:229] op_sel:[0,0,0] op_sel_hi:[0,1,1]
	v_pk_fma_f32 v[230:231], v[152:153], v[184:185], v[230:231] op_sel:[0,0,0] op_sel_hi:[0,1,1]
	v_pk_fma_f32 v[232:233], v[152:153], v[186:187], v[232:233] op_sel:[0,0,0] op_sel_hi:[0,1,1]
	v_pk_fma_f32 v[234:235], v[152:153], v[188:189], v[234:235] op_sel:[0,0,0] op_sel_hi:[0,1,1]
	v_pk_fma_f32 v[236:237], v[152:153], v[190:191], v[236:237] op_sel:[0,0,0] op_sel_hi:[0,1,1]
	v_pk_fma_f32 v[238:239], v[152:153], v[192:193], v[238:239] op_sel:[0,0,0] op_sel_hi:[0,1,1]
	v_pk_fma_f32 v[240:241], v[152:153], v[194:195], v[240:241] op_sel:[0,0,0] op_sel_hi:[0,1,1]
	ds_read_b128 v[180:183], v179 offset:6656
	ds_read_b128 v[184:187], v179 offset:6672
	ds_read_b128 v[188:191], v179 offset:6688
	ds_read_b128 v[192:195], v179 offset:6704
	s_waitcnt vmcnt(24) lgkmcnt(4)
	v_pk_fma_f32 v[226:227], v[152:153], v[210:211], v[226:227] op_sel:[1,0,0] op_sel_hi:[1,1,1]
	v_pk_fma_f32 v[228:229], v[152:153], v[212:213], v[228:229] op_sel:[1,0,0] op_sel_hi:[1,1,1]
	v_pk_fma_f32 v[230:231], v[152:153], v[214:215], v[230:231] op_sel:[1,0,0] op_sel_hi:[1,1,1]
	v_pk_fma_f32 v[232:233], v[152:153], v[216:217], v[232:233] op_sel:[1,0,0] op_sel_hi:[1,1,1]
	v_pk_fma_f32 v[234:235], v[152:153], v[218:219], v[234:235] op_sel:[1,0,0] op_sel_hi:[1,1,1]
	v_pk_fma_f32 v[236:237], v[152:153], v[220:221], v[236:237] op_sel:[1,0,0] op_sel_hi:[1,1,1]
	v_pk_fma_f32 v[238:239], v[152:153], v[222:223], v[238:239] op_sel:[1,0,0] op_sel_hi:[1,1,1]
	v_pk_fma_f32 v[240:241], v[152:153], v[224:225], v[240:241] op_sel:[1,0,0] op_sel_hi:[1,1,1]
	ds_read_b128 v[210:213], v179 offset:6720
	ds_read_b128 v[214:217], v179 offset:6736
	ds_read_b128 v[218:221], v179 offset:6752
	ds_read_b128 v[222:225], v179 offset:6768
	s_waitcnt vmcnt(23) lgkmcnt(4)
	v_pk_fma_f32 v[226:227], v[154:155], v[180:181], v[226:227] op_sel:[0,0,0] op_sel_hi:[0,1,1]
	v_pk_fma_f32 v[228:229], v[154:155], v[182:183], v[228:229] op_sel:[0,0,0] op_sel_hi:[0,1,1]
	v_pk_fma_f32 v[230:231], v[154:155], v[184:185], v[230:231] op_sel:[0,0,0] op_sel_hi:[0,1,1]
	v_pk_fma_f32 v[232:233], v[154:155], v[186:187], v[232:233] op_sel:[0,0,0] op_sel_hi:[0,1,1]
	v_pk_fma_f32 v[234:235], v[154:155], v[188:189], v[234:235] op_sel:[0,0,0] op_sel_hi:[0,1,1]
	v_pk_fma_f32 v[236:237], v[154:155], v[190:191], v[236:237] op_sel:[0,0,0] op_sel_hi:[0,1,1]
	v_pk_fma_f32 v[238:239], v[154:155], v[192:193], v[238:239] op_sel:[0,0,0] op_sel_hi:[0,1,1]
	v_pk_fma_f32 v[240:241], v[154:155], v[194:195], v[240:241] op_sel:[0,0,0] op_sel_hi:[0,1,1]
	ds_read_b128 v[180:183], v179 offset:6784
	ds_read_b128 v[184:187], v179 offset:6800
	ds_read_b128 v[188:191], v179 offset:6816
	ds_read_b128 v[192:195], v179 offset:6832
	s_waitcnt vmcnt(22) lgkmcnt(4)
	v_pk_fma_f32 v[226:227], v[154:155], v[210:211], v[226:227] op_sel:[1,0,0] op_sel_hi:[1,1,1]
	v_pk_fma_f32 v[228:229], v[154:155], v[212:213], v[228:229] op_sel:[1,0,0] op_sel_hi:[1,1,1]
	v_pk_fma_f32 v[230:231], v[154:155], v[214:215], v[230:231] op_sel:[1,0,0] op_sel_hi:[1,1,1]
	v_pk_fma_f32 v[232:233], v[154:155], v[216:217], v[232:233] op_sel:[1,0,0] op_sel_hi:[1,1,1]
	v_pk_fma_f32 v[234:235], v[154:155], v[218:219], v[234:235] op_sel:[1,0,0] op_sel_hi:[1,1,1]
	v_pk_fma_f32 v[236:237], v[154:155], v[220:221], v[236:237] op_sel:[1,0,0] op_sel_hi:[1,1,1]
	v_pk_fma_f32 v[238:239], v[154:155], v[222:223], v[238:239] op_sel:[1,0,0] op_sel_hi:[1,1,1]
	v_pk_fma_f32 v[240:241], v[154:155], v[224:225], v[240:241] op_sel:[1,0,0] op_sel_hi:[1,1,1]
	ds_read_b128 v[210:213], v179 offset:6848
	ds_read_b128 v[214:217], v179 offset:6864
	ds_read_b128 v[218:221], v179 offset:6880
	ds_read_b128 v[222:225], v179 offset:6896
	s_waitcnt vmcnt(21) lgkmcnt(4)
; #define LAS __attribute__((address_space(3)))
; __global__ void __launch_bounds__(NTHR, 2) hymba_fwd(Params P) {
;     ...
;             for (int kk = 0; kk < 128; ++kk) { const float wv = P.w_ada[(size_t)(wave * 128 + kk) * 3072 + col];
; #pragma unroll
;                 for (int q = 0; q < 4; ++q) { const f32x4 s = *(const LAS f32x4*)(sil + kk * 16 + 4 * q); acc[4 * q] += s[0] * wv; acc[4 * q + 1] += s[1] * wv; acc[4 * q + 2] += s[2] * wv; acc[4 * q + 3] += s[3] * wv; } }
	v_pk_fma_f32 v[226:227], v[156:157], v[180:181], v[226:227] op_sel:[0,0,0] op_sel_hi:[0,1,1]
	v_pk_fma_f32 v[228:229], v[156:157], v[182:183], v[228:229] op_sel:[0,0,0] op_sel_hi:[0,1,1]
	v_pk_fma_f32 v[230:231], v[156:157], v[184:185], v[230:231] op_sel:[0,0,0] op_sel_hi:[0,1,1]
	v_pk_fma_f32 v[232:233], v[156:157], v[186:187], v[232:233] op_sel:[0,0,0] op_sel_hi:[0,1,1]
	v_pk_fma_f32 v[234:235], v[156:157], v[188:189], v[234:235] op_sel:[0,0,0] op_sel_hi:[0,1,1]
	v_pk_fma_f32 v[236:237], v[156:157], v[190:191], v[236:237] op_sel:[0,0,0] op_sel_hi:[0,1,1]
	v_pk_fma_f32 v[238:239], v[156:157], v[192:193], v[238:239] op_sel:[0,0,0] op_sel_hi:[0,1,1]
	v_pk_fma_f32 v[240:241], v[156:157], v[194:195], v[240:241] op_sel:[0,0,0] op_sel_hi:[0,1,1]
	ds_read_b128 v[180:183], v179 offset:6912
	ds_read_b128 v[184:187], v179 offset:6928
	ds_read_b128 v[188:191], v179 offset:6944
	ds_read_b128 v[192:195], v179 offset:6960
	s_waitcnt vmcnt(20) lgkmcnt(4)
	v_pk_fma_f32 v[226:227], v[156:157], v[210:211], v[226:227] op_sel:[1,0,0] op_sel_hi:[1,1,1]
	v_pk_fma_f32 v[228:229], v[156:157], v[212:213], v[228:229] op_sel:[1,0,0] op_sel_hi:[1,1,1]
	v_pk_fma_f32 v[230:231], v[156:157], v[214:215], v[230:231] op_sel:[1,0,0] op_sel_hi:[1,1,1]
	v_pk_fma_f32 v[232:233], v[156:157], v[216:217], v[232:233] op_sel:[1,0,0] op_sel_hi:[1,1,1]
	v_pk_fma_f32 v[234:235], v[156:157], v[218:219], v[234:235] op_sel:[1,0,0] op_sel_hi:[1,1,1]
	v_pk_fma_f32 v[236:237], v[156:157], v[220:221], v[236:237] op_sel:[1,0,0] op_sel_hi:[1,1,1]
	v_pk_fma_f32 v[238:239], v[156:157], v[222:223], v[238:239] op_sel:[1,0,0] op_sel_hi:[1,1,1]
	v_pk_fma_f32 v[240:241], v[156:157], v[224:225], v[240:241] op_sel:[1,0,0] op_sel_hi:[1,1,1]
	ds_read_b128 v[210:213], v179 offset:6976
	ds_read_b128 v[214:217], v179 offset:6992
	ds_read_b128 v[218:221], v179 offset:7008
	ds_read_b128 v[222:225], v179 offset:7024
	s_waitcnt vmcnt(19) lgkmcnt(4)
	v_pk_fma_f32 v[226:227], v[158:159], v[180:181], v[226:227] op_sel:[0,0,0] op_sel_hi:[0,1,1]
	v_pk_fma_f32 v[228:229], v[158:159], v[182:183], v[228:229] op_sel:[0,0,0] op_sel_hi:[0,1,1]
	v_pk_fma_f32 v[230:231], v[158:159], v[184:185], v[230:231] op_sel:[0,0,0] op_sel_hi:[0,1,1]
	v_pk_fma_f32 v[232:233], v[158:159], v[186:187], v[232:233] op_sel:[0,0,0] op_sel_hi:[0,1,1]
	v_pk_fma_f32 v[234:235], v[158:159], v[188:189], v[234:235] op_sel:[0,0,0] op_sel_hi:[0,1,1]
	v_pk_fma_f32 v[236:237], v[158:159], v[190:191], v[236:237] op_sel:[0,0,0] op_sel_hi:[0,1,1]
	v_pk_fma_f32 v[238:239], v[158:159], v[192:193], v[238:239] op_sel:[0,0,0] op_sel_hi:[0,1,1]
	v_pk_fma_f32 v[240:241], v[158:159], v[194:195], v[240:241] op_sel:[0,0,0] op_sel_hi:[0,1,1]
	ds_read_b128 v[180:183], v179 offset:7040
	ds_read_b128 v[184:187], v179 offset:7056
	ds_read_b128 v[188:191], v179 offset:7072
	ds_read_b128 v[192:195], v179 offset:7088
	s_waitcnt vmcnt(18) lgkmcnt(4)
	v_pk_fma_f32 v[226:227], v[158:159], v[210:211], v[226:227] op_sel:[1,0,0] op_sel_hi:[1,1,1]
	v_pk_fma_f32 v[228:229], v[158:159], v[212:213], v[228:229] op_sel:[1,0,0] op_sel_hi:[1,1,1]
	v_pk_fma_f32 v[230:231], v[158:159], v[214:215], v[230:231] op_sel:[1,0,0] op_sel_hi:[1,1,1]
	v_pk_fma_f32 v[232:233], v[158:159], v[216:217], v[232:233] op_sel:[1,0,0] op_sel_hi:[1,1,1]
	v_pk_fma_f32 v[234:235], v[158:159], v[218:219], v[234:235] op_sel:[1,0,0] op_sel_hi:[1,1,1]
	v_pk_fma_f32 v[236:237], v[158:159], v[220:221], v[236:237] op_sel:[1,0,0] op_sel_hi:[1,1,1]
	v_pk_fma_f32 v[238:239], v[158:159], v[222:223], v[238:239] op_sel:[1,0,0] op_sel_hi:[1,1,1]
	v_pk_fma_f32 v[240:241], v[158:159], v[224:225], v[240:241] op_sel:[1,0,0] op_sel_hi:[1,1,1]
	ds_read_b128 v[210:213], v179 offset:7104
	ds_read_b128 v[214:217], v179 offset:7120
	ds_read_b128 v[218:221], v179 offset:7136
	ds_read_b128 v[222:225], v179 offset:7152
	s_waitcnt vmcnt(17) lgkmcnt(4)
	v_pk_fma_f32 v[226:227], v[160:161], v[180:181], v[226:227] op_sel:[0,0,0] op_sel_hi:[0,1,1]
	v_pk_fma_f32 v[228:229], v[160:161], v[182:183], v[228:229] op_sel:[0,0,0] op_sel_hi:[0,1,1]
	v_pk_fma_f32 v[230:231], v[160:161], v[184:185], v[230:231] op_sel:[0,0,0] op_sel_hi:[0,1,1]
	v_pk_fma_f32 v[232:233], v[160:161], v[186:187], v[232:233] op_sel:[0,0,0] op_sel_hi:[0,1,1]
	v_pk_fma_f32 v[234:235], v[160:161], v[188:189], v[234:235] op_sel:[0,0,0] op_sel_hi:[0,1,1]
	v_pk_fma_f32 v[236:237], v[160:161], v[190:191], v[236:237] op_sel:[0,0,0] op_sel_hi:[0,1,1]
	v_pk_fma_f32 v[238:239], v[160:161], v[192:193], v[238:239] op_sel:[0,0,0] op_sel_hi:[0,1,1]
	v_pk_fma_f32 v[240:241], v[160:161], v[194:195], v[240:241] op_sel:[0,0,0] op_sel_hi:[0,1,1]
	ds_read_b128 v[180:183], v179 offset:7168
	ds_read_b128 v[184:187], v179 offset:7184
	ds_read_b128 v[188:191], v179 offset:7200
	ds_read_b128 v[192:195], v179 offset:7216
	s_waitcnt vmcnt(16) lgkmcnt(4)
	v_pk_fma_f32 v[226:227], v[160:161], v[210:211], v[226:227] op_sel:[1,0,0] op_sel_hi:[1,1,1]
	v_pk_fma_f32 v[228:229], v[160:161], v[212:213], v[228:229] op_sel:[1,0,0] op_sel_hi:[1,1,1]
	v_pk_fma_f32 v[230:231], v[160:161], v[214:215], v[230:231] op_sel:[1,0,0] op_sel_hi:[1,1,1]
	v_pk_fma_f32 v[232:233], v[160:161], v[216:217], v[232:233] op_sel:[1,0,0] op_sel_hi:[1,1,1]
	v_pk_fma_f32 v[234:235], v[160:161], v[218:219], v[234:235] op_sel:[1,0,0] op_sel_hi:[1,1,1]
	v_pk_fma_f32 v[236:237], v[160:161], v[220:221], v[236:237] op_sel:[1,0,0] op_sel_hi:[1,1,1]
	v_pk_fma_f32 v[238:239], v[160:161], v[222:223], v[238:239] op_sel:[1,0,0] op_sel_hi:[1,1,1]
	v_pk_fma_f32 v[240:241], v[160:161], v[224:225], v[240:241] op_sel:[1,0,0] op_sel_hi:[1,1,1]
	ds_read_b128 v[210:213], v179 offset:7232
	ds_read_b128 v[214:217], v179 offset:7248
	ds_read_b128 v[218:221], v179 offset:7264
	ds_read_b128 v[222:225], v179 offset:7280
	s_waitcnt vmcnt(15) lgkmcnt(4)
; #define LAS __attribute__((address_space(3)))
; __global__ void __launch_bounds__(NTHR, 2) hymba_fwd(Params P) {
;     ...
;             for (int kk = 0; kk < 128; ++kk) { const float wv = P.w_ada[(size_t)(wave * 128 + kk) * 3072 + col];
; #pragma unroll
;                 for (int q = 0; q < 4; ++q) { const f32x4 s = *(const LAS f32x4*)(sil + kk * 16 + 4 * q); acc[4 * q] += s[0] * wv; acc[4 * q + 1] += s[1] * wv; acc[4 * q + 2] += s[2] * wv; acc[4 * q + 3] += s[3] * wv; } }
	v_pk_fma_f32 v[226:227], v[162:163], v[180:181], v[226:227] op_sel:[0,0,0] op_sel_hi:[0,1,1]
	v_pk_fma_f32 v[228:229], v[162:163], v[182:183], v[228:229] op_sel:[0,0,0] op_sel_hi:[0,1,1]
	v_pk_fma_f32 v[230:231], v[162:163], v[184:185], v[230:231] op_sel:[0,0,0] op_sel_hi:[0,1,1]
	v_pk_fma_f32 v[232:233], v[162:163], v[186:187], v[232:233] op_sel:[0,0,0] op_sel_hi:[0,1,1]
	v_pk_fma_f32 v[234:235], v[162:163], v[188:189], v[234:235] op_sel:[0,0,0] op_sel_hi:[0,1,1]
	v_pk_fma_f32 v[236:237], v[162:163], v[190:191], v[236:237] op_sel:[0,0,0] op_sel_hi:[0,1,1]
	v_pk_fma_f32 v[238:239], v[162:163], v[192:193], v[238:239] op_sel:[0,0,0] op_sel_hi:[0,1,1]
	v_pk_fma_f32 v[240:241], v[162:163], v[194:195], v[240:241] op_sel:[0,0,0] op_sel_hi:[0,1,1]
	ds_read_b128 v[180:183], v179 offset:7296
	ds_read_b128 v[184:187], v179 offset:7312
	ds_read_b128 v[188:191], v179 offset:7328
	ds_read_b128 v[192:195], v179 offset:7344
	s_waitcnt vmcnt(14) lgkmcnt(4)
	v_pk_fma_f32 v[226:227], v[162:163], v[210:211], v[226:227] op_sel:[1,0,0] op_sel_hi:[1,1,1]
	v_pk_fma_f32 v[228:229], v[162:163], v[212:213], v[228:229] op_sel:[1,0,0] op_sel_hi:[1,1,1]
	v_pk_fma_f32 v[230:231], v[162:163], v[214:215], v[230:231] op_sel:[1,0,0] op_sel_hi:[1,1,1]
	v_pk_fma_f32 v[232:233], v[162:163], v[216:217], v[232:233] op_sel:[1,0,0] op_sel_hi:[1,1,1]
	v_pk_fma_f32 v[234:235], v[162:163], v[218:219], v[234:235] op_sel:[1,0,0] op_sel_hi:[1,1,1]
	v_pk_fma_f32 v[236:237], v[162:163], v[220:221], v[236:237] op_sel:[1,0,0] op_sel_hi:[1,1,1]
	v_pk_fma_f32 v[238:239], v[162:163], v[222:223], v[238:239] op_sel:[1,0,0] op_sel_hi:[1,1,1]
	v_pk_fma_f32 v[240:241], v[162:163], v[224:225], v[240:241] op_sel:[1,0,0] op_sel_hi:[1,1,1]
	ds_read_b128 v[210:213], v179 offset:7360
	ds_read_b128 v[214:217], v179 offset:7376
	ds_read_b128 v[218:221], v179 offset:7392
	ds_read_b128 v[222:225], v179 offset:7408
	s_waitcnt vmcnt(13) lgkmcnt(4)
	v_pk_fma_f32 v[226:227], v[164:165], v[180:181], v[226:227] op_sel:[0,0,0] op_sel_hi:[0,1,1]
	v_pk_fma_f32 v[228:229], v[164:165], v[182:183], v[228:229] op_sel:[0,0,0] op_sel_hi:[0,1,1]
	v_pk_fma_f32 v[230:231], v[164:165], v[184:185], v[230:231] op_sel:[0,0,0] op_sel_hi:[0,1,1]
	v_pk_fma_f32 v[232:233], v[164:165], v[186:187], v[232:233] op_sel:[0,0,0] op_sel_hi:[0,1,1]
	v_pk_fma_f32 v[234:235], v[164:165], v[188:189], v[234:235] op_sel:[0,0,0] op_sel_hi:[0,1,1]
	v_pk_fma_f32 v[236:237], v[164:165], v[190:191], v[236:237] op_sel:[0,0,0] op_sel_hi:[0,1,1]
	v_pk_fma_f32 v[238:239], v[164:165], v[192:193], v[238:239] op_sel:[0,0,0] op_sel_hi:[0,1,1]
	v_pk_fma_f32 v[240:241], v[164:165], v[194:195], v[240:241] op_sel:[0,0,0] op_sel_hi:[0,1,1]
	ds_read_b128 v[180:183], v179 offset:7424
	ds_read_b128 v[184:187], v179 offset:7440
	ds_read_b128 v[188:191], v179 offset:7456
	ds_read_b128 v[192:195], v179 offset:7472
	s_waitcnt vmcnt(12) lgkmcnt(4)
	v_pk_fma_f32 v[226:227], v[164:165], v[210:211], v[226:227] op_sel:[1,0,0] op_sel_hi:[1,1,1]
	v_pk_fma_f32 v[228:229], v[164:165], v[212:213], v[228:229] op_sel:[1,0,0] op_sel_hi:[1,1,1]
	v_pk_fma_f32 v[230:231], v[164:165], v[214:215], v[230:231] op_sel:[1,0,0] op_sel_hi:[1,1,1]
	v_pk_fma_f32 v[232:233], v[164:165], v[216:217], v[232:233] op_sel:[1,0,0] op_sel_hi:[1,1,1]
	v_pk_fma_f32 v[234:235], v[164:165], v[218:219], v[234:235] op_sel:[1,0,0] op_sel_hi:[1,1,1]
	v_pk_fma_f32 v[236:237], v[164:165], v[220:221], v[236:237] op_sel:[1,0,0] op_sel_hi:[1,1,1]
	v_pk_fma_f32 v[238:239], v[164:165], v[222:223], v[238:239] op_sel:[1,0,0] op_sel_hi:[1,1,1]
	v_pk_fma_f32 v[240:241], v[164:165], v[224:225], v[240:241] op_sel:[1,0,0] op_sel_hi:[1,1,1]
	ds_read_b128 v[210:213], v179 offset:7488
	ds_read_b128 v[214:217], v179 offset:7504
	ds_read_b128 v[218:221], v179 offset:7520
	ds_read_b128 v[222:225], v179 offset:7536
	s_waitcnt vmcnt(11) lgkmcnt(4)
	v_pk_fma_f32 v[226:227], v[166:167], v[180:181], v[226:227] op_sel:[0,0,0] op_sel_hi:[0,1,1]
	v_pk_fma_f32 v[228:229], v[166:167], v[182:183], v[228:229] op_sel:[0,0,0] op_sel_hi:[0,1,1]
	v_pk_fma_f32 v[230:231], v[166:167], v[184:185], v[230:231] op_sel:[0,0,0] op_sel_hi:[0,1,1]
	v_pk_fma_f32 v[232:233], v[166:167], v[186:187], v[232:233] op_sel:[0,0,0] op_sel_hi:[0,1,1]
	v_pk_fma_f32 v[234:235], v[166:167], v[188:189], v[234:235] op_sel:[0,0,0] op_sel_hi:[0,1,1]
	v_pk_fma_f32 v[236:237], v[166:167], v[190:191], v[236:237] op_sel:[0,0,0] op_sel_hi:[0,1,1]
	v_pk_fma_f32 v[238:239], v[166:167], v[192:193], v[238:239] op_sel:[0,0,0] op_sel_hi:[0,1,1]
	v_pk_fma_f32 v[240:241], v[166:167], v[194:195], v[240:241] op_sel:[0,0,0] op_sel_hi:[0,1,1]
	ds_read_b128 v[180:183], v179 offset:7552
	ds_read_b128 v[184:187], v179 offset:7568
	ds_read_b128 v[188:191], v179 offset:7584
	ds_read_b128 v[192:195], v179 offset:7600
	s_waitcnt vmcnt(10) lgkmcnt(4)
	v_pk_fma_f32 v[226:227], v[166:167], v[210:211], v[226:227] op_sel:[1,0,0] op_sel_hi:[1,1,1]
	v_pk_fma_f32 v[228:229], v[166:167], v[212:213], v[228:229] op_sel:[1,0,0] op_sel_hi:[1,1,1]
	v_pk_fma_f32 v[230:231], v[166:167], v[214:215], v[230:231] op_sel:[1,0,0] op_sel_hi:[1,1,1]
	v_pk_fma_f32 v[232:233], v[166:167], v[216:217], v[232:233] op_sel:[1,0,0] op_sel_hi:[1,1,1]
	v_pk_fma_f32 v[234:235], v[166:167], v[218:219], v[234:235] op_sel:[1,0,0] op_sel_hi:[1,1,1]
	v_pk_fma_f32 v[236:237], v[166:167], v[220:221], v[236:237] op_sel:[1,0,0] op_sel_hi:[1,1,1]
	v_pk_fma_f32 v[238:239], v[166:167], v[222:223], v[238:239] op_sel:[1,0,0] op_sel_hi:[1,1,1]
	v_pk_fma_f32 v[240:241], v[166:167], v[224:225], v[240:241] op_sel:[1,0,0] op_sel_hi:[1,1,1]
	ds_read_b128 v[210:213], v179 offset:7616
	ds_read_b128 v[214:217], v179 offset:7632
	ds_read_b128 v[218:221], v179 offset:7648
	ds_read_b128 v[222:225], v179 offset:7664
	s_waitcnt vmcnt(9) lgkmcnt(4)
; #define LAS __attribute__((address_space(3)))
; __global__ void __launch_bounds__(NTHR, 2) hymba_fwd(Params P) {
;     ...
;             for (int kk = 0; kk < 128; ++kk) { const float wv = P.w_ada[(size_t)(wave * 128 + kk) * 3072 + col];
; #pragma unroll
;                 for (int q = 0; q < 4; ++q) { const f32x4 s = *(const LAS f32x4*)(sil + kk * 16 + 4 * q); acc[4 * q] += s[0] * wv; acc[4 * q + 1] += s[1] * wv; acc[4 * q + 2] += s[2] * wv; acc[4 * q + 3] += s[3] * wv; } }
	v_pk_fma_f32 v[226:227], v[168:169], v[180:181], v[226:227] op_sel:[0,0,0] op_sel_hi:[0,1,1]
	v_pk_fma_f32 v[228:229], v[168:169], v[182:183], v[228:229] op_sel:[0,0,0] op_sel_hi:[0,1,1]
	v_pk_fma_f32 v[230:231], v[168:169], v[184:185], v[230:231] op_sel:[0,0,0] op_sel_hi:[0,1,1]
	v_pk_fma_f32 v[232:233], v[168:169], v[186:187], v[232:233] op_sel:[0,0,0] op_sel_hi:[0,1,1]
	v_pk_fma_f32 v[234:235], v[168:169], v[188:189], v[234:235] op_sel:[0,0,0] op_sel_hi:[0,1,1]
	v_pk_fma_f32 v[236:237], v[168:169], v[190:191], v[236:237] op_sel:[0,0,0] op_sel_hi:[0,1,1]
	v_pk_fma_f32 v[238:239], v[168:169], v[192:193], v[238:239] op_sel:[0,0,0] op_sel_hi:[0,1,1]
	v_pk_fma_f32 v[240:241], v[168:169], v[194:195], v[240:241] op_sel:[0,0,0] op_sel_hi:[0,1,1]
	ds_read_b128 v[180:183], v179 offset:7680
	ds_read_b128 v[184:187], v179 offset:7696
	ds_read_b128 v[188:191], v179 offset:7712
	ds_read_b128 v[192:195], v179 offset:7728
	s_waitcnt vmcnt(8) lgkmcnt(4)
	v_pk_fma_f32 v[226:227], v[168:169], v[210:211], v[226:227] op_sel:[1,0,0] op_sel_hi:[1,1,1]
	v_pk_fma_f32 v[228:229], v[168:169], v[212:213], v[228:229] op_sel:[1,0,0] op_sel_hi:[1,1,1]
	v_pk_fma_f32 v[230:231], v[168:169], v[214:215], v[230:231] op_sel:[1,0,0] op_sel_hi:[1,1,1]
	v_pk_fma_f32 v[232:233], v[168:169], v[216:217], v[232:233] op_sel:[1,0,0] op_sel_hi:[1,1,1]
	v_pk_fma_f32 v[234:235], v[168:169], v[218:219], v[234:235] op_sel:[1,0,0] op_sel_hi:[1,1,1]
	v_pk_fma_f32 v[236:237], v[168:169], v[220:221], v[236:237] op_sel:[1,0,0] op_sel_hi:[1,1,1]
	v_pk_fma_f32 v[238:239], v[168:169], v[222:223], v[238:239] op_sel:[1,0,0] op_sel_hi:[1,1,1]
	v_pk_fma_f32 v[240:241], v[168:169], v[224:225], v[240:241] op_sel:[1,0,0] op_sel_hi:[1,1,1]
	ds_read_b128 v[210:213], v179 offset:7744
	ds_read_b128 v[214:217], v179 offset:7760
	ds_read_b128 v[218:221], v179 offset:7776
	ds_read_b128 v[222:225], v179 offset:7792
	s_waitcnt vmcnt(7) lgkmcnt(4)
	v_pk_fma_f32 v[226:227], v[170:171], v[180:181], v[226:227] op_sel:[0,0,0] op_sel_hi:[0,1,1]
	v_pk_fma_f32 v[228:229], v[170:171], v[182:183], v[228:229] op_sel:[0,0,0] op_sel_hi:[0,1,1]
	v_pk_fma_f32 v[230:231], v[170:171], v[184:185], v[230:231] op_sel:[0,0,0] op_sel_hi:[0,1,1]
	v_pk_fma_f32 v[232:233], v[170:171], v[186:187], v[232:233] op_sel:[0,0,0] op_sel_hi:[0,1,1]
	v_pk_fma_f32 v[234:235], v[170:171], v[188:189], v[234:235] op_sel:[0,0,0] op_sel_hi:[0,1,1]
	v_pk_fma_f32 v[236:237], v[170:171], v[190:191], v[236:237] op_sel:[0,0,0] op_sel_hi:[0,1,1]
	v_pk_fma_f32 v[238:239], v[170:171], v[192:193], v[238:239] op_sel:[0,0,0] op_sel_hi:[0,1,1]
	v_pk_fma_f32 v[240:241], v[170:171], v[194:195], v[240:241] op_sel:[0,0,0] op_sel_hi:[0,1,1]
	ds_read_b128 v[180:183], v179 offset:7808
	ds_read_b128 v[184:187], v179 offset:7824
	ds_read_b128 v[188:191], v179 offset:7840
	ds_read_b128 v[192:195], v179 offset:7856
	s_waitcnt vmcnt(6) lgkmcnt(4)
	v_pk_fma_f32 v[226:227], v[170:171], v[210:211], v[226:227] op_sel:[1,0,0] op_sel_hi:[1,1,1]
	v_pk_fma_f32 v[228:229], v[170:171], v[212:213], v[228:229] op_sel:[1,0,0] op_sel_hi:[1,1,1]
	v_pk_fma_f32 v[230:231], v[170:171], v[214:215], v[230:231] op_sel:[1,0,0] op_sel_hi:[1,1,1]
	v_pk_fma_f32 v[232:233], v[170:171], v[216:217], v[232:233] op_sel:[1,0,0] op_sel_hi:[1,1,1]
	v_pk_fma_f32 v[234:235], v[170:171], v[218:219], v[234:235] op_sel:[1,0,0] op_sel_hi:[1,1,1]
	v_pk_fma_f32 v[236:237], v[170:171], v[220:221], v[236:237] op_sel:[1,0,0] op_sel_hi:[1,1,1]
	v_pk_fma_f32 v[238:239], v[170:171], v[222:223], v[238:239] op_sel:[1,0,0] op_sel_hi:[1,1,1]
	v_pk_fma_f32 v[240:241], v[170:171], v[224:225], v[240:241] op_sel:[1,0,0] op_sel_hi:[1,1,1]
	ds_read_b128 v[210:213], v179 offset:7872
	ds_read_b128 v[214:217], v179 offset:7888
	ds_read_b128 v[218:221], v179 offset:7904
	ds_read_b128 v[222:225], v179 offset:7920
	s_waitcnt vmcnt(5) lgkmcnt(4)
	v_pk_fma_f32 v[226:227], v[172:173], v[180:181], v[226:227] op_sel:[0,0,0] op_sel_hi:[0,1,1]
	v_pk_fma_f32 v[228:229], v[172:173], v[182:183], v[228:229] op_sel:[0,0,0] op_sel_hi:[0,1,1]
	v_pk_fma_f32 v[230:231], v[172:173], v[184:185], v[230:231] op_sel:[0,0,0] op_sel_hi:[0,1,1]
	v_pk_fma_f32 v[232:233], v[172:173], v[186:187], v[232:233] op_sel:[0,0,0] op_sel_hi:[0,1,1]
	v_pk_fma_f32 v[234:235], v[172:173], v[188:189], v[234:235] op_sel:[0,0,0] op_sel_hi:[0,1,1]
	v_pk_fma_f32 v[236:237], v[172:173], v[190:191], v[236:237] op_sel:[0,0,0] op_sel_hi:[0,1,1]
	v_pk_fma_f32 v[238:239], v[172:173], v[192:193], v[238:239] op_sel:[0,0,0] op_sel_hi:[0,1,1]
	v_pk_fma_f32 v[240:241], v[172:173], v[194:195], v[240:241] op_sel:[0,0,0] op_sel_hi:[0,1,1]
	ds_read_b128 v[180:183], v179 offset:7936
	ds_read_b128 v[184:187], v179 offset:7952
	ds_read_b128 v[188:191], v179 offset:7968
	ds_read_b128 v[192:195], v179 offset:7984
	s_waitcnt vmcnt(4) lgkmcnt(4)
	v_pk_fma_f32 v[226:227], v[172:173], v[210:211], v[226:227] op_sel:[1,0,0] op_sel_hi:[1,1,1]
	v_pk_fma_f32 v[228:229], v[172:173], v[212:213], v[228:229] op_sel:[1,0,0] op_sel_hi:[1,1,1]
	v_pk_fma_f32 v[230:231], v[172:173], v[214:215], v[230:231] op_sel:[1,0,0] op_sel_hi:[1,1,1]
	v_pk_fma_f32 v[232:233], v[172:173], v[216:217], v[232:233] op_sel:[1,0,0] op_sel_hi:[1,1,1]
	v_pk_fma_f32 v[234:235], v[172:173], v[218:219], v[234:235] op_sel:[1,0,0] op_sel_hi:[1,1,1]
	v_pk_fma_f32 v[236:237], v[172:173], v[220:221], v[236:237] op_sel:[1,0,0] op_sel_hi:[1,1,1]
	v_pk_fma_f32 v[238:239], v[172:173], v[222:223], v[238:239] op_sel:[1,0,0] op_sel_hi:[1,1,1]
	v_pk_fma_f32 v[240:241], v[172:173], v[224:225], v[240:241] op_sel:[1,0,0] op_sel_hi:[1,1,1]
	ds_read_b128 v[210:213], v179 offset:8000
	ds_read_b128 v[214:217], v179 offset:8016
	ds_read_b128 v[218:221], v179 offset:8032
	ds_read_b128 v[222:225], v179 offset:8048
	s_waitcnt vmcnt(3) lgkmcnt(4)
; #define LAS __attribute__((address_space(3)))
; #define MOD WSP(float, WS_MOD)
; __global__ void __launch_bounds__(NTHR, 2) hymba_fwd(Params P) {
;     ...
;             for (int kk = 0; kk < 128; ++kk) { const float wv = P.w_ada[(size_t)(wave * 128 + kk) * 3072 + col];
; #pragma unroll
;                 for (int q = 0; q < 4; ++q) { const f32x4 s = *(const LAS f32x4*)(sil + kk * 16 + 4 * q); acc[4 * q] += s[0] * wv; acc[4 * q + 1] += s[1] * wv; acc[4 * q + 2] += s[2] * wv; acc[4 * q + 3] += s[3] * wv; } }
; #pragma unroll
;             for (int b = 0; b < 16; ++b) red[b * 64 + lane] = acc[b];
;             __syncthreads();
; #pragma unroll
;             for (int bb = 0; bb < 2; ++bb) { const int b = wave * 2 + bb; float s = P.b_ada[col];
; #pragma unroll
;                 for (int w = 0; w < 8; ++w) s += *((LAS float*)(lds + w * 16384 + 8192) + b * 64 + lane);
;                 MOD[b * 3072 + col] = s; }
	v_pk_fma_f32 v[226:227], v[174:175], v[180:181], v[226:227] op_sel:[0,0,0] op_sel_hi:[0,1,1]
	v_pk_fma_f32 v[228:229], v[174:175], v[182:183], v[228:229] op_sel:[0,0,0] op_sel_hi:[0,1,1]
	v_pk_fma_f32 v[230:231], v[174:175], v[184:185], v[230:231] op_sel:[0,0,0] op_sel_hi:[0,1,1]
	v_pk_fma_f32 v[232:233], v[174:175], v[186:187], v[232:233] op_sel:[0,0,0] op_sel_hi:[0,1,1]
	v_pk_fma_f32 v[234:235], v[174:175], v[188:189], v[234:235] op_sel:[0,0,0] op_sel_hi:[0,1,1]
	v_pk_fma_f32 v[236:237], v[174:175], v[190:191], v[236:237] op_sel:[0,0,0] op_sel_hi:[0,1,1]
	v_pk_fma_f32 v[238:239], v[174:175], v[192:193], v[238:239] op_sel:[0,0,0] op_sel_hi:[0,1,1]
	v_pk_fma_f32 v[240:241], v[174:175], v[194:195], v[240:241] op_sel:[0,0,0] op_sel_hi:[0,1,1]
	ds_read_b128 v[180:183], v179 offset:8064
	ds_read_b128 v[184:187], v179 offset:8080
	ds_read_b128 v[188:191], v179 offset:8096
	ds_read_b128 v[192:195], v179 offset:8112
	s_waitcnt vmcnt(2) lgkmcnt(4)
	v_pk_fma_f32 v[226:227], v[174:175], v[210:211], v[226:227] op_sel:[1,0,0] op_sel_hi:[1,1,1]
	v_pk_fma_f32 v[228:229], v[174:175], v[212:213], v[228:229] op_sel:[1,0,0] op_sel_hi:[1,1,1]
	v_pk_fma_f32 v[230:231], v[174:175], v[214:215], v[230:231] op_sel:[1,0,0] op_sel_hi:[1,1,1]
	v_pk_fma_f32 v[232:233], v[174:175], v[216:217], v[232:233] op_sel:[1,0,0] op_sel_hi:[1,1,1]
	v_pk_fma_f32 v[234:235], v[174:175], v[218:219], v[234:235] op_sel:[1,0,0] op_sel_hi:[1,1,1]
	v_pk_fma_f32 v[236:237], v[174:175], v[220:221], v[236:237] op_sel:[1,0,0] op_sel_hi:[1,1,1]
	v_pk_fma_f32 v[238:239], v[174:175], v[222:223], v[238:239] op_sel:[1,0,0] op_sel_hi:[1,1,1]
	v_pk_fma_f32 v[240:241], v[174:175], v[224:225], v[240:241] op_sel:[1,0,0] op_sel_hi:[1,1,1]
	ds_read_b128 v[210:213], v179 offset:8128
	ds_read_b128 v[214:217], v179 offset:8144
	ds_read_b128 v[218:221], v179 offset:8160
	ds_read_b128 v[222:225], v179 offset:8176
	s_waitcnt vmcnt(1) lgkmcnt(4)
	v_pk_fma_f32 v[226:227], v[176:177], v[180:181], v[226:227] op_sel:[0,0,0] op_sel_hi:[0,1,1]
	v_pk_fma_f32 v[228:229], v[176:177], v[182:183], v[228:229] op_sel:[0,0,0] op_sel_hi:[0,1,1]
	v_pk_fma_f32 v[230:231], v[176:177], v[184:185], v[230:231] op_sel:[0,0,0] op_sel_hi:[0,1,1]
	v_pk_fma_f32 v[232:233], v[176:177], v[186:187], v[232:233] op_sel:[0,0,0] op_sel_hi:[0,1,1]
	v_pk_fma_f32 v[234:235], v[176:177], v[188:189], v[234:235] op_sel:[0,0,0] op_sel_hi:[0,1,1]
	v_pk_fma_f32 v[236:237], v[176:177], v[190:191], v[236:237] op_sel:[0,0,0] op_sel_hi:[0,1,1]
	v_pk_fma_f32 v[238:239], v[176:177], v[192:193], v[238:239] op_sel:[0,0,0] op_sel_hi:[0,1,1]
	v_pk_fma_f32 v[240:241], v[176:177], v[194:195], v[240:241] op_sel:[0,0,0] op_sel_hi:[0,1,1]
	s_waitcnt vmcnt(0) lgkmcnt(0)
	v_pk_fma_f32 v[226:227], v[176:177], v[210:211], v[226:227] op_sel:[1,0,0] op_sel_hi:[1,1,1]
	v_pk_fma_f32 v[228:229], v[176:177], v[212:213], v[228:229] op_sel:[1,0,0] op_sel_hi:[1,1,1]
	v_pk_fma_f32 v[230:231], v[176:177], v[214:215], v[230:231] op_sel:[1,0,0] op_sel_hi:[1,1,1]
	v_pk_fma_f32 v[232:233], v[176:177], v[216:217], v[232:233] op_sel:[1,0,0] op_sel_hi:[1,1,1]
	v_pk_fma_f32 v[234:235], v[176:177], v[218:219], v[234:235] op_sel:[1,0,0] op_sel_hi:[1,1,1]
	v_pk_fma_f32 v[236:237], v[176:177], v[220:221], v[236:237] op_sel:[1,0,0] op_sel_hi:[1,1,1]
	v_pk_fma_f32 v[238:239], v[176:177], v[222:223], v[238:239] op_sel:[1,0,0] op_sel_hi:[1,1,1]
	v_pk_fma_f32 v[240:241], v[176:177], v[224:225], v[240:241] op_sel:[1,0,0] op_sel_hi:[1,1,1]
	v_mov_b32_e32 v10, v226
	v_mov_b32_e32 v11, v227
	v_mov_b32_e32 v14, v228
	v_mov_b32_e32 v15, v229
	v_mov_b32_e32 v12, v230
	v_mov_b32_e32 v13, v231
	v_mov_b32_e32 v16, v232
	v_mov_b32_e32 v17, v233
	v_mov_b32_e32 v6, v234
	v_mov_b32_e32 v7, v235
	v_mov_b32_e32 v8, v236
	v_mov_b32_e32 v9, v237
	v_mov_b32_e32 v4, v238
	v_mov_b32_e32 v5, v239
	v_mov_b32_e32 v2, v240
	v_mov_b32_e32 v3, v241
	v_lshl_or_b32 v18, s33, 6, v45
	v_lshlrev_b32_e32 v20, 2, v45
	v_ashrrev_i32_e32 v19, 31, v18
	v_add_u32_e32 v21, s5, v20
	ds_write2st64_b32 v21, v10, v11 offset0:32 offset1:33
	ds_write2st64_b32 v21, v14, v15 offset0:34 offset1:35
	ds_write2st64_b32 v21, v12, v13 offset0:36 offset1:37
	ds_write2st64_b32 v21, v16, v17 offset0:38 offset1:39
	ds_write2st64_b32 v21, v6, v7 offset0:40 offset1:41
	ds_write2st64_b32 v21, v8, v9 offset0:42 offset1:43
	ds_write2st64_b32 v21, v4, v5 offset0:44 offset1:45
	ds_write2st64_b32 v21, v2, v3 offset0:46 offset1:47
	v_lshl_add_u64 v[2:3], v[18:19], 2, s[56:57]
	s_waitcnt lgkmcnt(0)
	s_barrier
	global_load_dword v10, v[2:3], off
	s_lshl_b32 s0, s4, 9
	s_add_i32 s7, s0, 0
	v_add_u32_e32 v8, s7, v20
	ds_read2st64_b32 v[6:7], v8 offset0:32 offset1:96
	ds_read2st64_b32 v[8:9], v8 offset0:160 offset1:224
	s_add_i32 s1, 0, 0x12000
	s_add_i32 s5, 0, 0x1e000
	s_mul_i32 s6, s4, 0x1800
	s_lshl_b32 s4, s4, 1
	s_add_i32 s10, s1, s0
	s_add_i32 s14, s30, s0
	s_add_i32 s15, s31, s0
	s_add_i32 s0, s5, s0
	s_or_b32 s4, s4, 1
	v_add_u32_e32 v14, s0, v20
	s_lshl_b32 s0, s4, 8
	v_add_u32_e32 v4, s6, v18
	s_add_i32 s1, s1, s0
	s_add_i32 s6, s30, s0
	s_add_i32 s7, s31, s0
	s_add_i32 s5, s5, s0
	v_add_u32_e32 v11, s10, v20
	v_add_u32_e32 v12, s14, v20
	v_add_u32_e32 v13, s15, v20
	v_add_u32_e32 v15, s1, v20
	v_add_u32_e32 v16, s6, v20
	v_add_u32_e32 v17, s7, v20
	v_add_u32_e32 v19, s5, v20
	ds_read_b32 v11, v11
	ds_read_b32 v12, v12
	ds_read_b32 v13, v13
	ds_read_b32 v14, v14
	ds_read_b32 v15, v15
	ds_read_b32 v16, v16
	ds_read_b32 v17, v17
	ds_read_b32 v19, v19
	v_ashrrev_i32_e32 v5, 31, v4
	v_lshl_add_u64 v[4:5], v[4:5], 2, s[28:29]
	s_add_i32 s0, s0, 0
	s_mulk_i32 s4, 0xc00
	s_waitcnt vmcnt(0) lgkmcnt(9)
	v_add_f32_e32 v6, v10, v6
	v_add_f32_e32 v6, v6, v7
	s_waitcnt lgkmcnt(8)
	v_add_f32_e32 v6, v6, v8
	v_add_f32_e32 v6, v6, v9
	s_waitcnt lgkmcnt(7)
	v_add_f32_e32 v6, v6, v11
	s_waitcnt lgkmcnt(6)
	v_add_f32_e32 v6, v6, v12
	s_waitcnt lgkmcnt(5)
	v_add_f32_e32 v6, v6, v13
	s_waitcnt lgkmcnt(4)
	v_add_f32_e32 v6, v6, v14
	global_store_dword v[4:5], v6, off
	global_load_dword v8, v[2:3], off
	v_add_u32_e32 v5, s0, v20
	ds_read2st64_b32 v[2:3], v5 offset0:32 offset1:96
	ds_read2st64_b32 v[6:7], v5 offset0:160 offset1:224
	v_add_u32_e32 v4, s4, v18
	v_ashrrev_i32_e32 v5, 31, v4
	v_lshl_add_u64 v[4:5], v[4:5], 2, s[28:29]
	s_waitcnt vmcnt(0) lgkmcnt(1)
	v_add_f32_e32 v2, v8, v2
	v_add_f32_e32 v2, v2, v3
	s_waitcnt lgkmcnt(0)
	v_add_f32_e32 v2, v2, v6
	v_add_f32_e32 v2, v2, v7
	v_add_f32_e32 v2, v2, v15
	v_add_f32_e32 v2, v2, v16
	v_add_f32_e32 v2, v2, v17
	v_add_f32_e32 v2, v2, v19
	global_store_dword v[4:5], v2, off
	s_barrier
	s_branch .LBB0_7
